# peeled first K-iteration per unit with srcC=0 MFMAs; accumulator zero-fill (128 v_mov per unit) removed; on top of merged phases + critical-path trim
# speedup vs baseline: 1.0202x; 1.0046x over previous
; #define PG8_STAGE(bufoff, gbase, voff) do { _Pragma("unroll") for (int _i = 0; _i < 2; ++_i) \
;         __builtin_amdgcn_global_load_lds((const unsigned*)((const char*)(gbase) + (voff)[_i]), (LAS unsigned*)(lds + (bufoff) + ldsw + _i * 8192), 16, 0, 0); } while (0)
; #define PG8_LDA(dst, b, h) do { _Pragma("unroll") for (int m = 0; m < 4; ++m) _Pragma("unroll") for (int k = 0; k < 2; ++k) dst[m][k] = *(const LAS bf16x8*)(lds + PG8_SA(b, h) + aoff + m * 2048 + k * 1024); } while (0)
; #define PG8_LDB(dst, b, h) do { _Pragma("unroll") for (int n = 0; n < 2; ++n) _Pragma("unroll") for (int k = 0; k < 2; ++k) dst[n][k] = *(const LAS bf16x8*)(lds + PG8_SB(b, h) + boff + n * 2048 + k * 1024); } while (0)
; #define PG8_WAIT_V(n) asm volatile("s_waitcnt vmcnt(" #n ")" ::: "memory")
; #define PG8_WAIT_L(n) asm volatile("s_waitcnt lgkmcnt(" #n ")" ::: "memory")
; #define PG8_BAR __builtin_amdgcn_s_barrier()
; #define PG8_SCHED __builtin_amdgcn_sched_barrier(0)
; template <class Epi, class Sched>
; __device__ __forceinline__ void gemm_phase(LAS unsigned char* lds, const Gemm g, const Sched& S, const Epi& E) {
;     ...
;         const bool has_next = S.next(ui + 1, nxt);
;         const char* nA = has_next ? (const char*)g.A + (size_t)nxt.pm * tstepA : cA; const char* nB = has_next ? (const char*)g.Bt + (size_t)nxt.pn * tstepB : cB;
;         for (int t = 0; t < nt; t += 2) {
;             const bool last = (t == nt - 2);
;             const char* a1 = cA + (size_t)(t + 1) * kstep;
;             const char* a2 = last ? nA : cA + (size_t)(t + 2) * kstep; const char* b2 = last ? nB : cB + (size_t)(t + 2) * kstep;
;             const char* a3 = a2 + kstep; const char* b3 = b2 + kstep;
;             if (last && has_next) S.a_ready(nxt);
;             PG8_LDB(B0, 0, 0); PG8_SCHED; PG8_LDA(At, 0, 0); PG8_STAGE(PG8_SA(1, 1), a1 + hstepA, voffA);
;             PG8_WAIT_L(8); PG8_BAR; PG8_WAIT_L(0); PG8_MMA(0, 0, At, B0); PG8_BAR; PG8_SCHED;
;             PG8_LDB(B1, 0, 1); PG8_STAGE(PG8_SB(0, 0), b2, voffB);
;             PG8_BAR; PG8_WAIT_L(0); PG8_MMA(0, 1, At, B1); PG8_BAR;
;             PG8_LDA(At, 0, 1); PG8_STAGE(PG8_SA(0, 0), a2, voffA);
;             PG8_BAR; PG8_WAIT_L(0); PG8_MMA(1, 0, At, B0); PG8_BAR; PG8_SCHED;
;             PG8_STAGE(PG8_SB(0, 1), b2 + hstepB, voffB);
;             PG8_WAIT_V(6); PG8_BAR; PG8_MMA(1, 1, At, B1); PG8_BAR;
.LBB0_351:
	v_mov_b64_e32 v[4:5], 0xd80
	s_ashr_i32 s15, s14, 31
	v_cmp_lt_i64_e32 vcc, s[4:5], v[4:5]
	s_lshl_b64 s[4:5], s[14:15], 20
	s_add_u32 s18, s88, s4
	s_addc_u32 s19, s89, s5
	s_and_b64 s[4:5], vcc, exec
	s_cselect_b32 s15, s19, s7
	s_cselect_b32 s51, s18, s6
	s_ashr_i32 s1, s0, 31
	s_lshl_b64 s[4:5], s[0:1], 20
	s_add_u32 s4, s28, s4
	s_addc_u32 s5, s29, s5
	s_and_b64 s[24:25], vcc, exec
	s_cselect_b32 s1, s5, s21
	s_cselect_b32 s52, s4, s20
	s_add_u32 s6, s6, 0x80080
	s_addc_u32 s7, s7, 0
	s_add_u32 s53, s20, 0x100
	s_addc_u32 s54, s21, 0
	s_mov_b32 s55, -2
	s_waitcnt vmcnt(0)
	s_waitcnt lgkmcnt(0)
	s_setprio 0
	s_add_u32 s20, s6, 0xfff80080
	s_addc_u32 s21, s7, -1
	s_add_i32 s56, 0, 0x10000
	v_add_u32_e32 v2, s56, v1
	ds_read_b128 v[144:147], v2
	ds_read_b128 v[150:153], v2 offset:1024
	ds_read_b128 v[154:157], v2 offset:2048
	ds_read_b128 v[158:161], v2 offset:3072
	s_cmp_eq_u32 s55, 28
	s_cselect_b32 s25, s15, s21
	s_cselect_b32 s24, s51, s20
	s_cselect_b32 s21, s1, s54
	s_cselect_b32 s20, s52, s53
	ds_read_b128 v[162:165], v149
	ds_read_b128 v[166:169], v149 offset:1024
	ds_read_b128 v[170:173], v149 offset:2048
	ds_read_b128 v[174:177], v149 offset:3072
	ds_read_b128 v[178:181], v149 offset:4096
	ds_read_b128 v[182:185], v149 offset:5120
	ds_read_b128 v[186:189], v149 offset:6144
	ds_read_b128 v[190:193], v149 offset:7168
	s_add_i32 s58, 0, 0x14000
	v_add_u32_e32 v2, s58, v1
	ds_read_b128 v[194:197], v2
	ds_read_b128 v[198:201], v2 offset:1024
	ds_read_b128 v[202:205], v2 offset:2048
	ds_read_b128 v[206:209], v2 offset:3072
	s_add_i32 m0, s31, 0xc000
	s_nop 0
	global_load_lds_dwordx4 v140, s[6:7]
	s_add_i32 m0, s31, 0xe000
	s_nop 0
	global_load_lds_dwordx4 v142, s[6:7]
	s_waitcnt lgkmcnt(0)
	s_setprio 1
	s_barrier
	v_mfma_f32_16x16x32_bf16 v[128:131], v[144:147], v[162:165], 0
	v_mfma_f32_16x16x32_bf16 v[124:127], v[154:157], v[162:165], 0
	v_mfma_f32_16x16x32_bf16 v[112:115], v[144:147], v[170:173], 0
	v_mfma_f32_16x16x32_bf16 v[108:111], v[154:157], v[170:173], 0
	v_mfma_f32_16x16x32_bf16 v[96:99], v[144:147], v[178:181], 0
	v_mfma_f32_16x16x32_bf16 v[92:95], v[154:157], v[178:181], 0
	v_mfma_f32_16x16x32_bf16 v[80:83], v[144:147], v[186:189], 0
	v_mfma_f32_16x16x32_bf16 v[76:79], v[154:157], v[186:189], 0
	v_mfma_f32_16x16x32_bf16 v[128:131], v[150:153], v[166:169], v[128:131]
	v_mfma_f32_16x16x32_bf16 v[124:127], v[158:161], v[166:169], v[124:127]
	v_mfma_f32_16x16x32_bf16 v[112:115], v[150:153], v[174:177], v[112:115]
	v_mfma_f32_16x16x32_bf16 v[108:111], v[158:161], v[174:177], v[108:111]
	v_mfma_f32_16x16x32_bf16 v[96:99], v[150:153], v[182:185], v[96:99]
	v_mfma_f32_16x16x32_bf16 v[92:95], v[158:161], v[182:185], v[92:95]
	v_mfma_f32_16x16x32_bf16 v[80:83], v[150:153], v[190:193], v[80:83]
	v_mfma_f32_16x16x32_bf16 v[76:79], v[158:161], v[190:193], v[76:79]
	v_mfma_f32_16x16x32_bf16 v[120:123], v[194:197], v[162:165], 0
	v_mfma_f32_16x16x32_bf16 v[116:119], v[202:205], v[162:165], 0
	v_mfma_f32_16x16x32_bf16 v[104:107], v[194:197], v[170:173], 0
	v_mfma_f32_16x16x32_bf16 v[100:103], v[202:205], v[170:173], 0
	v_mfma_f32_16x16x32_bf16 v[88:91], v[194:197], v[178:181], 0
	v_mfma_f32_16x16x32_bf16 v[84:87], v[202:205], v[178:181], 0
	v_mfma_f32_16x16x32_bf16 v[72:75], v[194:197], v[186:189], 0
	v_mfma_f32_16x16x32_bf16 v[68:71], v[202:205], v[186:189], 0
	v_mfma_f32_16x16x32_bf16 v[120:123], v[198:201], v[166:169], v[120:123]
	v_mfma_f32_16x16x32_bf16 v[116:119], v[206:209], v[166:169], v[116:119]
	v_mfma_f32_16x16x32_bf16 v[104:107], v[198:201], v[174:177], v[104:107]
	v_mfma_f32_16x16x32_bf16 v[100:103], v[206:209], v[174:177], v[100:103]
	v_mfma_f32_16x16x32_bf16 v[88:91], v[198:201], v[182:185], v[88:91]
	v_mfma_f32_16x16x32_bf16 v[84:87], v[206:209], v[182:185], v[84:87]
	v_mfma_f32_16x16x32_bf16 v[72:75], v[198:201], v[190:193], v[72:75]
	v_mfma_f32_16x16x32_bf16 v[68:71], v[206:209], v[190:193], v[68:71]
	s_barrier
	s_setprio 0
	ds_read_b128 v[162:165], v149 offset:16384
	ds_read_b128 v[166:169], v149 offset:17408
	ds_read_b128 v[170:173], v149 offset:18432
	ds_read_b128 v[174:177], v149 offset:19456
	ds_read_b128 v[178:181], v149 offset:20480
	ds_read_b128 v[182:185], v149 offset:21504
	ds_read_b128 v[186:189], v149 offset:22528
	ds_read_b128 v[190:193], v149 offset:23552
	s_add_i32 s56, s56, s30
	v_lshl_add_u64 v[210:211], s[20:21], 0, v[136:137]
	s_mov_b32 m0, s56
	s_nop 0
	global_load_lds_dwordx4 v[210:211], off
	v_lshl_add_u64 v[212:213], s[20:21], 0, v[132:133]
	s_add_i32 m0, s56, 0x2000
	s_nop 0
	global_load_lds_dwordx4 v[212:213], off
	s_mov_b32 m0, s31
	v_lshl_add_u64 v[216:217], s[24:25], 0, v[138:139]
	global_load_lds_dwordx4 v[216:217], off
	v_lshl_add_u64 v[218:219], s[24:25], 0, v[134:135]
	s_mov_b32 m0, s35
	s_nop 0
	global_load_lds_dwordx4 v[218:219], off
	s_add_u32 s56, s20, 0x80000
	s_addc_u32 s57, s21, 0
	s_add_i32 s58, s58, s30
	s_mov_b32 m0, s58
	s_nop 0
	global_load_lds_dwordx4 v136, s[56:57]
	s_add_i32 m0, s58, 0x2000
	s_nop 0
	global_load_lds_dwordx4 v132, s[56:57]
	s_waitcnt lgkmcnt(0)
	s_waitcnt vmcnt(6)
	s_setprio 1
	s_barrier
; #define PG8_STAGE(bufoff, gbase, voff) do { _Pragma("unroll") for (int _i = 0; _i < 2; ++_i) \
;         __builtin_amdgcn_global_load_lds((const unsigned*)((const char*)(gbase) + (voff)[_i]), (LAS unsigned*)(lds + (bufoff) + ldsw + _i * 8192), 16, 0, 0); } while (0)
; #define PG8_LDA(dst, b, h) do { _Pragma("unroll") for (int m = 0; m < 4; ++m) _Pragma("unroll") for (int k = 0; k < 2; ++k) dst[m][k] = *(const LAS bf16x8*)(lds + PG8_SA(b, h) + aoff + m * 2048 + k * 1024); } while (0)
; #define PG8_LDB(dst, b, h) do { _Pragma("unroll") for (int n = 0; n < 2; ++n) _Pragma("unroll") for (int k = 0; k < 2; ++k) dst[n][k] = *(const LAS bf16x8*)(lds + PG8_SB(b, h) + boff + n * 2048 + k * 1024); } while (0)
; #define PG8_MMA(ai, bj, At, Bt) do { __builtin_amdgcn_s_setprio(1); _Pragma("unroll") for (int m = 0; m < 4; ++m) _Pragma("unroll") for (int n = 0; n < 2; ++n) _Pragma("unroll") for (int k = 0; k < 2; ++k) \
;         acc[ai][bj][m][n] = __builtin_amdgcn_mfma_f32_16x16x32_bf16(Bt[n][k], At[m][k], acc[ai][bj][m][n], 0, 0, 0); __builtin_amdgcn_s_setprio(0); } while (0)
; #define PG8_WAIT_V(n) asm volatile("s_waitcnt vmcnt(" #n ")" ::: "memory")
; #define PG8_WAIT_L(n) asm volatile("s_waitcnt lgkmcnt(" #n ")" ::: "memory")
; #define PG8_BAR __builtin_amdgcn_s_barrier()
; #define PG8_SCHED __builtin_amdgcn_sched_barrier(0)
; template <class Epi, class Sched>
; __device__ __forceinline__ void gemm_phase(LAS unsigned char* lds, const Gemm g, const Sched& S, const Epi& E) {
;     ...
;             PG8_WAIT_V(6); PG8_BAR; PG8_MMA(1, 1, At, B1); PG8_BAR;
;             PG8_LDB(B0, 1, 0); PG8_SCHED; PG8_LDA(At, 1, 0); PG8_STAGE(PG8_SA(0, 1), a2 + hstepA, voffA);
;             PG8_WAIT_L(8); PG8_BAR; PG8_WAIT_L(0); PG8_MMA(0, 0, At, B0); PG8_BAR; PG8_SCHED;
;             PG8_LDB(B1, 1, 1); PG8_STAGE(PG8_SB(1, 0), b3, voffB);
;             PG8_BAR; PG8_WAIT_L(0); PG8_MMA(0, 1, At, B1); PG8_BAR;
;             PG8_LDA(At, 1, 1); PG8_STAGE(PG8_SA(1, 0), a3, voffA);
;             PG8_BAR; PG8_WAIT_L(0); PG8_MMA(1, 0, At, B0); PG8_BAR; PG8_SCHED;
	v_mfma_f32_16x16x32_bf16 v[64:67], v[144:147], v[162:165], 0
	v_mfma_f32_16x16x32_bf16 v[60:63], v[154:157], v[162:165], 0
	v_mfma_f32_16x16x32_bf16 v[48:51], v[144:147], v[170:173], 0
	v_mfma_f32_16x16x32_bf16 v[44:47], v[154:157], v[170:173], 0
	v_mfma_f32_16x16x32_bf16 v[32:35], v[144:147], v[178:181], 0
	v_mfma_f32_16x16x32_bf16 v[28:31], v[154:157], v[178:181], 0
	v_mfma_f32_16x16x32_bf16 v[16:19], v[144:147], v[186:189], 0
	v_mfma_f32_16x16x32_bf16 v[12:15], v[154:157], v[186:189], 0
	v_mfma_f32_16x16x32_bf16 v[64:67], v[150:153], v[166:169], v[64:67]
	v_mfma_f32_16x16x32_bf16 v[60:63], v[158:161], v[166:169], v[60:63]
	v_mfma_f32_16x16x32_bf16 v[48:51], v[150:153], v[174:177], v[48:51]
	v_mfma_f32_16x16x32_bf16 v[44:47], v[158:161], v[174:177], v[44:47]
	v_mfma_f32_16x16x32_bf16 v[32:35], v[150:153], v[182:185], v[32:35]
	v_mfma_f32_16x16x32_bf16 v[28:31], v[158:161], v[182:185], v[28:31]
	v_mfma_f32_16x16x32_bf16 v[16:19], v[150:153], v[190:193], v[16:19]
	v_mfma_f32_16x16x32_bf16 v[12:15], v[158:161], v[190:193], v[12:15]
	v_mfma_f32_16x16x32_bf16 v[56:59], v[194:197], v[162:165], 0
	v_mfma_f32_16x16x32_bf16 v[52:55], v[202:205], v[162:165], 0
	v_mfma_f32_16x16x32_bf16 v[40:43], v[194:197], v[170:173], 0
	v_mfma_f32_16x16x32_bf16 v[36:39], v[202:205], v[170:173], 0
	v_mfma_f32_16x16x32_bf16 v[24:27], v[194:197], v[178:181], 0
	v_mfma_f32_16x16x32_bf16 v[20:23], v[202:205], v[178:181], 0
	v_mfma_f32_16x16x32_bf16 v[8:11], v[194:197], v[186:189], 0
	v_mfma_f32_16x16x32_bf16 v[4:7], v[202:205], v[186:189], 0
	v_mfma_f32_16x16x32_bf16 v[56:59], v[198:201], v[166:169], v[56:59]
	v_mfma_f32_16x16x32_bf16 v[52:55], v[206:209], v[166:169], v[52:55]
	v_mfma_f32_16x16x32_bf16 v[40:43], v[198:201], v[174:177], v[40:43]
	v_mfma_f32_16x16x32_bf16 v[36:39], v[206:209], v[174:177], v[36:39]
	v_mfma_f32_16x16x32_bf16 v[24:27], v[198:201], v[182:185], v[24:27]
	v_mfma_f32_16x16x32_bf16 v[20:23], v[206:209], v[182:185], v[20:23]
	v_mfma_f32_16x16x32_bf16 v[8:11], v[198:201], v[190:193], v[8:11]
	v_mfma_f32_16x16x32_bf16 v[4:7], v[206:209], v[190:193], v[4:7]
	s_barrier
	s_setprio 0
	s_add_i32 s56, 0, 0x18000
	v_add_u32_e32 v2, s56, v1
	ds_read_b128 v[144:147], v2
	ds_read_b128 v[150:153], v2 offset:1024
	ds_read_b128 v[154:157], v2 offset:2048
	ds_read_b128 v[158:161], v2 offset:3072
	s_add_u32 s24, s24, 0x80000
	s_addc_u32 s25, s25, 0
	ds_read_b128 v[162:165], v149 offset:32768
	ds_read_b128 v[166:169], v149 offset:33792
	ds_read_b128 v[170:173], v149 offset:34816
	ds_read_b128 v[174:177], v149 offset:35840
	ds_read_b128 v[178:181], v149 offset:36864
	ds_read_b128 v[182:185], v149 offset:37888
	ds_read_b128 v[186:189], v149 offset:38912
	ds_read_b128 v[190:193], v149 offset:39936
	s_mov_b32 m0, s36
	s_nop 0
	global_load_lds_dwordx4 v138, s[24:25]
	s_mov_b32 m0, s37
	s_nop 0
	global_load_lds_dwordx4 v134, s[24:25]
	s_add_i32 s24, 0, 0x1c000
	v_add_u32_e32 v2, s24, v1
	ds_read_b128 v[194:197], v2
	ds_read_b128 v[198:201], v2 offset:1024
	ds_read_b128 v[202:205], v2 offset:2048
	ds_read_b128 v[206:209], v2 offset:3072
	s_waitcnt lgkmcnt(0)
	s_setprio 1
	s_barrier
	v_mfma_f32_16x16x32_bf16 v[128:131], v[144:147], v[162:165], v[128:131]
	v_mfma_f32_16x16x32_bf16 v[124:127], v[154:157], v[162:165], v[124:127]
	v_mfma_f32_16x16x32_bf16 v[112:115], v[144:147], v[170:173], v[112:115]
	v_mfma_f32_16x16x32_bf16 v[108:111], v[154:157], v[170:173], v[108:111]
	v_mfma_f32_16x16x32_bf16 v[96:99], v[144:147], v[178:181], v[96:99]
	v_mfma_f32_16x16x32_bf16 v[92:95], v[154:157], v[178:181], v[92:95]
	v_mfma_f32_16x16x32_bf16 v[80:83], v[144:147], v[186:189], v[80:83]
	v_mfma_f32_16x16x32_bf16 v[76:79], v[154:157], v[186:189], v[76:79]
	v_mfma_f32_16x16x32_bf16 v[128:131], v[150:153], v[166:169], v[128:131]
	v_mfma_f32_16x16x32_bf16 v[124:127], v[158:161], v[166:169], v[124:127]
	v_mfma_f32_16x16x32_bf16 v[112:115], v[150:153], v[174:177], v[112:115]
	v_mfma_f32_16x16x32_bf16 v[108:111], v[158:161], v[174:177], v[108:111]
	v_mfma_f32_16x16x32_bf16 v[96:99], v[150:153], v[182:185], v[96:99]
	v_mfma_f32_16x16x32_bf16 v[92:95], v[158:161], v[182:185], v[92:95]
	v_mfma_f32_16x16x32_bf16 v[80:83], v[150:153], v[190:193], v[80:83]
	v_mfma_f32_16x16x32_bf16 v[76:79], v[158:161], v[190:193], v[76:79]
	v_mfma_f32_16x16x32_bf16 v[120:123], v[194:197], v[162:165], v[120:123]
	v_mfma_f32_16x16x32_bf16 v[116:119], v[202:205], v[162:165], v[116:119]
	v_mfma_f32_16x16x32_bf16 v[104:107], v[194:197], v[170:173], v[104:107]
	v_mfma_f32_16x16x32_bf16 v[100:103], v[202:205], v[170:173], v[100:103]
	v_mfma_f32_16x16x32_bf16 v[88:91], v[194:197], v[178:181], v[88:91]
	v_mfma_f32_16x16x32_bf16 v[84:87], v[202:205], v[178:181], v[84:87]
	v_mfma_f32_16x16x32_bf16 v[72:75], v[194:197], v[186:189], v[72:75]
	v_mfma_f32_16x16x32_bf16 v[68:71], v[202:205], v[186:189], v[68:71]
	v_mfma_f32_16x16x32_bf16 v[120:123], v[198:201], v[166:169], v[120:123]
	v_mfma_f32_16x16x32_bf16 v[116:119], v[206:209], v[166:169], v[116:119]
	v_mfma_f32_16x16x32_bf16 v[104:107], v[198:201], v[174:177], v[104:107]
	v_mfma_f32_16x16x32_bf16 v[100:103], v[206:209], v[174:177], v[100:103]
	v_mfma_f32_16x16x32_bf16 v[88:91], v[198:201], v[182:185], v[88:91]
	v_mfma_f32_16x16x32_bf16 v[84:87], v[206:209], v[182:185], v[84:87]
	v_mfma_f32_16x16x32_bf16 v[72:75], v[198:201], v[190:193], v[72:75]
	v_mfma_f32_16x16x32_bf16 v[68:71], v[206:209], v[190:193], v[68:71]
	s_barrier
; #define PG8_STAGE(bufoff, gbase, voff) do { _Pragma("unroll") for (int _i = 0; _i < 2; ++_i) \
;         __builtin_amdgcn_global_load_lds((const unsigned*)((const char*)(gbase) + (voff)[_i]), (LAS unsigned*)(lds + (bufoff) + ldsw + _i * 8192), 16, 0, 0); } while (0)
; #define PG8_LDA(dst, b, h) do { _Pragma("unroll") for (int m = 0; m < 4; ++m) _Pragma("unroll") for (int k = 0; k < 2; ++k) dst[m][k] = *(const LAS bf16x8*)(lds + PG8_SA(b, h) + aoff + m * 2048 + k * 1024); } while (0)
; #define PG8_MMA(ai, bj, At, Bt) do { __builtin_amdgcn_s_setprio(1); _Pragma("unroll") for (int m = 0; m < 4; ++m) _Pragma("unroll") for (int n = 0; n < 2; ++n) _Pragma("unroll") for (int k = 0; k < 2; ++k) \
;         acc[ai][bj][m][n] = __builtin_amdgcn_mfma_f32_16x16x32_bf16(Bt[n][k], At[m][k], acc[ai][bj][m][n], 0, 0, 0); __builtin_amdgcn_s_setprio(0); } while (0)
; #define PG8_WAIT_V(n) asm volatile("s_waitcnt vmcnt(" #n ")" ::: "memory")
; #define PG8_WAIT_L(n) asm volatile("s_waitcnt lgkmcnt(" #n ")" ::: "memory")
; #define PG8_BAR __builtin_amdgcn_s_barrier()
; #define PG8_SCHED __builtin_amdgcn_sched_barrier(0)
; template <class Epi, class Sched>
; __device__ __forceinline__ void gemm_phase(LAS unsigned char* lds, const Gemm g, const Sched& S, const Epi& E) {
;     ...
;             PG8_LDA(At, 1, 1); PG8_STAGE(PG8_SA(1, 0), a3, voffA);
;             PG8_BAR; PG8_WAIT_L(0); PG8_MMA(1, 0, At, B0); PG8_BAR; PG8_SCHED;
;             PG8_STAGE(PG8_SB(1, 1), b3 + hstepB, voffB);
;             PG8_WAIT_V(6); PG8_BAR; PG8_MMA(1, 1, At, B1); PG8_BAR;
;         }
	s_setprio 0
	ds_read_b128 v[162:165], v149 offset:49152
	ds_read_b128 v[166:169], v149 offset:50176
	ds_read_b128 v[170:173], v149 offset:51200
	ds_read_b128 v[174:177], v149 offset:52224
	ds_read_b128 v[178:181], v149 offset:53248
	ds_read_b128 v[182:185], v149 offset:54272
	ds_read_b128 v[186:189], v149 offset:55296
	ds_read_b128 v[190:193], v149 offset:56320
	s_add_i32 s25, s56, s30
	v_lshl_add_u64 v[210:211], v[210:211], 0, s[8:9]
	s_mov_b32 m0, s25
	s_nop 0
	global_load_lds_dwordx4 v[210:211], off
	v_lshl_add_u64 v[210:211], v[212:213], 0, s[8:9]
	s_add_i32 m0, s25, 0x2000
	s_nop 0
	global_load_lds_dwordx4 v[210:211], off
	s_mov_b32 m0, s40
	v_lshl_add_u64 v[210:211], v[216:217], 0, s[8:9]
	global_load_lds_dwordx4 v[210:211], off
	v_lshl_add_u64 v[210:211], v[218:219], 0, s[8:9]
	s_mov_b32 m0, s41
	s_nop 0
	global_load_lds_dwordx4 v[210:211], off
	s_add_u32 s20, s20, 0x80080
	s_addc_u32 s21, s21, 0
	s_add_i32 s24, s24, s30
	s_mov_b32 m0, s24
	s_nop 0
	global_load_lds_dwordx4 v136, s[20:21]
	s_add_i32 m0, s24, 0x2000
	s_nop 0
	global_load_lds_dwordx4 v132, s[20:21]
	s_add_i32 s55, s55, 2
	s_add_u32 s6, s6, 0x100
	s_addc_u32 s7, s7, 0
	s_add_u32 s53, s53, 0x100
	s_addc_u32 s54, s54, 0
	s_cmp_gt_u32 s55, 29
	s_waitcnt lgkmcnt(0)
	s_waitcnt vmcnt(6)
	s_setprio 1
	s_barrier
	v_mfma_f32_16x16x32_bf16 v[64:67], v[144:147], v[162:165], v[64:67]
	v_mfma_f32_16x16x32_bf16 v[60:63], v[154:157], v[162:165], v[60:63]
	v_mfma_f32_16x16x32_bf16 v[48:51], v[144:147], v[170:173], v[48:51]
	v_mfma_f32_16x16x32_bf16 v[44:47], v[154:157], v[170:173], v[44:47]
	v_mfma_f32_16x16x32_bf16 v[32:35], v[144:147], v[178:181], v[32:35]
	v_mfma_f32_16x16x32_bf16 v[28:31], v[154:157], v[178:181], v[28:31]
	v_mfma_f32_16x16x32_bf16 v[16:19], v[144:147], v[186:189], v[16:19]
	v_mfma_f32_16x16x32_bf16 v[12:15], v[154:157], v[186:189], v[12:15]
	v_mfma_f32_16x16x32_bf16 v[64:67], v[150:153], v[166:169], v[64:67]
	v_mfma_f32_16x16x32_bf16 v[60:63], v[158:161], v[166:169], v[60:63]
	v_mfma_f32_16x16x32_bf16 v[48:51], v[150:153], v[174:177], v[48:51]
	v_mfma_f32_16x16x32_bf16 v[44:47], v[158:161], v[174:177], v[44:47]
	v_mfma_f32_16x16x32_bf16 v[32:35], v[150:153], v[182:185], v[32:35]
	v_mfma_f32_16x16x32_bf16 v[28:31], v[158:161], v[182:185], v[28:31]
	v_mfma_f32_16x16x32_bf16 v[16:19], v[150:153], v[190:193], v[16:19]
	v_mfma_f32_16x16x32_bf16 v[12:15], v[158:161], v[190:193], v[12:15]
	v_mfma_f32_16x16x32_bf16 v[56:59], v[194:197], v[162:165], v[56:59]
	v_mfma_f32_16x16x32_bf16 v[52:55], v[202:205], v[162:165], v[52:55]
	v_mfma_f32_16x16x32_bf16 v[40:43], v[194:197], v[170:173], v[40:43]
	v_mfma_f32_16x16x32_bf16 v[36:39], v[202:205], v[170:173], v[36:39]
	v_mfma_f32_16x16x32_bf16 v[24:27], v[194:197], v[178:181], v[24:27]
	v_mfma_f32_16x16x32_bf16 v[20:23], v[202:205], v[178:181], v[20:23]
	v_mfma_f32_16x16x32_bf16 v[8:11], v[194:197], v[186:189], v[8:11]
	v_mfma_f32_16x16x32_bf16 v[4:7], v[202:205], v[186:189], v[4:7]
	v_mfma_f32_16x16x32_bf16 v[56:59], v[198:201], v[166:169], v[56:59]
	v_mfma_f32_16x16x32_bf16 v[52:55], v[206:209], v[166:169], v[52:55]
	v_mfma_f32_16x16x32_bf16 v[40:43], v[198:201], v[174:177], v[40:43]
	v_mfma_f32_16x16x32_bf16 v[36:39], v[206:209], v[174:177], v[36:39]
	v_mfma_f32_16x16x32_bf16 v[24:27], v[198:201], v[182:185], v[24:27]
	v_mfma_f32_16x16x32_bf16 v[20:23], v[206:209], v[182:185], v[20:23]
	v_mfma_f32_16x16x32_bf16 v[8:11], v[198:201], v[190:193], v[8:11]
	v_mfma_f32_16x16x32_bf16 v[4:7], v[206:209], v[190:193], v[4:7]
	s_barrier
	s_setprio 0

; #define PG8_STAGE(bufoff, gbase, voff) do { _Pragma("unroll") for (int _i = 0; _i < 2; ++_i) \
;         __builtin_amdgcn_global_load_lds((const unsigned*)((const char*)(gbase) + (voff)[_i]), (LAS unsigned*)(lds + (bufoff) + ldsw + _i * 8192), 16, 0, 0); } while (0)
; #define PG8_LDA(dst, b, h) do { _Pragma("unroll") for (int m = 0; m < 4; ++m) _Pragma("unroll") for (int k = 0; k < 2; ++k) dst[m][k] = *(const LAS bf16x8*)(lds + PG8_SA(b, h) + aoff + m * 2048 + k * 1024); } while (0)
; #define PG8_LDB(dst, b, h) do { _Pragma("unroll") for (int n = 0; n < 2; ++n) _Pragma("unroll") for (int k = 0; k < 2; ++k) dst[n][k] = *(const LAS bf16x8*)(lds + PG8_SB(b, h) + boff + n * 2048 + k * 1024); } while (0)
; #define PG8_WAIT_V(n) asm volatile("s_waitcnt vmcnt(" #n ")" ::: "memory")
; #define PG8_WAIT_L(n) asm volatile("s_waitcnt lgkmcnt(" #n ")" ::: "memory")
; #define PG8_BAR __builtin_amdgcn_s_barrier()
; #define PG8_SCHED __builtin_amdgcn_sched_barrier(0)
; template <class Epi, class Sched>
; __device__ __forceinline__ void gemm_phase(LAS unsigned char* lds, const Gemm g, const Sched& S, const Epi& E) {
;     ...
;         const bool has_next = S.next(ui + 1, nxt);
;         const char* nA = has_next ? (const char*)g.A + (size_t)nxt.pm * tstepA : cA; const char* nB = has_next ? (const char*)g.Bt + (size_t)nxt.pn * tstepB : cB;
;         for (int t = 0; t < nt; t += 2) {
;             const bool last = (t == nt - 2);
;             const char* a1 = cA + (size_t)(t + 1) * kstep;
;             const char* a2 = last ? nA : cA + (size_t)(t + 2) * kstep; const char* b2 = last ? nB : cB + (size_t)(t + 2) * kstep;
;             const char* a3 = a2 + kstep; const char* b3 = b2 + kstep;
;             if (last && has_next) S.a_ready(nxt);
;             PG8_LDB(B0, 0, 0); PG8_SCHED; PG8_LDA(At, 0, 0); PG8_STAGE(PG8_SA(1, 1), a1 + hstepA, voffA);
;             PG8_WAIT_L(8); PG8_BAR; PG8_WAIT_L(0); PG8_MMA(0, 0, At, B0); PG8_BAR; PG8_SCHED;
;             PG8_LDB(B1, 0, 1); PG8_STAGE(PG8_SB(0, 0), b2, voffB);
;             PG8_BAR; PG8_WAIT_L(0); PG8_MMA(0, 1, At, B1); PG8_BAR;
;             PG8_LDA(At, 0, 1); PG8_STAGE(PG8_SA(0, 0), a2, voffA);
;             PG8_BAR; PG8_WAIT_L(0); PG8_MMA(1, 0, At, B0); PG8_BAR; PG8_SCHED;
;             PG8_STAGE(PG8_SB(0, 1), b2 + hstepB, voffB);
;             PG8_WAIT_V(6); PG8_BAR; PG8_MMA(1, 1, At, B1); PG8_BAR;
.LBB0_490:
	s_ashr_i32 s53, s52, 31
	s_lshl_b64 s[18:19], s[52:53], 20
	s_add_u32 s54, s25, s18
	v_cmp_lt_i64_e64 s[14:15], s[14:15], 16
	s_addc_u32 s55, s28, s19
	s_and_b64 s[18:19], s[14:15], exec
	s_cselect_b32 s18, s55, s5
	s_cselect_b32 s19, s54, s4
	s_ashr_i32 s51, s50, 31
	s_lshl_b64 s[56:57], s[50:51], 21
	s_add_u32 s56, s44, s56
	s_addc_u32 s57, s45, s57
	s_and_b64 s[14:15], s[14:15], exec
	s_cselect_b32 s51, s57, s7
	s_cselect_b32 s53, s56, s6
	s_add_u32 s4, s4, 0x80080
	s_addc_u32 s5, s5, 0
	s_add_u32 s65, s6, 0x100
	s_addc_u32 s66, s7, 0
	s_mov_b32 s67, -2
	s_waitcnt vmcnt(0)
	s_waitcnt lgkmcnt(0)
	s_setprio 0
	s_add_u32 s6, s4, 0xfff80080
	s_addc_u32 s7, s5, -1
	s_add_i32 s68, 0, 0x10000
	v_add_u32_e32 v154, s68, v1
	ds_read_b128 v[142:145], v154
	ds_read_b128 v[146:149], v154 offset:1024
	ds_read_b128 v[150:153], v154 offset:2048
	ds_read_b128 v[158:161], v154 offset:3072
	s_cmp_eq_u32 s67, 60
	s_cselect_b32 s15, s18, s7
	s_cselect_b32 s14, s19, s6
	s_cselect_b32 s7, s51, s66
	s_cselect_b32 s6, s53, s65
	ds_read_b128 v[162:165], v156
	ds_read_b128 v[166:169], v156 offset:1024
	ds_read_b128 v[170:173], v156 offset:2048
	ds_read_b128 v[174:177], v156 offset:3072
	ds_read_b128 v[178:181], v156 offset:4096
	ds_read_b128 v[182:185], v156 offset:5120
	ds_read_b128 v[186:189], v156 offset:6144
	ds_read_b128 v[190:193], v156 offset:7168
	s_add_i32 s70, 0, 0x14000
	v_add_u32_e32 v154, s70, v1
	ds_read_b128 v[194:197], v154
	ds_read_b128 v[198:201], v154 offset:1024
	ds_read_b128 v[202:205], v154 offset:2048
	ds_read_b128 v[206:209], v154 offset:3072
	s_add_i32 m0, s30, 0xc000
	s_nop 0
	global_load_lds_dwordx4 v138, s[4:5]
	s_add_i32 m0, s30, 0xe000
	s_nop 0
	global_load_lds_dwordx4 v140, s[4:5]
	s_waitcnt lgkmcnt(0)
	s_setprio 1
	s_barrier
	v_mfma_f32_16x16x32_bf16 v[128:131], v[142:145], v[162:165], 0
	v_mfma_f32_16x16x32_bf16 v[124:127], v[150:153], v[162:165], 0
	v_mfma_f32_16x16x32_bf16 v[120:123], v[142:145], v[170:173], 0
	v_mfma_f32_16x16x32_bf16 v[116:119], v[150:153], v[170:173], 0
	v_mfma_f32_16x16x32_bf16 v[112:115], v[142:145], v[178:181], 0
	v_mfma_f32_16x16x32_bf16 v[108:111], v[150:153], v[178:181], 0
	v_mfma_f32_16x16x32_bf16 v[104:107], v[142:145], v[186:189], 0
	v_mfma_f32_16x16x32_bf16 v[100:103], v[150:153], v[186:189], 0
	v_mfma_f32_16x16x32_bf16 v[128:131], v[146:149], v[166:169], v[128:131]
	v_mfma_f32_16x16x32_bf16 v[124:127], v[158:161], v[166:169], v[124:127]
	v_mfma_f32_16x16x32_bf16 v[120:123], v[146:149], v[174:177], v[120:123]
	v_mfma_f32_16x16x32_bf16 v[116:119], v[158:161], v[174:177], v[116:119]
	v_mfma_f32_16x16x32_bf16 v[112:115], v[146:149], v[182:185], v[112:115]
	v_mfma_f32_16x16x32_bf16 v[108:111], v[158:161], v[182:185], v[108:111]
	v_mfma_f32_16x16x32_bf16 v[104:107], v[146:149], v[190:193], v[104:107]
	v_mfma_f32_16x16x32_bf16 v[100:103], v[158:161], v[190:193], v[100:103]
	v_mfma_f32_16x16x32_bf16 v[64:67], v[194:197], v[162:165], 0
	v_mfma_f32_16x16x32_bf16 v[60:63], v[202:205], v[162:165], 0
	v_mfma_f32_16x16x32_bf16 v[56:59], v[194:197], v[170:173], 0
	v_mfma_f32_16x16x32_bf16 v[52:55], v[202:205], v[170:173], 0
	v_mfma_f32_16x16x32_bf16 v[48:51], v[194:197], v[178:181], 0
	v_mfma_f32_16x16x32_bf16 v[44:47], v[202:205], v[178:181], 0
	v_mfma_f32_16x16x32_bf16 v[40:43], v[194:197], v[186:189], 0
	v_mfma_f32_16x16x32_bf16 v[36:39], v[202:205], v[186:189], 0
	v_mfma_f32_16x16x32_bf16 v[64:67], v[198:201], v[166:169], v[64:67]
	v_mfma_f32_16x16x32_bf16 v[60:63], v[206:209], v[166:169], v[60:63]
	v_mfma_f32_16x16x32_bf16 v[56:59], v[198:201], v[174:177], v[56:59]
	v_mfma_f32_16x16x32_bf16 v[52:55], v[206:209], v[174:177], v[52:55]
	v_mfma_f32_16x16x32_bf16 v[48:51], v[198:201], v[182:185], v[48:51]
	v_mfma_f32_16x16x32_bf16 v[44:47], v[206:209], v[182:185], v[44:47]
	v_mfma_f32_16x16x32_bf16 v[40:43], v[198:201], v[190:193], v[40:43]
	v_mfma_f32_16x16x32_bf16 v[36:39], v[206:209], v[190:193], v[36:39]
	s_barrier
	s_setprio 0
	ds_read_b128 v[162:165], v156 offset:16384
	ds_read_b128 v[166:169], v156 offset:17408
	ds_read_b128 v[170:173], v156 offset:18432
	ds_read_b128 v[174:177], v156 offset:19456
	ds_read_b128 v[178:181], v156 offset:20480
	ds_read_b128 v[182:185], v156 offset:21504
	ds_read_b128 v[186:189], v156 offset:22528
	ds_read_b128 v[190:193], v156 offset:23552
	s_add_i32 s68, s68, s29
	v_lshl_add_u64 v[154:155], s[6:7], 0, v[2:3]
	s_mov_b32 m0, s68
	v_lshl_add_u64 v[210:211], s[6:7], 0, v[136:137]
	global_load_lds_dwordx4 v[154:155], off
	s_add_i32 m0, s68, 0x2000
	s_nop 0
	global_load_lds_dwordx4 v[210:211], off
	s_mov_b32 m0, s30
	v_lshl_add_u64 v[212:213], s[14:15], 0, v[132:133]
	global_load_lds_dwordx4 v[212:213], off
	v_lshl_add_u64 v[216:217], s[14:15], 0, v[134:135]
	s_mov_b32 m0, s31
	s_nop 0
	global_load_lds_dwordx4 v[216:217], off
	s_add_u32 s68, s6, 0x100000
	s_addc_u32 s69, s7, 0
	s_add_i32 s70, s70, s29
	s_mov_b32 m0, s70
	s_nop 0
	global_load_lds_dwordx4 v2, s[68:69]
	s_add_i32 m0, s70, 0x2000
	s_nop 0
	global_load_lds_dwordx4 v136, s[68:69]
	s_waitcnt lgkmcnt(0)
	s_waitcnt vmcnt(6)
	s_setprio 1
	s_barrier
; #define PG8_STAGE(bufoff, gbase, voff) do { _Pragma("unroll") for (int _i = 0; _i < 2; ++_i) \
;         __builtin_amdgcn_global_load_lds((const unsigned*)((const char*)(gbase) + (voff)[_i]), (LAS unsigned*)(lds + (bufoff) + ldsw + _i * 8192), 16, 0, 0); } while (0)
; #define PG8_LDA(dst, b, h) do { _Pragma("unroll") for (int m = 0; m < 4; ++m) _Pragma("unroll") for (int k = 0; k < 2; ++k) dst[m][k] = *(const LAS bf16x8*)(lds + PG8_SA(b, h) + aoff + m * 2048 + k * 1024); } while (0)
; #define PG8_LDB(dst, b, h) do { _Pragma("unroll") for (int n = 0; n < 2; ++n) _Pragma("unroll") for (int k = 0; k < 2; ++k) dst[n][k] = *(const LAS bf16x8*)(lds + PG8_SB(b, h) + boff + n * 2048 + k * 1024); } while (0)
; #define PG8_MMA(ai, bj, At, Bt) do { __builtin_amdgcn_s_setprio(1); _Pragma("unroll") for (int m = 0; m < 4; ++m) _Pragma("unroll") for (int n = 0; n < 2; ++n) _Pragma("unroll") for (int k = 0; k < 2; ++k) \
;         acc[ai][bj][m][n] = __builtin_amdgcn_mfma_f32_16x16x32_bf16(Bt[n][k], At[m][k], acc[ai][bj][m][n], 0, 0, 0); __builtin_amdgcn_s_setprio(0); } while (0)
; #define PG8_WAIT_V(n) asm volatile("s_waitcnt vmcnt(" #n ")" ::: "memory")
; #define PG8_WAIT_L(n) asm volatile("s_waitcnt lgkmcnt(" #n ")" ::: "memory")
; #define PG8_BAR __builtin_amdgcn_s_barrier()
; #define PG8_SCHED __builtin_amdgcn_sched_barrier(0)
; template <class Epi, class Sched>
; __device__ __forceinline__ void gemm_phase(LAS unsigned char* lds, const Gemm g, const Sched& S, const Epi& E) {
;     ...
;             PG8_WAIT_V(6); PG8_BAR; PG8_MMA(1, 1, At, B1); PG8_BAR;
;             PG8_LDB(B0, 1, 0); PG8_SCHED; PG8_LDA(At, 1, 0); PG8_STAGE(PG8_SA(0, 1), a2 + hstepA, voffA);
;             PG8_WAIT_L(8); PG8_BAR; PG8_WAIT_L(0); PG8_MMA(0, 0, At, B0); PG8_BAR; PG8_SCHED;
;             PG8_LDB(B1, 1, 1); PG8_STAGE(PG8_SB(1, 0), b3, voffB);
;             PG8_BAR; PG8_WAIT_L(0); PG8_MMA(0, 1, At, B1); PG8_BAR;
;             PG8_LDA(At, 1, 1); PG8_STAGE(PG8_SA(1, 0), a3, voffA);
;             PG8_BAR; PG8_WAIT_L(0); PG8_MMA(1, 0, At, B0); PG8_BAR; PG8_SCHED;
	v_mfma_f32_16x16x32_bf16 v[96:99], v[142:145], v[162:165], 0
	v_mfma_f32_16x16x32_bf16 v[92:95], v[150:153], v[162:165], 0
	v_mfma_f32_16x16x32_bf16 v[88:91], v[142:145], v[170:173], 0
	v_mfma_f32_16x16x32_bf16 v[84:87], v[150:153], v[170:173], 0
	v_mfma_f32_16x16x32_bf16 v[80:83], v[142:145], v[178:181], 0
	v_mfma_f32_16x16x32_bf16 v[76:79], v[150:153], v[178:181], 0
	v_mfma_f32_16x16x32_bf16 v[72:75], v[142:145], v[186:189], 0
	v_mfma_f32_16x16x32_bf16 v[68:71], v[150:153], v[186:189], 0
	v_mfma_f32_16x16x32_bf16 v[96:99], v[146:149], v[166:169], v[96:99]
	v_mfma_f32_16x16x32_bf16 v[92:95], v[158:161], v[166:169], v[92:95]
	v_mfma_f32_16x16x32_bf16 v[88:91], v[146:149], v[174:177], v[88:91]
	v_mfma_f32_16x16x32_bf16 v[84:87], v[158:161], v[174:177], v[84:87]
	v_mfma_f32_16x16x32_bf16 v[80:83], v[146:149], v[182:185], v[80:83]
	v_mfma_f32_16x16x32_bf16 v[76:79], v[158:161], v[182:185], v[76:79]
	v_mfma_f32_16x16x32_bf16 v[72:75], v[146:149], v[190:193], v[72:75]
	v_mfma_f32_16x16x32_bf16 v[68:71], v[158:161], v[190:193], v[68:71]
	v_mfma_f32_16x16x32_bf16 v[32:35], v[194:197], v[162:165], 0
	v_mfma_f32_16x16x32_bf16 v[28:31], v[202:205], v[162:165], 0
	v_mfma_f32_16x16x32_bf16 v[24:27], v[194:197], v[170:173], 0
	v_mfma_f32_16x16x32_bf16 v[20:23], v[202:205], v[170:173], 0
	v_mfma_f32_16x16x32_bf16 v[16:19], v[194:197], v[178:181], 0
	v_mfma_f32_16x16x32_bf16 v[12:15], v[202:205], v[178:181], 0
	v_mfma_f32_16x16x32_bf16 v[8:11], v[194:197], v[186:189], 0
	v_mfma_f32_16x16x32_bf16 v[4:7], v[202:205], v[186:189], 0
	v_mfma_f32_16x16x32_bf16 v[32:35], v[198:201], v[166:169], v[32:35]
	v_mfma_f32_16x16x32_bf16 v[28:31], v[206:209], v[166:169], v[28:31]
	v_mfma_f32_16x16x32_bf16 v[24:27], v[198:201], v[174:177], v[24:27]
	v_mfma_f32_16x16x32_bf16 v[20:23], v[206:209], v[174:177], v[20:23]
	v_mfma_f32_16x16x32_bf16 v[16:19], v[198:201], v[182:185], v[16:19]
	v_mfma_f32_16x16x32_bf16 v[12:15], v[206:209], v[182:185], v[12:15]
	v_mfma_f32_16x16x32_bf16 v[8:11], v[198:201], v[190:193], v[8:11]
	v_mfma_f32_16x16x32_bf16 v[4:7], v[206:209], v[190:193], v[4:7]
	s_barrier
	s_setprio 0
	s_add_i32 s68, 0, 0x18000
	v_add_u32_e32 v157, s68, v1
	ds_read_b128 v[142:145], v157
	ds_read_b128 v[146:149], v157 offset:1024
	ds_read_b128 v[150:153], v157 offset:2048
	ds_read_b128 v[158:161], v157 offset:3072
	s_add_u32 s14, s14, 0x80000
	s_addc_u32 s15, s15, 0
	ds_read_b128 v[162:165], v156 offset:32768
	ds_read_b128 v[166:169], v156 offset:33792
	ds_read_b128 v[170:173], v156 offset:34816
	ds_read_b128 v[174:177], v156 offset:35840
	ds_read_b128 v[178:181], v156 offset:36864
	ds_read_b128 v[182:185], v156 offset:37888
	ds_read_b128 v[186:189], v156 offset:38912
	ds_read_b128 v[190:193], v156 offset:39936
	s_mov_b32 m0, s38
	s_nop 0
	global_load_lds_dwordx4 v132, s[14:15]
	s_mov_b32 m0, s39
	s_nop 0
	global_load_lds_dwordx4 v134, s[14:15]
	s_add_i32 s14, 0, 0x1c000
	v_add_u32_e32 v157, s14, v1
	ds_read_b128 v[194:197], v157
	ds_read_b128 v[198:201], v157 offset:1024
	ds_read_b128 v[202:205], v157 offset:2048
	ds_read_b128 v[206:209], v157 offset:3072
	s_waitcnt lgkmcnt(0)
	s_setprio 1
	s_barrier
	v_mfma_f32_16x16x32_bf16 v[128:131], v[142:145], v[162:165], v[128:131]
	v_mfma_f32_16x16x32_bf16 v[124:127], v[150:153], v[162:165], v[124:127]
	v_mfma_f32_16x16x32_bf16 v[120:123], v[142:145], v[170:173], v[120:123]
	v_mfma_f32_16x16x32_bf16 v[116:119], v[150:153], v[170:173], v[116:119]
	v_mfma_f32_16x16x32_bf16 v[112:115], v[142:145], v[178:181], v[112:115]
	v_mfma_f32_16x16x32_bf16 v[108:111], v[150:153], v[178:181], v[108:111]
	v_mfma_f32_16x16x32_bf16 v[104:107], v[142:145], v[186:189], v[104:107]
	v_mfma_f32_16x16x32_bf16 v[100:103], v[150:153], v[186:189], v[100:103]
	v_mfma_f32_16x16x32_bf16 v[128:131], v[146:149], v[166:169], v[128:131]
	v_mfma_f32_16x16x32_bf16 v[124:127], v[158:161], v[166:169], v[124:127]
	v_mfma_f32_16x16x32_bf16 v[120:123], v[146:149], v[174:177], v[120:123]
	v_mfma_f32_16x16x32_bf16 v[116:119], v[158:161], v[174:177], v[116:119]
	v_mfma_f32_16x16x32_bf16 v[112:115], v[146:149], v[182:185], v[112:115]
	v_mfma_f32_16x16x32_bf16 v[108:111], v[158:161], v[182:185], v[108:111]
	v_mfma_f32_16x16x32_bf16 v[104:107], v[146:149], v[190:193], v[104:107]
	v_mfma_f32_16x16x32_bf16 v[100:103], v[158:161], v[190:193], v[100:103]
	v_mfma_f32_16x16x32_bf16 v[64:67], v[194:197], v[162:165], v[64:67]
	v_mfma_f32_16x16x32_bf16 v[60:63], v[202:205], v[162:165], v[60:63]
	v_mfma_f32_16x16x32_bf16 v[56:59], v[194:197], v[170:173], v[56:59]
	v_mfma_f32_16x16x32_bf16 v[52:55], v[202:205], v[170:173], v[52:55]
	v_mfma_f32_16x16x32_bf16 v[48:51], v[194:197], v[178:181], v[48:51]
	v_mfma_f32_16x16x32_bf16 v[44:47], v[202:205], v[178:181], v[44:47]
	v_mfma_f32_16x16x32_bf16 v[40:43], v[194:197], v[186:189], v[40:43]
	v_mfma_f32_16x16x32_bf16 v[36:39], v[202:205], v[186:189], v[36:39]
	v_mfma_f32_16x16x32_bf16 v[64:67], v[198:201], v[166:169], v[64:67]
	v_mfma_f32_16x16x32_bf16 v[60:63], v[206:209], v[166:169], v[60:63]
	v_mfma_f32_16x16x32_bf16 v[56:59], v[198:201], v[174:177], v[56:59]
	v_mfma_f32_16x16x32_bf16 v[52:55], v[206:209], v[174:177], v[52:55]
	v_mfma_f32_16x16x32_bf16 v[48:51], v[198:201], v[182:185], v[48:51]
	v_mfma_f32_16x16x32_bf16 v[44:47], v[206:209], v[182:185], v[44:47]
	v_mfma_f32_16x16x32_bf16 v[40:43], v[198:201], v[190:193], v[40:43]
	v_mfma_f32_16x16x32_bf16 v[36:39], v[206:209], v[190:193], v[36:39]
	s_barrier
; #define PG8_STAGE(bufoff, gbase, voff) do { _Pragma("unroll") for (int _i = 0; _i < 2; ++_i) \
;         __builtin_amdgcn_global_load_lds((const unsigned*)((const char*)(gbase) + (voff)[_i]), (LAS unsigned*)(lds + (bufoff) + ldsw + _i * 8192), 16, 0, 0); } while (0)
; #define PG8_LDA(dst, b, h) do { _Pragma("unroll") for (int m = 0; m < 4; ++m) _Pragma("unroll") for (int k = 0; k < 2; ++k) dst[m][k] = *(const LAS bf16x8*)(lds + PG8_SA(b, h) + aoff + m * 2048 + k * 1024); } while (0)
; #define PG8_MMA(ai, bj, At, Bt) do { __builtin_amdgcn_s_setprio(1); _Pragma("unroll") for (int m = 0; m < 4; ++m) _Pragma("unroll") for (int n = 0; n < 2; ++n) _Pragma("unroll") for (int k = 0; k < 2; ++k) \
;         acc[ai][bj][m][n] = __builtin_amdgcn_mfma_f32_16x16x32_bf16(Bt[n][k], At[m][k], acc[ai][bj][m][n], 0, 0, 0); __builtin_amdgcn_s_setprio(0); } while (0)
; #define PG8_WAIT_V(n) asm volatile("s_waitcnt vmcnt(" #n ")" ::: "memory")
; #define PG8_WAIT_L(n) asm volatile("s_waitcnt lgkmcnt(" #n ")" ::: "memory")
; #define PG8_BAR __builtin_amdgcn_s_barrier()
; #define PG8_SCHED __builtin_amdgcn_sched_barrier(0)
; template <class Epi, class Sched>
; __device__ __forceinline__ void gemm_phase(LAS unsigned char* lds, const Gemm g, const Sched& S, const Epi& E) {
;     ...
;             PG8_LDA(At, 1, 1); PG8_STAGE(PG8_SA(1, 0), a3, voffA);
;             PG8_BAR; PG8_WAIT_L(0); PG8_MMA(1, 0, At, B0); PG8_BAR; PG8_SCHED;
;             PG8_STAGE(PG8_SB(1, 1), b3 + hstepB, voffB);
;             PG8_WAIT_V(6); PG8_BAR; PG8_MMA(1, 1, At, B1); PG8_BAR;
;         }
	s_setprio 0
	ds_read_b128 v[162:165], v156 offset:49152
	ds_read_b128 v[166:169], v156 offset:50176
	ds_read_b128 v[170:173], v156 offset:51200
	ds_read_b128 v[174:177], v156 offset:52224
	ds_read_b128 v[178:181], v156 offset:53248
	ds_read_b128 v[182:185], v156 offset:54272
	ds_read_b128 v[186:189], v156 offset:55296
	ds_read_b128 v[190:193], v156 offset:56320
	s_add_i32 s15, s68, s29
	v_lshl_add_u64 v[154:155], v[154:155], 0, s[8:9]
	s_mov_b32 m0, s15
	s_nop 0
	global_load_lds_dwordx4 v[154:155], off
	v_lshl_add_u64 v[154:155], v[210:211], 0, s[8:9]
	s_add_i32 m0, s15, 0x2000
	s_nop 0
	global_load_lds_dwordx4 v[154:155], off
	s_mov_b32 m0, s62
	v_lshl_add_u64 v[154:155], v[212:213], 0, s[8:9]
	global_load_lds_dwordx4 v[154:155], off
	v_lshl_add_u64 v[154:155], v[216:217], 0, s[8:9]
	s_mov_b32 m0, s63
	s_nop 0
	global_load_lds_dwordx4 v[154:155], off
	s_add_u32 s6, s6, 0x100080
	s_addc_u32 s7, s7, 0
	s_add_i32 s14, s14, s29
	s_mov_b32 m0, s14
	s_nop 0
	global_load_lds_dwordx4 v2, s[6:7]
	s_add_i32 m0, s14, 0x2000
	s_nop 0
	global_load_lds_dwordx4 v136, s[6:7]
	s_add_i32 s67, s67, 2
	s_add_u32 s4, s4, 0x100
	s_addc_u32 s5, s5, 0
	s_add_u32 s65, s65, 0x100
	s_addc_u32 s66, s66, 0
	s_cmp_gt_u32 s67, 61
	s_waitcnt lgkmcnt(0)
	s_waitcnt vmcnt(6)
	s_setprio 1
	s_barrier
	v_mfma_f32_16x16x32_bf16 v[96:99], v[142:145], v[162:165], v[96:99]
	v_mfma_f32_16x16x32_bf16 v[92:95], v[150:153], v[162:165], v[92:95]
	v_mfma_f32_16x16x32_bf16 v[88:91], v[142:145], v[170:173], v[88:91]
	v_mfma_f32_16x16x32_bf16 v[84:87], v[150:153], v[170:173], v[84:87]
	v_mfma_f32_16x16x32_bf16 v[80:83], v[142:145], v[178:181], v[80:83]
	v_mfma_f32_16x16x32_bf16 v[76:79], v[150:153], v[178:181], v[76:79]
	v_mfma_f32_16x16x32_bf16 v[72:75], v[142:145], v[186:189], v[72:75]
	v_mfma_f32_16x16x32_bf16 v[68:71], v[150:153], v[186:189], v[68:71]
	v_mfma_f32_16x16x32_bf16 v[96:99], v[146:149], v[166:169], v[96:99]
	v_mfma_f32_16x16x32_bf16 v[92:95], v[158:161], v[166:169], v[92:95]
	v_mfma_f32_16x16x32_bf16 v[88:91], v[146:149], v[174:177], v[88:91]
	v_mfma_f32_16x16x32_bf16 v[84:87], v[158:161], v[174:177], v[84:87]
	v_mfma_f32_16x16x32_bf16 v[80:83], v[146:149], v[182:185], v[80:83]
	v_mfma_f32_16x16x32_bf16 v[76:79], v[158:161], v[182:185], v[76:79]
	v_mfma_f32_16x16x32_bf16 v[72:75], v[146:149], v[190:193], v[72:75]
	v_mfma_f32_16x16x32_bf16 v[68:71], v[158:161], v[190:193], v[68:71]
	v_mfma_f32_16x16x32_bf16 v[32:35], v[194:197], v[162:165], v[32:35]
	v_mfma_f32_16x16x32_bf16 v[28:31], v[202:205], v[162:165], v[28:31]
	v_mfma_f32_16x16x32_bf16 v[24:27], v[194:197], v[170:173], v[24:27]
	v_mfma_f32_16x16x32_bf16 v[20:23], v[202:205], v[170:173], v[20:23]
	v_mfma_f32_16x16x32_bf16 v[16:19], v[194:197], v[178:181], v[16:19]
	v_mfma_f32_16x16x32_bf16 v[12:15], v[202:205], v[178:181], v[12:15]
	v_mfma_f32_16x16x32_bf16 v[8:11], v[194:197], v[186:189], v[8:11]
	v_mfma_f32_16x16x32_bf16 v[4:7], v[202:205], v[186:189], v[4:7]
	v_mfma_f32_16x16x32_bf16 v[32:35], v[198:201], v[166:169], v[32:35]
	v_mfma_f32_16x16x32_bf16 v[28:31], v[206:209], v[166:169], v[28:31]
	v_mfma_f32_16x16x32_bf16 v[24:27], v[198:201], v[174:177], v[24:27]
	v_mfma_f32_16x16x32_bf16 v[20:23], v[206:209], v[174:177], v[20:23]
	v_mfma_f32_16x16x32_bf16 v[16:19], v[198:201], v[182:185], v[16:19]
	v_mfma_f32_16x16x32_bf16 v[12:15], v[206:209], v[182:185], v[12:15]
	v_mfma_f32_16x16x32_bf16 v[8:11], v[198:201], v[190:193], v[8:11]
	v_mfma_f32_16x16x32_bf16 v[4:7], v[206:209], v[190:193], v[4:7]
	s_barrier
	s_setprio 0

; #define PG8_STAGE(bufoff, gbase, voff) do { _Pragma("unroll") for (int _i = 0; _i < 2; ++_i) \
;         __builtin_amdgcn_global_load_lds((const unsigned*)((const char*)(gbase) + (voff)[_i]), (LAS unsigned*)(lds + (bufoff) + ldsw + _i * 8192), 16, 0, 0); } while (0)
; #define PG8_LDA(dst, b, h) do { _Pragma("unroll") for (int m = 0; m < 4; ++m) _Pragma("unroll") for (int k = 0; k < 2; ++k) dst[m][k] = *(const LAS bf16x8*)(lds + PG8_SA(b, h) + aoff + m * 2048 + k * 1024); } while (0)
; #define PG8_LDB(dst, b, h) do { _Pragma("unroll") for (int n = 0; n < 2; ++n) _Pragma("unroll") for (int k = 0; k < 2; ++k) dst[n][k] = *(const LAS bf16x8*)(lds + PG8_SB(b, h) + boff + n * 2048 + k * 1024); } while (0)
; #define PG8_WAIT_V(n) asm volatile("s_waitcnt vmcnt(" #n ")" ::: "memory")
; #define PG8_WAIT_L(n) asm volatile("s_waitcnt lgkmcnt(" #n ")" ::: "memory")
; #define PG8_BAR __builtin_amdgcn_s_barrier()
; #define PG8_SCHED __builtin_amdgcn_sched_barrier(0)
; template <class Epi, class Sched>
; __device__ __forceinline__ void gemm_phase(LAS unsigned char* lds, const Gemm g, const Sched& S, const Epi& E) {
;     ...
;         const bool has_next = S.next(ui + 1, nxt);
;         const char* nA = has_next ? (const char*)g.A + (size_t)nxt.pm * tstepA : cA; const char* nB = has_next ? (const char*)g.Bt + (size_t)nxt.pn * tstepB : cB;
;         for (int t = 0; t < nt; t += 2) {
;             const bool last = (t == nt - 2);
;             const char* a1 = cA + (size_t)(t + 1) * kstep;
;             const char* a2 = last ? nA : cA + (size_t)(t + 2) * kstep; const char* b2 = last ? nB : cB + (size_t)(t + 2) * kstep;
;             const char* a3 = a2 + kstep; const char* b3 = b2 + kstep;
;             if (last && has_next) S.a_ready(nxt);
;             PG8_LDB(B0, 0, 0); PG8_SCHED; PG8_LDA(At, 0, 0); PG8_STAGE(PG8_SA(1, 1), a1 + hstepA, voffA);
;             PG8_WAIT_L(8); PG8_BAR; PG8_WAIT_L(0); PG8_MMA(0, 0, At, B0); PG8_BAR; PG8_SCHED;
;             PG8_LDB(B1, 0, 1); PG8_STAGE(PG8_SB(0, 0), b2, voffB);
;             PG8_BAR; PG8_WAIT_L(0); PG8_MMA(0, 1, At, B1); PG8_BAR;
;             PG8_LDA(At, 0, 1); PG8_STAGE(PG8_SA(0, 0), a2, voffA);
;             PG8_BAR; PG8_WAIT_L(0); PG8_MMA(1, 0, At, B0); PG8_BAR; PG8_SCHED;
;             PG8_STAGE(PG8_SB(0, 1), b2 + hstepB, voffB);
;             PG8_WAIT_V(6); PG8_BAR; PG8_MMA(1, 1, At, B1); PG8_BAR;
.LBB0_965:
	v_mov_b64_e32 v[4:5], 0x400
	s_ashr_i32 s15, s14, 31
	v_cmp_lt_i64_e32 vcc, s[4:5], v[4:5]
	s_lshl_b64 s[4:5], s[14:15], 20
	v_readlane_b32 s48, v252, 0
	v_readlane_b32 s49, v252, 1
	s_add_u32 s4, s48, s4
	s_addc_u32 s5, s49, s5
	s_and_b64 s[18:19], vcc, exec
	s_cselect_b32 s15, s5, s7
	s_cselect_b32 s47, s4, s6
	s_ashr_i32 s1, s0, 31
	s_lshl_b64 s[18:19], s[0:1], 20
	s_add_u32 s18, s28, s18
	s_addc_u32 s19, s29, s19
	s_and_b64 s[24:25], vcc, exec
	s_cselect_b32 s1, s19, s21
	s_cselect_b32 s48, s18, s20
	s_add_u32 s6, s6, 0x80080
	s_addc_u32 s7, s7, 0
	v_readlane_b32 s50, v252, 2
	v_readlane_b32 s51, v252, 3
	s_add_u32 s49, s20, 0x100
	s_addc_u32 s50, s21, 0
	s_mov_b32 s51, -2
	s_waitcnt vmcnt(0)
	s_waitcnt lgkmcnt(0)
	s_setprio 0
	s_add_u32 s20, s6, 0xfff80080
	s_addc_u32 s21, s7, -1
	s_add_i32 s52, 0, 0x10000
	v_add_u32_e32 v144, s52, v1
	ds_read_b128 v[132:135], v144
	ds_read_b128 v[136:139], v144 offset:1024
	ds_read_b128 v[140:143], v144 offset:2048
	ds_read_b128 v[144:147], v144 offset:3072
	s_cmp_eq_u32 s51, 28
	s_cselect_b32 s25, s15, s21
	s_cselect_b32 s24, s47, s20
	s_cselect_b32 s21, s1, s50
	s_cselect_b32 s20, s48, s49
	ds_read_b128 v[148:151], v224
	ds_read_b128 v[152:155], v224 offset:1024
	ds_read_b128 v[156:159], v224 offset:2048
	ds_read_b128 v[160:163], v224 offset:3072
	ds_read_b128 v[164:167], v224 offset:4096
	ds_read_b128 v[168:171], v224 offset:5120
	ds_read_b128 v[172:175], v224 offset:6144
	ds_read_b128 v[176:179], v224 offset:7168
	s_add_i32 s54, 0, 0x14000
	v_add_u32_e32 v202, s54, v1
	ds_read_b128 v[180:183], v202
	ds_read_b128 v[184:187], v202 offset:1024
	ds_read_b128 v[188:191], v202 offset:2048
	ds_read_b128 v[202:205], v202 offset:3072
	s_add_i32 m0, s31, 0xc000
	s_nop 0
	global_load_lds_dwordx4 v198, s[6:7]
	s_add_i32 m0, s31, 0xe000
	s_nop 0
	global_load_lds_dwordx4 v200, s[6:7]
	s_waitcnt lgkmcnt(0)
	s_setprio 1
	s_barrier
	v_mfma_f32_16x16x32_bf16 v[128:131], v[132:135], v[148:151], 0
	v_mfma_f32_16x16x32_bf16 v[124:127], v[140:143], v[148:151], 0
	v_mfma_f32_16x16x32_bf16 v[112:115], v[132:135], v[156:159], 0
	v_mfma_f32_16x16x32_bf16 v[108:111], v[140:143], v[156:159], 0
	v_mfma_f32_16x16x32_bf16 v[100:103], v[132:135], v[164:167], 0
	v_mfma_f32_16x16x32_bf16 v[92:95], v[140:143], v[164:167], 0
	v_mfma_f32_16x16x32_bf16 v[84:87], v[132:135], v[172:175], 0
	v_mfma_f32_16x16x32_bf16 v[76:79], v[140:143], v[172:175], 0
	v_mfma_f32_16x16x32_bf16 v[128:131], v[136:139], v[152:155], v[128:131]
	v_mfma_f32_16x16x32_bf16 v[124:127], v[144:147], v[152:155], v[124:127]
	v_mfma_f32_16x16x32_bf16 v[112:115], v[136:139], v[160:163], v[112:115]
	v_mfma_f32_16x16x32_bf16 v[108:111], v[144:147], v[160:163], v[108:111]
	v_mfma_f32_16x16x32_bf16 v[100:103], v[136:139], v[168:171], v[100:103]
	v_mfma_f32_16x16x32_bf16 v[92:95], v[144:147], v[168:171], v[92:95]
	v_mfma_f32_16x16x32_bf16 v[84:87], v[136:139], v[176:179], v[84:87]
	v_mfma_f32_16x16x32_bf16 v[76:79], v[144:147], v[176:179], v[76:79]
	v_mfma_f32_16x16x32_bf16 v[120:123], v[180:183], v[148:151], 0
	v_mfma_f32_16x16x32_bf16 v[116:119], v[188:191], v[148:151], 0
	v_mfma_f32_16x16x32_bf16 v[104:107], v[180:183], v[156:159], 0
	v_mfma_f32_16x16x32_bf16 v[96:99], v[188:191], v[156:159], 0
	v_mfma_f32_16x16x32_bf16 v[88:91], v[180:183], v[164:167], 0
	v_mfma_f32_16x16x32_bf16 v[80:83], v[188:191], v[164:167], 0
	v_mfma_f32_16x16x32_bf16 v[72:75], v[180:183], v[172:175], 0
	v_mfma_f32_16x16x32_bf16 v[68:71], v[188:191], v[172:175], 0
	v_mfma_f32_16x16x32_bf16 v[120:123], v[184:187], v[152:155], v[120:123]
	v_mfma_f32_16x16x32_bf16 v[116:119], v[202:205], v[152:155], v[116:119]
	v_mfma_f32_16x16x32_bf16 v[104:107], v[184:187], v[160:163], v[104:107]
	v_mfma_f32_16x16x32_bf16 v[96:99], v[202:205], v[160:163], v[96:99]
	v_mfma_f32_16x16x32_bf16 v[88:91], v[184:187], v[168:171], v[88:91]
	v_mfma_f32_16x16x32_bf16 v[80:83], v[202:205], v[168:171], v[80:83]
	v_mfma_f32_16x16x32_bf16 v[72:75], v[184:187], v[176:179], v[72:75]
	v_mfma_f32_16x16x32_bf16 v[68:71], v[202:205], v[176:179], v[68:71]
	s_barrier
	s_setprio 0
	ds_read_b128 v[148:151], v224 offset:16384
	ds_read_b128 v[152:155], v224 offset:17408
	ds_read_b128 v[156:159], v224 offset:18432
	ds_read_b128 v[160:163], v224 offset:19456
	ds_read_b128 v[164:167], v224 offset:20480
	ds_read_b128 v[168:171], v224 offset:21504
	ds_read_b128 v[172:175], v224 offset:22528
	ds_read_b128 v[176:179], v224 offset:23552
	s_add_i32 s52, s52, s30
	v_lshl_add_u64 v[206:207], s[20:21], 0, v[2:3]
	s_mov_b32 m0, s52
	s_nop 0
	global_load_lds_dwordx4 v[206:207], off
	v_lshl_add_u64 v[208:209], s[20:21], 0, v[192:193]
	s_add_i32 m0, s52, 0x2000
	s_nop 0
	global_load_lds_dwordx4 v[208:209], off
	s_mov_b32 m0, s31
	v_lshl_add_u64 v[210:211], s[24:25], 0, v[196:197]
	global_load_lds_dwordx4 v[210:211], off
	v_lshl_add_u64 v[212:213], s[24:25], 0, v[194:195]
	s_mov_b32 m0, s35
	s_nop 0
	global_load_lds_dwordx4 v[212:213], off
	s_add_u32 s52, s20, 0x80000
	s_addc_u32 s53, s21, 0
	s_add_i32 s54, s54, s30
	s_mov_b32 m0, s54
	s_nop 0
	global_load_lds_dwordx4 v2, s[52:53]
	s_add_i32 m0, s54, 0x2000
	s_nop 0
	global_load_lds_dwordx4 v192, s[52:53]
	s_waitcnt lgkmcnt(0)
	s_waitcnt vmcnt(6)
	s_setprio 1
	s_barrier
; #define PG8_STAGE(bufoff, gbase, voff) do { _Pragma("unroll") for (int _i = 0; _i < 2; ++_i) \
;         __builtin_amdgcn_global_load_lds((const unsigned*)((const char*)(gbase) + (voff)[_i]), (LAS unsigned*)(lds + (bufoff) + ldsw + _i * 8192), 16, 0, 0); } while (0)
; #define PG8_LDA(dst, b, h) do { _Pragma("unroll") for (int m = 0; m < 4; ++m) _Pragma("unroll") for (int k = 0; k < 2; ++k) dst[m][k] = *(const LAS bf16x8*)(lds + PG8_SA(b, h) + aoff + m * 2048 + k * 1024); } while (0)
; #define PG8_LDB(dst, b, h) do { _Pragma("unroll") for (int n = 0; n < 2; ++n) _Pragma("unroll") for (int k = 0; k < 2; ++k) dst[n][k] = *(const LAS bf16x8*)(lds + PG8_SB(b, h) + boff + n * 2048 + k * 1024); } while (0)
; #define PG8_MMA(ai, bj, At, Bt) do { __builtin_amdgcn_s_setprio(1); _Pragma("unroll") for (int m = 0; m < 4; ++m) _Pragma("unroll") for (int n = 0; n < 2; ++n) _Pragma("unroll") for (int k = 0; k < 2; ++k) \
;         acc[ai][bj][m][n] = __builtin_amdgcn_mfma_f32_16x16x32_bf16(Bt[n][k], At[m][k], acc[ai][bj][m][n], 0, 0, 0); __builtin_amdgcn_s_setprio(0); } while (0)
; #define PG8_WAIT_V(n) asm volatile("s_waitcnt vmcnt(" #n ")" ::: "memory")
; #define PG8_WAIT_L(n) asm volatile("s_waitcnt lgkmcnt(" #n ")" ::: "memory")
; #define PG8_BAR __builtin_amdgcn_s_barrier()
; #define PG8_SCHED __builtin_amdgcn_sched_barrier(0)
; template <class Epi, class Sched>
; __device__ __forceinline__ void gemm_phase(LAS unsigned char* lds, const Gemm g, const Sched& S, const Epi& E) {
;     ...
;             PG8_WAIT_V(6); PG8_BAR; PG8_MMA(1, 1, At, B1); PG8_BAR;
;             PG8_LDB(B0, 1, 0); PG8_SCHED; PG8_LDA(At, 1, 0); PG8_STAGE(PG8_SA(0, 1), a2 + hstepA, voffA);
;             PG8_WAIT_L(8); PG8_BAR; PG8_WAIT_L(0); PG8_MMA(0, 0, At, B0); PG8_BAR; PG8_SCHED;
;             PG8_LDB(B1, 1, 1); PG8_STAGE(PG8_SB(1, 0), b3, voffB);
;             PG8_BAR; PG8_WAIT_L(0); PG8_MMA(0, 1, At, B1); PG8_BAR;
;             PG8_LDA(At, 1, 1); PG8_STAGE(PG8_SA(1, 0), a3, voffA);
;             PG8_BAR; PG8_WAIT_L(0); PG8_MMA(1, 0, At, B0); PG8_BAR; PG8_SCHED;
	v_mfma_f32_16x16x32_bf16 v[64:67], v[132:135], v[148:151], 0
	v_mfma_f32_16x16x32_bf16 v[60:63], v[140:143], v[148:151], 0
	v_mfma_f32_16x16x32_bf16 v[52:55], v[132:135], v[156:159], 0
	v_mfma_f32_16x16x32_bf16 v[44:47], v[140:143], v[156:159], 0
	v_mfma_f32_16x16x32_bf16 v[36:39], v[132:135], v[164:167], 0
	v_mfma_f32_16x16x32_bf16 v[28:31], v[140:143], v[164:167], 0
	v_mfma_f32_16x16x32_bf16 v[20:23], v[132:135], v[172:175], 0
	v_mfma_f32_16x16x32_bf16 v[12:15], v[140:143], v[172:175], 0
	v_mfma_f32_16x16x32_bf16 v[64:67], v[136:139], v[152:155], v[64:67]
	v_mfma_f32_16x16x32_bf16 v[60:63], v[144:147], v[152:155], v[60:63]
	v_mfma_f32_16x16x32_bf16 v[52:55], v[136:139], v[160:163], v[52:55]
	v_mfma_f32_16x16x32_bf16 v[44:47], v[144:147], v[160:163], v[44:47]
	v_mfma_f32_16x16x32_bf16 v[36:39], v[136:139], v[168:171], v[36:39]
	v_mfma_f32_16x16x32_bf16 v[28:31], v[144:147], v[168:171], v[28:31]
	v_mfma_f32_16x16x32_bf16 v[20:23], v[136:139], v[176:179], v[20:23]
	v_mfma_f32_16x16x32_bf16 v[12:15], v[144:147], v[176:179], v[12:15]
	v_mfma_f32_16x16x32_bf16 v[56:59], v[180:183], v[148:151], 0
	v_mfma_f32_16x16x32_bf16 v[48:51], v[188:191], v[148:151], 0
	v_mfma_f32_16x16x32_bf16 v[40:43], v[180:183], v[156:159], 0
	v_mfma_f32_16x16x32_bf16 v[32:35], v[188:191], v[156:159], 0
	v_mfma_f32_16x16x32_bf16 v[24:27], v[180:183], v[164:167], 0
	v_mfma_f32_16x16x32_bf16 v[16:19], v[188:191], v[164:167], 0
	v_mfma_f32_16x16x32_bf16 v[8:11], v[180:183], v[172:175], 0
	v_mfma_f32_16x16x32_bf16 v[4:7], v[188:191], v[172:175], 0
	v_mfma_f32_16x16x32_bf16 v[56:59], v[184:187], v[152:155], v[56:59]
	v_mfma_f32_16x16x32_bf16 v[48:51], v[202:205], v[152:155], v[48:51]
	v_mfma_f32_16x16x32_bf16 v[40:43], v[184:187], v[160:163], v[40:43]
	v_mfma_f32_16x16x32_bf16 v[32:35], v[202:205], v[160:163], v[32:35]
	v_mfma_f32_16x16x32_bf16 v[24:27], v[184:187], v[168:171], v[24:27]
	v_mfma_f32_16x16x32_bf16 v[16:19], v[202:205], v[168:171], v[16:19]
	v_mfma_f32_16x16x32_bf16 v[8:11], v[184:187], v[176:179], v[8:11]
	v_mfma_f32_16x16x32_bf16 v[4:7], v[202:205], v[176:179], v[4:7]
	s_barrier
	s_setprio 0
	s_add_i32 s52, 0, 0x18000
	v_add_u32_e32 v144, s52, v1
	ds_read_b128 v[132:135], v144
	ds_read_b128 v[136:139], v144 offset:1024
	ds_read_b128 v[140:143], v144 offset:2048
	ds_read_b128 v[144:147], v144 offset:3072
	s_add_u32 s24, s24, 0x80000
	s_addc_u32 s25, s25, 0
	ds_read_b128 v[148:151], v224 offset:32768
	ds_read_b128 v[152:155], v224 offset:33792
	ds_read_b128 v[156:159], v224 offset:34816
	ds_read_b128 v[160:163], v224 offset:35840
	ds_read_b128 v[164:167], v224 offset:36864
	ds_read_b128 v[168:171], v224 offset:37888
	ds_read_b128 v[172:175], v224 offset:38912
	ds_read_b128 v[176:179], v224 offset:39936
	s_mov_b32 m0, s36
	s_nop 0
	global_load_lds_dwordx4 v196, s[24:25]
	s_mov_b32 m0, s37
	s_nop 0
	global_load_lds_dwordx4 v194, s[24:25]
	s_add_i32 s24, 0, 0x1c000
	v_add_u32_e32 v202, s24, v1
	ds_read_b128 v[180:183], v202
	ds_read_b128 v[184:187], v202 offset:1024
	ds_read_b128 v[188:191], v202 offset:2048
	ds_read_b128 v[202:205], v202 offset:3072
	s_waitcnt lgkmcnt(0)
	s_setprio 1
	s_barrier
	v_mfma_f32_16x16x32_bf16 v[128:131], v[132:135], v[148:151], v[128:131]
	v_mfma_f32_16x16x32_bf16 v[124:127], v[140:143], v[148:151], v[124:127]
	v_mfma_f32_16x16x32_bf16 v[112:115], v[132:135], v[156:159], v[112:115]
	v_mfma_f32_16x16x32_bf16 v[108:111], v[140:143], v[156:159], v[108:111]
	v_mfma_f32_16x16x32_bf16 v[100:103], v[132:135], v[164:167], v[100:103]
	v_mfma_f32_16x16x32_bf16 v[92:95], v[140:143], v[164:167], v[92:95]
	v_mfma_f32_16x16x32_bf16 v[84:87], v[132:135], v[172:175], v[84:87]
	v_mfma_f32_16x16x32_bf16 v[76:79], v[140:143], v[172:175], v[76:79]
	v_mfma_f32_16x16x32_bf16 v[128:131], v[136:139], v[152:155], v[128:131]
	v_mfma_f32_16x16x32_bf16 v[124:127], v[144:147], v[152:155], v[124:127]
	v_mfma_f32_16x16x32_bf16 v[112:115], v[136:139], v[160:163], v[112:115]
	v_mfma_f32_16x16x32_bf16 v[108:111], v[144:147], v[160:163], v[108:111]
	v_mfma_f32_16x16x32_bf16 v[100:103], v[136:139], v[168:171], v[100:103]
	v_mfma_f32_16x16x32_bf16 v[92:95], v[144:147], v[168:171], v[92:95]
	v_mfma_f32_16x16x32_bf16 v[84:87], v[136:139], v[176:179], v[84:87]
	v_mfma_f32_16x16x32_bf16 v[76:79], v[144:147], v[176:179], v[76:79]
	v_mfma_f32_16x16x32_bf16 v[120:123], v[180:183], v[148:151], v[120:123]
	v_mfma_f32_16x16x32_bf16 v[116:119], v[188:191], v[148:151], v[116:119]
	v_mfma_f32_16x16x32_bf16 v[104:107], v[180:183], v[156:159], v[104:107]
	v_mfma_f32_16x16x32_bf16 v[96:99], v[188:191], v[156:159], v[96:99]
	v_mfma_f32_16x16x32_bf16 v[88:91], v[180:183], v[164:167], v[88:91]
	v_mfma_f32_16x16x32_bf16 v[80:83], v[188:191], v[164:167], v[80:83]
	v_mfma_f32_16x16x32_bf16 v[72:75], v[180:183], v[172:175], v[72:75]
	v_mfma_f32_16x16x32_bf16 v[68:71], v[188:191], v[172:175], v[68:71]
	v_mfma_f32_16x16x32_bf16 v[120:123], v[184:187], v[152:155], v[120:123]
	v_mfma_f32_16x16x32_bf16 v[116:119], v[202:205], v[152:155], v[116:119]
	v_mfma_f32_16x16x32_bf16 v[104:107], v[184:187], v[160:163], v[104:107]
	v_mfma_f32_16x16x32_bf16 v[96:99], v[202:205], v[160:163], v[96:99]
	v_mfma_f32_16x16x32_bf16 v[88:91], v[184:187], v[168:171], v[88:91]
	v_mfma_f32_16x16x32_bf16 v[80:83], v[202:205], v[168:171], v[80:83]
	v_mfma_f32_16x16x32_bf16 v[72:75], v[184:187], v[176:179], v[72:75]
	v_mfma_f32_16x16x32_bf16 v[68:71], v[202:205], v[176:179], v[68:71]
	s_barrier
; #define PG8_STAGE(bufoff, gbase, voff) do { _Pragma("unroll") for (int _i = 0; _i < 2; ++_i) \
;         __builtin_amdgcn_global_load_lds((const unsigned*)((const char*)(gbase) + (voff)[_i]), (LAS unsigned*)(lds + (bufoff) + ldsw + _i * 8192), 16, 0, 0); } while (0)
; #define PG8_LDA(dst, b, h) do { _Pragma("unroll") for (int m = 0; m < 4; ++m) _Pragma("unroll") for (int k = 0; k < 2; ++k) dst[m][k] = *(const LAS bf16x8*)(lds + PG8_SA(b, h) + aoff + m * 2048 + k * 1024); } while (0)
; #define PG8_MMA(ai, bj, At, Bt) do { __builtin_amdgcn_s_setprio(1); _Pragma("unroll") for (int m = 0; m < 4; ++m) _Pragma("unroll") for (int n = 0; n < 2; ++n) _Pragma("unroll") for (int k = 0; k < 2; ++k) \
;         acc[ai][bj][m][n] = __builtin_amdgcn_mfma_f32_16x16x32_bf16(Bt[n][k], At[m][k], acc[ai][bj][m][n], 0, 0, 0); __builtin_amdgcn_s_setprio(0); } while (0)
; #define PG8_WAIT_V(n) asm volatile("s_waitcnt vmcnt(" #n ")" ::: "memory")
; #define PG8_WAIT_L(n) asm volatile("s_waitcnt lgkmcnt(" #n ")" ::: "memory")
; #define PG8_BAR __builtin_amdgcn_s_barrier()
; #define PG8_SCHED __builtin_amdgcn_sched_barrier(0)
; template <class Epi, class Sched>
; __device__ __forceinline__ void gemm_phase(LAS unsigned char* lds, const Gemm g, const Sched& S, const Epi& E) {
;     ...
;             PG8_LDA(At, 1, 1); PG8_STAGE(PG8_SA(1, 0), a3, voffA);
;             PG8_BAR; PG8_WAIT_L(0); PG8_MMA(1, 0, At, B0); PG8_BAR; PG8_SCHED;
;             PG8_STAGE(PG8_SB(1, 1), b3 + hstepB, voffB);
;             PG8_WAIT_V(6); PG8_BAR; PG8_MMA(1, 1, At, B1); PG8_BAR;
;         }
	s_setprio 0
	ds_read_b128 v[148:151], v224 offset:49152
	ds_read_b128 v[152:155], v224 offset:50176
	ds_read_b128 v[156:159], v224 offset:51200
	ds_read_b128 v[160:163], v224 offset:52224
	ds_read_b128 v[164:167], v224 offset:53248
	ds_read_b128 v[168:171], v224 offset:54272
	ds_read_b128 v[172:175], v224 offset:55296
	ds_read_b128 v[176:179], v224 offset:56320
	s_add_i32 s25, s52, s30
	v_lshl_add_u64 v[206:207], v[206:207], 0, s[8:9]
	s_mov_b32 m0, s25
	s_nop 0
	global_load_lds_dwordx4 v[206:207], off
	v_lshl_add_u64 v[206:207], v[208:209], 0, s[8:9]
	s_add_i32 m0, s25, 0x2000
	s_nop 0
	global_load_lds_dwordx4 v[206:207], off
	s_mov_b32 m0, s40
	v_lshl_add_u64 v[206:207], v[210:211], 0, s[8:9]
	global_load_lds_dwordx4 v[206:207], off
	v_lshl_add_u64 v[206:207], v[212:213], 0, s[8:9]
	s_mov_b32 m0, s41
	s_nop 0
	global_load_lds_dwordx4 v[206:207], off
	s_add_u32 s20, s20, 0x80080
	s_addc_u32 s21, s21, 0
	s_add_i32 s24, s24, s30
	s_mov_b32 m0, s24
	s_nop 0
	global_load_lds_dwordx4 v2, s[20:21]
	s_add_i32 m0, s24, 0x2000
	s_nop 0
	global_load_lds_dwordx4 v192, s[20:21]
	s_add_i32 s51, s51, 2
	s_add_u32 s6, s6, 0x100
	s_addc_u32 s7, s7, 0
	s_add_u32 s49, s49, 0x100
	s_addc_u32 s50, s50, 0
	s_cmp_gt_u32 s51, 29
	s_waitcnt lgkmcnt(0)
	s_waitcnt vmcnt(6)
	s_setprio 1
	s_barrier
	v_mfma_f32_16x16x32_bf16 v[64:67], v[132:135], v[148:151], v[64:67]
	v_mfma_f32_16x16x32_bf16 v[60:63], v[140:143], v[148:151], v[60:63]
	v_mfma_f32_16x16x32_bf16 v[52:55], v[132:135], v[156:159], v[52:55]
	v_mfma_f32_16x16x32_bf16 v[44:47], v[140:143], v[156:159], v[44:47]
	v_mfma_f32_16x16x32_bf16 v[36:39], v[132:135], v[164:167], v[36:39]
	v_mfma_f32_16x16x32_bf16 v[28:31], v[140:143], v[164:167], v[28:31]
	v_mfma_f32_16x16x32_bf16 v[20:23], v[132:135], v[172:175], v[20:23]
	v_mfma_f32_16x16x32_bf16 v[12:15], v[140:143], v[172:175], v[12:15]
	v_mfma_f32_16x16x32_bf16 v[64:67], v[136:139], v[152:155], v[64:67]
	v_mfma_f32_16x16x32_bf16 v[60:63], v[144:147], v[152:155], v[60:63]
	v_mfma_f32_16x16x32_bf16 v[52:55], v[136:139], v[160:163], v[52:55]
	v_mfma_f32_16x16x32_bf16 v[44:47], v[144:147], v[160:163], v[44:47]
	v_mfma_f32_16x16x32_bf16 v[36:39], v[136:139], v[168:171], v[36:39]
	v_mfma_f32_16x16x32_bf16 v[28:31], v[144:147], v[168:171], v[28:31]
	v_mfma_f32_16x16x32_bf16 v[20:23], v[136:139], v[176:179], v[20:23]
	v_mfma_f32_16x16x32_bf16 v[12:15], v[144:147], v[176:179], v[12:15]
	v_mfma_f32_16x16x32_bf16 v[56:59], v[180:183], v[148:151], v[56:59]
	v_mfma_f32_16x16x32_bf16 v[48:51], v[188:191], v[148:151], v[48:51]
	v_mfma_f32_16x16x32_bf16 v[40:43], v[180:183], v[156:159], v[40:43]
	v_mfma_f32_16x16x32_bf16 v[32:35], v[188:191], v[156:159], v[32:35]
	v_mfma_f32_16x16x32_bf16 v[24:27], v[180:183], v[164:167], v[24:27]
	v_mfma_f32_16x16x32_bf16 v[16:19], v[188:191], v[164:167], v[16:19]
	v_mfma_f32_16x16x32_bf16 v[8:11], v[180:183], v[172:175], v[8:11]
	v_mfma_f32_16x16x32_bf16 v[4:7], v[188:191], v[172:175], v[4:7]
	v_mfma_f32_16x16x32_bf16 v[56:59], v[184:187], v[152:155], v[56:59]
	v_mfma_f32_16x16x32_bf16 v[48:51], v[202:205], v[152:155], v[48:51]
	v_mfma_f32_16x16x32_bf16 v[40:43], v[184:187], v[160:163], v[40:43]
	v_mfma_f32_16x16x32_bf16 v[32:35], v[202:205], v[160:163], v[32:35]
	v_mfma_f32_16x16x32_bf16 v[24:27], v[184:187], v[168:171], v[24:27]
	v_mfma_f32_16x16x32_bf16 v[16:19], v[202:205], v[168:171], v[16:19]
	v_mfma_f32_16x16x32_bf16 v[8:11], v[184:187], v[176:179], v[8:11]
	v_mfma_f32_16x16x32_bf16 v[4:7], v[202:205], v[176:179], v[4:7]
	s_barrier
	s_setprio 0

; #define PG8_STAGE(bufoff, gbase, voff) do { _Pragma("unroll") for (int _i = 0; _i < 2; ++_i) \
;         __builtin_amdgcn_global_load_lds((const unsigned*)((const char*)(gbase) + (voff)[_i]), (LAS unsigned*)(lds + (bufoff) + ldsw + _i * 8192), 16, 0, 0); } while (0)
; #define PG8_LDA(dst, b, h) do { _Pragma("unroll") for (int m = 0; m < 4; ++m) _Pragma("unroll") for (int k = 0; k < 2; ++k) dst[m][k] = *(const LAS bf16x8*)(lds + PG8_SA(b, h) + aoff + m * 2048 + k * 1024); } while (0)
; #define PG8_LDB(dst, b, h) do { _Pragma("unroll") for (int n = 0; n < 2; ++n) _Pragma("unroll") for (int k = 0; k < 2; ++k) dst[n][k] = *(const LAS bf16x8*)(lds + PG8_SB(b, h) + boff + n * 2048 + k * 1024); } while (0)
; #define PG8_WAIT_V(n) asm volatile("s_waitcnt vmcnt(" #n ")" ::: "memory")
; #define PG8_WAIT_L(n) asm volatile("s_waitcnt lgkmcnt(" #n ")" ::: "memory")
; #define PG8_BAR __builtin_amdgcn_s_barrier()
; #define PG8_SCHED __builtin_amdgcn_sched_barrier(0)
; template <class Epi, class Sched>
; __device__ __forceinline__ void gemm_phase(LAS unsigned char* lds, const Gemm g, const Sched& S, const Epi& E) {
;     ...
;         const bool has_next = S.next(ui + 1, nxt);
;         const char* nA = has_next ? (const char*)g.A + (size_t)nxt.pm * tstepA : cA; const char* nB = has_next ? (const char*)g.Bt + (size_t)nxt.pn * tstepB : cB;
;         for (int t = 0; t < nt; t += 2) {
;             const bool last = (t == nt - 2);
;             const char* a1 = cA + (size_t)(t + 1) * kstep;
;             const char* a2 = last ? nA : cA + (size_t)(t + 2) * kstep; const char* b2 = last ? nB : cB + (size_t)(t + 2) * kstep;
;             const char* a3 = a2 + kstep; const char* b3 = b2 + kstep;
;             if (last && has_next) S.a_ready(nxt);
;             PG8_LDB(B0, 0, 0); PG8_SCHED; PG8_LDA(At, 0, 0); PG8_STAGE(PG8_SA(1, 1), a1 + hstepA, voffA);
;             PG8_WAIT_L(8); PG8_BAR; PG8_WAIT_L(0); PG8_MMA(0, 0, At, B0); PG8_BAR; PG8_SCHED;
;             PG8_LDB(B1, 0, 1); PG8_STAGE(PG8_SB(0, 0), b2, voffB);
;             PG8_BAR; PG8_WAIT_L(0); PG8_MMA(0, 1, At, B1); PG8_BAR;
;             PG8_LDA(At, 0, 1); PG8_STAGE(PG8_SA(0, 0), a2, voffA);
;             PG8_BAR; PG8_WAIT_L(0); PG8_MMA(1, 0, At, B0); PG8_BAR; PG8_SCHED;
;             PG8_STAGE(PG8_SB(0, 1), b2 + hstepB, voffB);
;             PG8_WAIT_V(6); PG8_BAR; PG8_MMA(1, 1, At, B1); PG8_BAR;
.LBB0_1093:
	v_mov_b64_e32 v[4:5], 0x900
	s_ashr_i32 s5, s4, 31
	v_cmp_lt_i64_e32 vcc, s[6:7], v[4:5]
	s_lshl_b64 s[6:7], s[4:5], 20
	s_add_u32 s6, s88, s6
	s_addc_u32 s7, s89, s7
	s_and_b64 s[14:15], vcc, exec
	s_cselect_b32 s5, s7, s19
	s_cselect_b32 s49, s6, s18
	s_ashr_i32 s1, s0, 31
	s_lshl_b64 s[14:15], s[0:1], 20
	s_add_u32 s14, s28, s14
	s_addc_u32 s15, s29, s15
	s_and_b64 s[24:25], vcc, exec
	s_cselect_b32 s1, s15, s21
	s_cselect_b32 s50, s14, s20
	s_add_u32 s18, s18, 0x80080
	s_addc_u32 s19, s19, 0
	s_add_u32 s51, s20, 0x100
	s_addc_u32 s52, s21, 0
	s_mov_b32 s53, -2
	s_setprio 0
	s_add_u32 s20, s18, 0xfff80080
	s_addc_u32 s21, s19, -1
	s_add_i32 s54, 0, 0x10000
	v_add_u32_e32 v146, s54, v1
	ds_read_b128 v[142:145], v146
	ds_read_b128 v[150:153], v146 offset:1024
	ds_read_b128 v[154:157], v146 offset:2048
	ds_read_b128 v[158:161], v146 offset:3072
	s_cmp_eq_u32 s53, 28
	s_cselect_b32 s25, s5, s21
	s_cselect_b32 s24, s49, s20
	s_cselect_b32 s21, s1, s52
	s_cselect_b32 s20, s50, s51
	ds_read_b128 v[162:165], v148
	ds_read_b128 v[166:169], v148 offset:1024
	ds_read_b128 v[170:173], v148 offset:2048
	ds_read_b128 v[174:177], v148 offset:3072
	ds_read_b128 v[178:181], v148 offset:4096
	ds_read_b128 v[182:185], v148 offset:5120
	ds_read_b128 v[186:189], v148 offset:6144
	ds_read_b128 v[190:193], v148 offset:7168
	s_add_i32 s56, 0, 0x14000
	v_add_u32_e32 v146, s56, v1
	ds_read_b128 v[194:197], v146
	ds_read_b128 v[198:201], v146 offset:1024
	ds_read_b128 v[202:205], v146 offset:2048
	ds_read_b128 v[206:209], v146 offset:3072
	s_add_i32 m0, s31, 0xc000
	s_nop 0
	global_load_lds_dwordx4 v138, s[18:19]
	s_add_i32 m0, s31, 0xe000
	s_nop 0
	global_load_lds_dwordx4 v140, s[18:19]
	s_waitcnt lgkmcnt(0)
	s_setprio 1
	s_barrier
	v_mfma_f32_16x16x32_bf16 v[128:131], v[142:145], v[162:165], 0
	v_mfma_f32_16x16x32_bf16 v[124:127], v[154:157], v[162:165], 0
	v_mfma_f32_16x16x32_bf16 v[120:123], v[142:145], v[170:173], 0
	v_mfma_f32_16x16x32_bf16 v[112:115], v[154:157], v[170:173], 0
	v_mfma_f32_16x16x32_bf16 v[104:107], v[142:145], v[178:181], 0
	v_mfma_f32_16x16x32_bf16 v[96:99], v[154:157], v[178:181], 0
	v_mfma_f32_16x16x32_bf16 v[88:91], v[142:145], v[186:189], 0
	v_mfma_f32_16x16x32_bf16 v[80:83], v[154:157], v[186:189], 0
	v_mfma_f32_16x16x32_bf16 v[128:131], v[150:153], v[166:169], v[128:131]
	v_mfma_f32_16x16x32_bf16 v[124:127], v[158:161], v[166:169], v[124:127]
	v_mfma_f32_16x16x32_bf16 v[120:123], v[150:153], v[174:177], v[120:123]
	v_mfma_f32_16x16x32_bf16 v[112:115], v[158:161], v[174:177], v[112:115]
	v_mfma_f32_16x16x32_bf16 v[104:107], v[150:153], v[182:185], v[104:107]
	v_mfma_f32_16x16x32_bf16 v[96:99], v[158:161], v[182:185], v[96:99]
	v_mfma_f32_16x16x32_bf16 v[88:91], v[150:153], v[190:193], v[88:91]
	v_mfma_f32_16x16x32_bf16 v[80:83], v[158:161], v[190:193], v[80:83]
	v_mfma_f32_16x16x32_bf16 v[116:119], v[194:197], v[162:165], 0
	v_mfma_f32_16x16x32_bf16 v[108:111], v[202:205], v[162:165], 0
	v_mfma_f32_16x16x32_bf16 v[100:103], v[194:197], v[170:173], 0
	v_mfma_f32_16x16x32_bf16 v[92:95], v[202:205], v[170:173], 0
	v_mfma_f32_16x16x32_bf16 v[84:87], v[194:197], v[178:181], 0
	v_mfma_f32_16x16x32_bf16 v[76:79], v[202:205], v[178:181], 0
	v_mfma_f32_16x16x32_bf16 v[72:75], v[194:197], v[186:189], 0
	v_mfma_f32_16x16x32_bf16 v[68:71], v[202:205], v[186:189], 0
	v_mfma_f32_16x16x32_bf16 v[116:119], v[198:201], v[166:169], v[116:119]
	v_mfma_f32_16x16x32_bf16 v[108:111], v[206:209], v[166:169], v[108:111]
	v_mfma_f32_16x16x32_bf16 v[100:103], v[198:201], v[174:177], v[100:103]
	v_mfma_f32_16x16x32_bf16 v[92:95], v[206:209], v[174:177], v[92:95]
	v_mfma_f32_16x16x32_bf16 v[84:87], v[198:201], v[182:185], v[84:87]
	v_mfma_f32_16x16x32_bf16 v[76:79], v[206:209], v[182:185], v[76:79]
	v_mfma_f32_16x16x32_bf16 v[72:75], v[198:201], v[190:193], v[72:75]
	v_mfma_f32_16x16x32_bf16 v[68:71], v[206:209], v[190:193], v[68:71]
	s_barrier
	s_setprio 0
	ds_read_b128 v[162:165], v148 offset:16384
	ds_read_b128 v[166:169], v148 offset:17408
	ds_read_b128 v[170:173], v148 offset:18432
	ds_read_b128 v[174:177], v148 offset:19456
	ds_read_b128 v[178:181], v148 offset:20480
	ds_read_b128 v[182:185], v148 offset:21504
	ds_read_b128 v[186:189], v148 offset:22528
	ds_read_b128 v[190:193], v148 offset:23552
	s_add_i32 s54, s54, s30
	v_lshl_add_u64 v[146:147], s[20:21], 0, v[2:3]
	s_mov_b32 m0, s54
	v_lshl_add_u64 v[210:211], s[20:21], 0, v[132:133]
	global_load_lds_dwordx4 v[146:147], off
	s_add_i32 m0, s54, 0x2000
	s_nop 0
	global_load_lds_dwordx4 v[210:211], off
	s_mov_b32 m0, s31
	v_lshl_add_u64 v[212:213], s[24:25], 0, v[136:137]
	global_load_lds_dwordx4 v[212:213], off
	v_lshl_add_u64 v[216:217], s[24:25], 0, v[134:135]
	s_mov_b32 m0, s35
	s_nop 0
	global_load_lds_dwordx4 v[216:217], off
	s_add_u32 s54, s20, 0x80000
	s_addc_u32 s55, s21, 0
	s_add_i32 s56, s56, s30
	s_mov_b32 m0, s56
	s_nop 0
	global_load_lds_dwordx4 v2, s[54:55]
	s_add_i32 m0, s56, 0x2000
	s_nop 0
	global_load_lds_dwordx4 v132, s[54:55]
	s_waitcnt lgkmcnt(0)
	s_waitcnt vmcnt(6)
	s_setprio 1
	s_barrier
; #define PG8_STAGE(bufoff, gbase, voff) do { _Pragma("unroll") for (int _i = 0; _i < 2; ++_i) \
;         __builtin_amdgcn_global_load_lds((const unsigned*)((const char*)(gbase) + (voff)[_i]), (LAS unsigned*)(lds + (bufoff) + ldsw + _i * 8192), 16, 0, 0); } while (0)
; #define PG8_LDA(dst, b, h) do { _Pragma("unroll") for (int m = 0; m < 4; ++m) _Pragma("unroll") for (int k = 0; k < 2; ++k) dst[m][k] = *(const LAS bf16x8*)(lds + PG8_SA(b, h) + aoff + m * 2048 + k * 1024); } while (0)
; #define PG8_LDB(dst, b, h) do { _Pragma("unroll") for (int n = 0; n < 2; ++n) _Pragma("unroll") for (int k = 0; k < 2; ++k) dst[n][k] = *(const LAS bf16x8*)(lds + PG8_SB(b, h) + boff + n * 2048 + k * 1024); } while (0)
; #define PG8_MMA(ai, bj, At, Bt) do { __builtin_amdgcn_s_setprio(1); _Pragma("unroll") for (int m = 0; m < 4; ++m) _Pragma("unroll") for (int n = 0; n < 2; ++n) _Pragma("unroll") for (int k = 0; k < 2; ++k) \
;         acc[ai][bj][m][n] = __builtin_amdgcn_mfma_f32_16x16x32_bf16(Bt[n][k], At[m][k], acc[ai][bj][m][n], 0, 0, 0); __builtin_amdgcn_s_setprio(0); } while (0)
; #define PG8_WAIT_V(n) asm volatile("s_waitcnt vmcnt(" #n ")" ::: "memory")
; #define PG8_WAIT_L(n) asm volatile("s_waitcnt lgkmcnt(" #n ")" ::: "memory")
; #define PG8_BAR __builtin_amdgcn_s_barrier()
; #define PG8_SCHED __builtin_amdgcn_sched_barrier(0)
; template <class Epi, class Sched>
; __device__ __forceinline__ void gemm_phase(LAS unsigned char* lds, const Gemm g, const Sched& S, const Epi& E) {
;     ...
;             PG8_WAIT_V(6); PG8_BAR; PG8_MMA(1, 1, At, B1); PG8_BAR;
;             PG8_LDB(B0, 1, 0); PG8_SCHED; PG8_LDA(At, 1, 0); PG8_STAGE(PG8_SA(0, 1), a2 + hstepA, voffA);
;             PG8_WAIT_L(8); PG8_BAR; PG8_WAIT_L(0); PG8_MMA(0, 0, At, B0); PG8_BAR; PG8_SCHED;
;             PG8_LDB(B1, 1, 1); PG8_STAGE(PG8_SB(1, 0), b3, voffB);
;             PG8_BAR; PG8_WAIT_L(0); PG8_MMA(0, 1, At, B1); PG8_BAR;
;             PG8_LDA(At, 1, 1); PG8_STAGE(PG8_SA(1, 0), a3, voffA);
;             PG8_BAR; PG8_WAIT_L(0); PG8_MMA(1, 0, At, B0); PG8_BAR; PG8_SCHED;
	v_mfma_f32_16x16x32_bf16 v[64:67], v[142:145], v[162:165], 0
	v_mfma_f32_16x16x32_bf16 v[60:63], v[154:157], v[162:165], 0
	v_mfma_f32_16x16x32_bf16 v[56:59], v[142:145], v[170:173], 0
	v_mfma_f32_16x16x32_bf16 v[48:51], v[154:157], v[170:173], 0
	v_mfma_f32_16x16x32_bf16 v[40:43], v[142:145], v[178:181], 0
	v_mfma_f32_16x16x32_bf16 v[32:35], v[154:157], v[178:181], 0
	v_mfma_f32_16x16x32_bf16 v[24:27], v[142:145], v[186:189], 0
	v_mfma_f32_16x16x32_bf16 v[16:19], v[154:157], v[186:189], 0
	v_mfma_f32_16x16x32_bf16 v[64:67], v[150:153], v[166:169], v[64:67]
	v_mfma_f32_16x16x32_bf16 v[60:63], v[158:161], v[166:169], v[60:63]
	v_mfma_f32_16x16x32_bf16 v[56:59], v[150:153], v[174:177], v[56:59]
	v_mfma_f32_16x16x32_bf16 v[48:51], v[158:161], v[174:177], v[48:51]
	v_mfma_f32_16x16x32_bf16 v[40:43], v[150:153], v[182:185], v[40:43]
	v_mfma_f32_16x16x32_bf16 v[32:35], v[158:161], v[182:185], v[32:35]
	v_mfma_f32_16x16x32_bf16 v[24:27], v[150:153], v[190:193], v[24:27]
	v_mfma_f32_16x16x32_bf16 v[16:19], v[158:161], v[190:193], v[16:19]
	v_mfma_f32_16x16x32_bf16 v[52:55], v[194:197], v[162:165], 0
	v_mfma_f32_16x16x32_bf16 v[44:47], v[202:205], v[162:165], 0
	v_mfma_f32_16x16x32_bf16 v[36:39], v[194:197], v[170:173], 0
	v_mfma_f32_16x16x32_bf16 v[28:31], v[202:205], v[170:173], 0
	v_mfma_f32_16x16x32_bf16 v[20:23], v[194:197], v[178:181], 0
	v_mfma_f32_16x16x32_bf16 v[12:15], v[202:205], v[178:181], 0
	v_mfma_f32_16x16x32_bf16 v[8:11], v[194:197], v[186:189], 0
	v_mfma_f32_16x16x32_bf16 v[4:7], v[202:205], v[186:189], 0
	v_mfma_f32_16x16x32_bf16 v[52:55], v[198:201], v[166:169], v[52:55]
	v_mfma_f32_16x16x32_bf16 v[44:47], v[206:209], v[166:169], v[44:47]
	v_mfma_f32_16x16x32_bf16 v[36:39], v[198:201], v[174:177], v[36:39]
	v_mfma_f32_16x16x32_bf16 v[28:31], v[206:209], v[174:177], v[28:31]
	v_mfma_f32_16x16x32_bf16 v[20:23], v[198:201], v[182:185], v[20:23]
	v_mfma_f32_16x16x32_bf16 v[12:15], v[206:209], v[182:185], v[12:15]
	v_mfma_f32_16x16x32_bf16 v[8:11], v[198:201], v[190:193], v[8:11]
	v_mfma_f32_16x16x32_bf16 v[4:7], v[206:209], v[190:193], v[4:7]
	s_barrier
	s_setprio 0
	s_add_i32 s54, 0, 0x18000
	v_add_u32_e32 v149, s54, v1
	ds_read_b128 v[142:145], v149
	ds_read_b128 v[150:153], v149 offset:1024
	ds_read_b128 v[154:157], v149 offset:2048
	ds_read_b128 v[158:161], v149 offset:3072
	s_add_u32 s24, s24, 0x80000
	s_addc_u32 s25, s25, 0
	ds_read_b128 v[162:165], v148 offset:32768
	ds_read_b128 v[166:169], v148 offset:33792
	ds_read_b128 v[170:173], v148 offset:34816
	ds_read_b128 v[174:177], v148 offset:35840
	ds_read_b128 v[178:181], v148 offset:36864
	ds_read_b128 v[182:185], v148 offset:37888
	ds_read_b128 v[186:189], v148 offset:38912
	ds_read_b128 v[190:193], v148 offset:39936
	s_mov_b32 m0, s36
	s_nop 0
	global_load_lds_dwordx4 v136, s[24:25]
	s_mov_b32 m0, s37
	s_nop 0
	global_load_lds_dwordx4 v134, s[24:25]
	s_add_i32 s24, 0, 0x1c000
	v_add_u32_e32 v149, s24, v1
	ds_read_b128 v[194:197], v149
	ds_read_b128 v[198:201], v149 offset:1024
	ds_read_b128 v[202:205], v149 offset:2048
	ds_read_b128 v[206:209], v149 offset:3072
	s_waitcnt lgkmcnt(0)
	s_setprio 1
	s_barrier
	v_mfma_f32_16x16x32_bf16 v[128:131], v[142:145], v[162:165], v[128:131]
	v_mfma_f32_16x16x32_bf16 v[124:127], v[154:157], v[162:165], v[124:127]
	v_mfma_f32_16x16x32_bf16 v[120:123], v[142:145], v[170:173], v[120:123]
	v_mfma_f32_16x16x32_bf16 v[112:115], v[154:157], v[170:173], v[112:115]
	v_mfma_f32_16x16x32_bf16 v[104:107], v[142:145], v[178:181], v[104:107]
	v_mfma_f32_16x16x32_bf16 v[96:99], v[154:157], v[178:181], v[96:99]
	v_mfma_f32_16x16x32_bf16 v[88:91], v[142:145], v[186:189], v[88:91]
	v_mfma_f32_16x16x32_bf16 v[80:83], v[154:157], v[186:189], v[80:83]
	v_mfma_f32_16x16x32_bf16 v[128:131], v[150:153], v[166:169], v[128:131]
	v_mfma_f32_16x16x32_bf16 v[124:127], v[158:161], v[166:169], v[124:127]
	v_mfma_f32_16x16x32_bf16 v[120:123], v[150:153], v[174:177], v[120:123]
	v_mfma_f32_16x16x32_bf16 v[112:115], v[158:161], v[174:177], v[112:115]
	v_mfma_f32_16x16x32_bf16 v[104:107], v[150:153], v[182:185], v[104:107]
	v_mfma_f32_16x16x32_bf16 v[96:99], v[158:161], v[182:185], v[96:99]
	v_mfma_f32_16x16x32_bf16 v[88:91], v[150:153], v[190:193], v[88:91]
	v_mfma_f32_16x16x32_bf16 v[80:83], v[158:161], v[190:193], v[80:83]
	v_mfma_f32_16x16x32_bf16 v[116:119], v[194:197], v[162:165], v[116:119]
	v_mfma_f32_16x16x32_bf16 v[108:111], v[202:205], v[162:165], v[108:111]
	v_mfma_f32_16x16x32_bf16 v[100:103], v[194:197], v[170:173], v[100:103]
	v_mfma_f32_16x16x32_bf16 v[92:95], v[202:205], v[170:173], v[92:95]
	v_mfma_f32_16x16x32_bf16 v[84:87], v[194:197], v[178:181], v[84:87]
	v_mfma_f32_16x16x32_bf16 v[76:79], v[202:205], v[178:181], v[76:79]
	v_mfma_f32_16x16x32_bf16 v[72:75], v[194:197], v[186:189], v[72:75]
	v_mfma_f32_16x16x32_bf16 v[68:71], v[202:205], v[186:189], v[68:71]
	v_mfma_f32_16x16x32_bf16 v[116:119], v[198:201], v[166:169], v[116:119]
	v_mfma_f32_16x16x32_bf16 v[108:111], v[206:209], v[166:169], v[108:111]
	v_mfma_f32_16x16x32_bf16 v[100:103], v[198:201], v[174:177], v[100:103]
	v_mfma_f32_16x16x32_bf16 v[92:95], v[206:209], v[174:177], v[92:95]
	v_mfma_f32_16x16x32_bf16 v[84:87], v[198:201], v[182:185], v[84:87]
	v_mfma_f32_16x16x32_bf16 v[76:79], v[206:209], v[182:185], v[76:79]
	v_mfma_f32_16x16x32_bf16 v[72:75], v[198:201], v[190:193], v[72:75]
	v_mfma_f32_16x16x32_bf16 v[68:71], v[206:209], v[190:193], v[68:71]
	s_barrier
; #define PG8_STAGE(bufoff, gbase, voff) do { _Pragma("unroll") for (int _i = 0; _i < 2; ++_i) \
;         __builtin_amdgcn_global_load_lds((const unsigned*)((const char*)(gbase) + (voff)[_i]), (LAS unsigned*)(lds + (bufoff) + ldsw + _i * 8192), 16, 0, 0); } while (0)
; #define PG8_LDA(dst, b, h) do { _Pragma("unroll") for (int m = 0; m < 4; ++m) _Pragma("unroll") for (int k = 0; k < 2; ++k) dst[m][k] = *(const LAS bf16x8*)(lds + PG8_SA(b, h) + aoff + m * 2048 + k * 1024); } while (0)
; #define PG8_MMA(ai, bj, At, Bt) do { __builtin_amdgcn_s_setprio(1); _Pragma("unroll") for (int m = 0; m < 4; ++m) _Pragma("unroll") for (int n = 0; n < 2; ++n) _Pragma("unroll") for (int k = 0; k < 2; ++k) \
;         acc[ai][bj][m][n] = __builtin_amdgcn_mfma_f32_16x16x32_bf16(Bt[n][k], At[m][k], acc[ai][bj][m][n], 0, 0, 0); __builtin_amdgcn_s_setprio(0); } while (0)
; #define PG8_WAIT_V(n) asm volatile("s_waitcnt vmcnt(" #n ")" ::: "memory")
; #define PG8_WAIT_L(n) asm volatile("s_waitcnt lgkmcnt(" #n ")" ::: "memory")
; #define PG8_BAR __builtin_amdgcn_s_barrier()
; #define PG8_SCHED __builtin_amdgcn_sched_barrier(0)
; template <class Epi, class Sched>
; __device__ __forceinline__ void gemm_phase(LAS unsigned char* lds, const Gemm g, const Sched& S, const Epi& E) {
;     ...
;             PG8_LDA(At, 1, 1); PG8_STAGE(PG8_SA(1, 0), a3, voffA);
;             PG8_BAR; PG8_WAIT_L(0); PG8_MMA(1, 0, At, B0); PG8_BAR; PG8_SCHED;
;             PG8_STAGE(PG8_SB(1, 1), b3 + hstepB, voffB);
;             PG8_WAIT_V(6); PG8_BAR; PG8_MMA(1, 1, At, B1); PG8_BAR;
;         }
	s_setprio 0
	ds_read_b128 v[162:165], v148 offset:49152
	ds_read_b128 v[166:169], v148 offset:50176
	ds_read_b128 v[170:173], v148 offset:51200
	ds_read_b128 v[174:177], v148 offset:52224
	ds_read_b128 v[178:181], v148 offset:53248
	ds_read_b128 v[182:185], v148 offset:54272
	ds_read_b128 v[186:189], v148 offset:55296
	ds_read_b128 v[190:193], v148 offset:56320
	s_add_i32 s25, s54, s30
	v_lshl_add_u64 v[146:147], v[146:147], 0, s[8:9]
	s_mov_b32 m0, s25
	s_nop 0
	global_load_lds_dwordx4 v[146:147], off
	v_lshl_add_u64 v[146:147], v[210:211], 0, s[8:9]
	s_add_i32 m0, s25, 0x2000
	s_nop 0
	global_load_lds_dwordx4 v[146:147], off
	s_mov_b32 m0, s42
	v_lshl_add_u64 v[146:147], v[212:213], 0, s[8:9]
	global_load_lds_dwordx4 v[146:147], off
	v_lshl_add_u64 v[146:147], v[216:217], 0, s[8:9]
	s_mov_b32 m0, s43
	s_nop 0
	global_load_lds_dwordx4 v[146:147], off
	s_add_u32 s20, s20, 0x80080
	s_addc_u32 s21, s21, 0
	s_add_i32 s24, s24, s30
	s_mov_b32 m0, s24
	s_nop 0
	global_load_lds_dwordx4 v2, s[20:21]
	s_add_i32 m0, s24, 0x2000
	s_nop 0
	global_load_lds_dwordx4 v132, s[20:21]
	s_add_i32 s53, s53, 2
	s_add_u32 s18, s18, 0x100
	s_addc_u32 s19, s19, 0
	s_add_u32 s51, s51, 0x100
	s_addc_u32 s52, s52, 0
	s_cmp_gt_u32 s53, 29
	s_waitcnt lgkmcnt(0)
	s_waitcnt vmcnt(6)
	s_setprio 1
	s_barrier
	v_mfma_f32_16x16x32_bf16 v[64:67], v[142:145], v[162:165], v[64:67]
	v_mfma_f32_16x16x32_bf16 v[60:63], v[154:157], v[162:165], v[60:63]
	v_mfma_f32_16x16x32_bf16 v[56:59], v[142:145], v[170:173], v[56:59]
	v_mfma_f32_16x16x32_bf16 v[48:51], v[154:157], v[170:173], v[48:51]
	v_mfma_f32_16x16x32_bf16 v[40:43], v[142:145], v[178:181], v[40:43]
	v_mfma_f32_16x16x32_bf16 v[32:35], v[154:157], v[178:181], v[32:35]
	v_mfma_f32_16x16x32_bf16 v[24:27], v[142:145], v[186:189], v[24:27]
	v_mfma_f32_16x16x32_bf16 v[16:19], v[154:157], v[186:189], v[16:19]
	v_mfma_f32_16x16x32_bf16 v[64:67], v[150:153], v[166:169], v[64:67]
	v_mfma_f32_16x16x32_bf16 v[60:63], v[158:161], v[166:169], v[60:63]
	v_mfma_f32_16x16x32_bf16 v[56:59], v[150:153], v[174:177], v[56:59]
	v_mfma_f32_16x16x32_bf16 v[48:51], v[158:161], v[174:177], v[48:51]
	v_mfma_f32_16x16x32_bf16 v[40:43], v[150:153], v[182:185], v[40:43]
	v_mfma_f32_16x16x32_bf16 v[32:35], v[158:161], v[182:185], v[32:35]
	v_mfma_f32_16x16x32_bf16 v[24:27], v[150:153], v[190:193], v[24:27]
	v_mfma_f32_16x16x32_bf16 v[16:19], v[158:161], v[190:193], v[16:19]
	v_mfma_f32_16x16x32_bf16 v[52:55], v[194:197], v[162:165], v[52:55]
	v_mfma_f32_16x16x32_bf16 v[44:47], v[202:205], v[162:165], v[44:47]
	v_mfma_f32_16x16x32_bf16 v[36:39], v[194:197], v[170:173], v[36:39]
	v_mfma_f32_16x16x32_bf16 v[28:31], v[202:205], v[170:173], v[28:31]
	v_mfma_f32_16x16x32_bf16 v[20:23], v[194:197], v[178:181], v[20:23]
	v_mfma_f32_16x16x32_bf16 v[12:15], v[202:205], v[178:181], v[12:15]
	v_mfma_f32_16x16x32_bf16 v[8:11], v[194:197], v[186:189], v[8:11]
	v_mfma_f32_16x16x32_bf16 v[4:7], v[202:205], v[186:189], v[4:7]
	v_mfma_f32_16x16x32_bf16 v[52:55], v[198:201], v[166:169], v[52:55]
	v_mfma_f32_16x16x32_bf16 v[44:47], v[206:209], v[166:169], v[44:47]
	v_mfma_f32_16x16x32_bf16 v[36:39], v[198:201], v[174:177], v[36:39]
	v_mfma_f32_16x16x32_bf16 v[28:31], v[206:209], v[174:177], v[28:31]
	v_mfma_f32_16x16x32_bf16 v[20:23], v[198:201], v[182:185], v[20:23]
	v_mfma_f32_16x16x32_bf16 v[12:15], v[206:209], v[182:185], v[12:15]
	v_mfma_f32_16x16x32_bf16 v[8:11], v[198:201], v[190:193], v[8:11]
	v_mfma_f32_16x16x32_bf16 v[4:7], v[206:209], v[190:193], v[4:7]
	s_barrier
	s_setprio 0

; #define PG8_STAGE(bufoff, gbase, voff) do { _Pragma("unroll") for (int _i = 0; _i < 2; ++_i) \
;         __builtin_amdgcn_global_load_lds((const unsigned*)((const char*)(gbase) + (voff)[_i]), (LAS unsigned*)(lds + (bufoff) + ldsw + _i * 8192), 16, 0, 0); } while (0)
; #define PG8_LDA(dst, b, h) do { _Pragma("unroll") for (int m = 0; m < 4; ++m) _Pragma("unroll") for (int k = 0; k < 2; ++k) dst[m][k] = *(const LAS bf16x8*)(lds + PG8_SA(b, h) + aoff + m * 2048 + k * 1024); } while (0)
; #define PG8_LDB(dst, b, h) do { _Pragma("unroll") for (int n = 0; n < 2; ++n) _Pragma("unroll") for (int k = 0; k < 2; ++k) dst[n][k] = *(const LAS bf16x8*)(lds + PG8_SB(b, h) + boff + n * 2048 + k * 1024); } while (0)
; #define PG8_WAIT_V(n) asm volatile("s_waitcnt vmcnt(" #n ")" ::: "memory")
; #define PG8_WAIT_L(n) asm volatile("s_waitcnt lgkmcnt(" #n ")" ::: "memory")
; #define PG8_BAR __builtin_amdgcn_s_barrier()
; #define PG8_SCHED __builtin_amdgcn_sched_barrier(0)
; template <class Epi, class Sched>
; __device__ __forceinline__ void gemm_phase(LAS unsigned char* lds, const Gemm g, const Sched& S, const Epi& E) {
;     ...
;         const bool has_next = S.next(ui + 1, nxt);
;         const char* nA = has_next ? (const char*)g.A + (size_t)nxt.pm * tstepA : cA; const char* nB = has_next ? (const char*)g.Bt + (size_t)nxt.pn * tstepB : cB;
;         for (int t = 0; t < nt; t += 2) {
;             const bool last = (t == nt - 2);
;             const char* a1 = cA + (size_t)(t + 1) * kstep;
;             const char* a2 = last ? nA : cA + (size_t)(t + 2) * kstep; const char* b2 = last ? nB : cB + (size_t)(t + 2) * kstep;
;             const char* a3 = a2 + kstep; const char* b3 = b2 + kstep;
;             if (last && has_next) S.a_ready(nxt);
;             PG8_LDB(B0, 0, 0); PG8_SCHED; PG8_LDA(At, 0, 0); PG8_STAGE(PG8_SA(1, 1), a1 + hstepA, voffA);
;             PG8_WAIT_L(8); PG8_BAR; PG8_WAIT_L(0); PG8_MMA(0, 0, At, B0); PG8_BAR; PG8_SCHED;
;             PG8_LDB(B1, 0, 1); PG8_STAGE(PG8_SB(0, 0), b2, voffB);
;             PG8_BAR; PG8_WAIT_L(0); PG8_MMA(0, 1, At, B1); PG8_BAR;
;             PG8_LDA(At, 0, 1); PG8_STAGE(PG8_SA(0, 0), a2, voffA);
;             PG8_BAR; PG8_WAIT_L(0); PG8_MMA(1, 0, At, B0); PG8_BAR; PG8_SCHED;
;             PG8_STAGE(PG8_SB(0, 1), b2 + hstepB, voffB);
;             PG8_WAIT_V(6); PG8_BAR; PG8_MMA(1, 1, At, B1); PG8_BAR;
.LBB0_1395:
	v_mov_b64_e32 v[4:5], 0x400
	s_ashr_i32 s15, s14, 31
	v_cmp_lt_i64_e32 vcc, s[4:5], v[4:5]
	s_lshl_b64 s[4:5], s[14:15], 20
	v_readlane_b32 s48, v252, 0
	v_readlane_b32 s49, v252, 1
	s_add_u32 s4, s48, s4
	s_addc_u32 s5, s49, s5
	s_and_b64 s[18:19], vcc, exec
	s_cselect_b32 s15, s5, s7
	s_cselect_b32 s47, s4, s6
	s_ashr_i32 s1, s0, 31
	s_lshl_b64 s[18:19], s[0:1], 20
	s_add_u32 s18, s28, s18
	s_addc_u32 s19, s29, s19
	s_and_b64 s[24:25], vcc, exec
	s_cselect_b32 s1, s19, s21
	s_cselect_b32 s48, s18, s20
	s_add_u32 s6, s6, 0x80080
	s_addc_u32 s7, s7, 0
	v_readlane_b32 s50, v252, 2
	v_readlane_b32 s51, v252, 3
	s_add_u32 s49, s20, 0x100
	s_addc_u32 s50, s21, 0
	s_mov_b32 s51, -2
	s_waitcnt vmcnt(0)
	s_setprio 0
	s_add_u32 s20, s6, 0xfff80080
	s_addc_u32 s21, s7, -1
	s_add_i32 s52, 0, 0x10000
	v_add_u32_e32 v144, s52, v1
	ds_read_b128 v[132:135], v144
	ds_read_b128 v[136:139], v144 offset:1024
	ds_read_b128 v[140:143], v144 offset:2048
	ds_read_b128 v[144:147], v144 offset:3072
	s_cmp_eq_u32 s51, 28
	s_cselect_b32 s25, s15, s21
	s_cselect_b32 s24, s47, s20
	s_cselect_b32 s21, s1, s50
	s_cselect_b32 s20, s48, s49
	ds_read_b128 v[148:151], v224
	ds_read_b128 v[152:155], v224 offset:1024
	ds_read_b128 v[156:159], v224 offset:2048
	ds_read_b128 v[160:163], v224 offset:3072
	ds_read_b128 v[164:167], v224 offset:4096
	ds_read_b128 v[168:171], v224 offset:5120
	ds_read_b128 v[172:175], v224 offset:6144
	ds_read_b128 v[176:179], v224 offset:7168
	s_add_i32 s54, 0, 0x14000
	v_add_u32_e32 v202, s54, v1
	ds_read_b128 v[180:183], v202
	ds_read_b128 v[184:187], v202 offset:1024
	ds_read_b128 v[188:191], v202 offset:2048
	ds_read_b128 v[202:205], v202 offset:3072
	s_add_i32 m0, s31, 0xc000
	s_nop 0
	global_load_lds_dwordx4 v198, s[6:7]
	s_add_i32 m0, s31, 0xe000
	s_nop 0
	global_load_lds_dwordx4 v200, s[6:7]
	s_waitcnt lgkmcnt(0)
	s_setprio 1
	s_barrier
	v_mfma_f32_16x16x32_bf16 v[128:131], v[132:135], v[148:151], 0
	v_mfma_f32_16x16x32_bf16 v[124:127], v[140:143], v[148:151], 0
	v_mfma_f32_16x16x32_bf16 v[112:115], v[132:135], v[156:159], 0
	v_mfma_f32_16x16x32_bf16 v[108:111], v[140:143], v[156:159], 0
	v_mfma_f32_16x16x32_bf16 v[100:103], v[132:135], v[164:167], 0
	v_mfma_f32_16x16x32_bf16 v[92:95], v[140:143], v[164:167], 0
	v_mfma_f32_16x16x32_bf16 v[84:87], v[132:135], v[172:175], 0
	v_mfma_f32_16x16x32_bf16 v[76:79], v[140:143], v[172:175], 0
	v_mfma_f32_16x16x32_bf16 v[128:131], v[136:139], v[152:155], v[128:131]
	v_mfma_f32_16x16x32_bf16 v[124:127], v[144:147], v[152:155], v[124:127]
	v_mfma_f32_16x16x32_bf16 v[112:115], v[136:139], v[160:163], v[112:115]
	v_mfma_f32_16x16x32_bf16 v[108:111], v[144:147], v[160:163], v[108:111]
	v_mfma_f32_16x16x32_bf16 v[100:103], v[136:139], v[168:171], v[100:103]
	v_mfma_f32_16x16x32_bf16 v[92:95], v[144:147], v[168:171], v[92:95]
	v_mfma_f32_16x16x32_bf16 v[84:87], v[136:139], v[176:179], v[84:87]
	v_mfma_f32_16x16x32_bf16 v[76:79], v[144:147], v[176:179], v[76:79]
	v_mfma_f32_16x16x32_bf16 v[120:123], v[180:183], v[148:151], 0
	v_mfma_f32_16x16x32_bf16 v[116:119], v[188:191], v[148:151], 0
	v_mfma_f32_16x16x32_bf16 v[104:107], v[180:183], v[156:159], 0
	v_mfma_f32_16x16x32_bf16 v[96:99], v[188:191], v[156:159], 0
	v_mfma_f32_16x16x32_bf16 v[88:91], v[180:183], v[164:167], 0
	v_mfma_f32_16x16x32_bf16 v[80:83], v[188:191], v[164:167], 0
	v_mfma_f32_16x16x32_bf16 v[72:75], v[180:183], v[172:175], 0
	v_mfma_f32_16x16x32_bf16 v[68:71], v[188:191], v[172:175], 0
	v_mfma_f32_16x16x32_bf16 v[120:123], v[184:187], v[152:155], v[120:123]
	v_mfma_f32_16x16x32_bf16 v[116:119], v[202:205], v[152:155], v[116:119]
	v_mfma_f32_16x16x32_bf16 v[104:107], v[184:187], v[160:163], v[104:107]
	v_mfma_f32_16x16x32_bf16 v[96:99], v[202:205], v[160:163], v[96:99]
	v_mfma_f32_16x16x32_bf16 v[88:91], v[184:187], v[168:171], v[88:91]
	v_mfma_f32_16x16x32_bf16 v[80:83], v[202:205], v[168:171], v[80:83]
	v_mfma_f32_16x16x32_bf16 v[72:75], v[184:187], v[176:179], v[72:75]
	v_mfma_f32_16x16x32_bf16 v[68:71], v[202:205], v[176:179], v[68:71]
	s_barrier
	s_setprio 0
	ds_read_b128 v[148:151], v224 offset:16384
	ds_read_b128 v[152:155], v224 offset:17408
	ds_read_b128 v[156:159], v224 offset:18432
	ds_read_b128 v[160:163], v224 offset:19456
	ds_read_b128 v[164:167], v224 offset:20480
	ds_read_b128 v[168:171], v224 offset:21504
	ds_read_b128 v[172:175], v224 offset:22528
	ds_read_b128 v[176:179], v224 offset:23552
	s_add_i32 s52, s52, s30
	v_lshl_add_u64 v[206:207], s[20:21], 0, v[2:3]
	s_mov_b32 m0, s52
	s_nop 0
	global_load_lds_dwordx4 v[206:207], off
	v_lshl_add_u64 v[208:209], s[20:21], 0, v[192:193]
	s_add_i32 m0, s52, 0x2000
	s_nop 0
	global_load_lds_dwordx4 v[208:209], off
	s_mov_b32 m0, s31
	v_lshl_add_u64 v[210:211], s[24:25], 0, v[196:197]
	global_load_lds_dwordx4 v[210:211], off
	v_lshl_add_u64 v[212:213], s[24:25], 0, v[194:195]
	s_mov_b32 m0, s35
	s_nop 0
	global_load_lds_dwordx4 v[212:213], off
	s_add_u32 s52, s20, 0x80000
	s_addc_u32 s53, s21, 0
	s_add_i32 s54, s54, s30
	s_mov_b32 m0, s54
	s_nop 0
	global_load_lds_dwordx4 v2, s[52:53]
	s_add_i32 m0, s54, 0x2000
	s_nop 0
	global_load_lds_dwordx4 v192, s[52:53]
	s_waitcnt lgkmcnt(0)
	s_waitcnt vmcnt(6)
	s_setprio 1
	s_barrier
; #define PG8_STAGE(bufoff, gbase, voff) do { _Pragma("unroll") for (int _i = 0; _i < 2; ++_i) \
;         __builtin_amdgcn_global_load_lds((const unsigned*)((const char*)(gbase) + (voff)[_i]), (LAS unsigned*)(lds + (bufoff) + ldsw + _i * 8192), 16, 0, 0); } while (0)
; #define PG8_LDA(dst, b, h) do { _Pragma("unroll") for (int m = 0; m < 4; ++m) _Pragma("unroll") for (int k = 0; k < 2; ++k) dst[m][k] = *(const LAS bf16x8*)(lds + PG8_SA(b, h) + aoff + m * 2048 + k * 1024); } while (0)
; #define PG8_LDB(dst, b, h) do { _Pragma("unroll") for (int n = 0; n < 2; ++n) _Pragma("unroll") for (int k = 0; k < 2; ++k) dst[n][k] = *(const LAS bf16x8*)(lds + PG8_SB(b, h) + boff + n * 2048 + k * 1024); } while (0)
; #define PG8_MMA(ai, bj, At, Bt) do { __builtin_amdgcn_s_setprio(1); _Pragma("unroll") for (int m = 0; m < 4; ++m) _Pragma("unroll") for (int n = 0; n < 2; ++n) _Pragma("unroll") for (int k = 0; k < 2; ++k) \
;         acc[ai][bj][m][n] = __builtin_amdgcn_mfma_f32_16x16x32_bf16(Bt[n][k], At[m][k], acc[ai][bj][m][n], 0, 0, 0); __builtin_amdgcn_s_setprio(0); } while (0)
; #define PG8_WAIT_V(n) asm volatile("s_waitcnt vmcnt(" #n ")" ::: "memory")
; #define PG8_WAIT_L(n) asm volatile("s_waitcnt lgkmcnt(" #n ")" ::: "memory")
; #define PG8_BAR __builtin_amdgcn_s_barrier()
; #define PG8_SCHED __builtin_amdgcn_sched_barrier(0)
; template <class Epi, class Sched>
; __device__ __forceinline__ void gemm_phase(LAS unsigned char* lds, const Gemm g, const Sched& S, const Epi& E) {
;     ...
;             PG8_WAIT_V(6); PG8_BAR; PG8_MMA(1, 1, At, B1); PG8_BAR;
;             PG8_LDB(B0, 1, 0); PG8_SCHED; PG8_LDA(At, 1, 0); PG8_STAGE(PG8_SA(0, 1), a2 + hstepA, voffA);
;             PG8_WAIT_L(8); PG8_BAR; PG8_WAIT_L(0); PG8_MMA(0, 0, At, B0); PG8_BAR; PG8_SCHED;
;             PG8_LDB(B1, 1, 1); PG8_STAGE(PG8_SB(1, 0), b3, voffB);
;             PG8_BAR; PG8_WAIT_L(0); PG8_MMA(0, 1, At, B1); PG8_BAR;
;             PG8_LDA(At, 1, 1); PG8_STAGE(PG8_SA(1, 0), a3, voffA);
;             PG8_BAR; PG8_WAIT_L(0); PG8_MMA(1, 0, At, B0); PG8_BAR; PG8_SCHED;
	v_mfma_f32_16x16x32_bf16 v[64:67], v[132:135], v[148:151], 0
	v_mfma_f32_16x16x32_bf16 v[60:63], v[140:143], v[148:151], 0
	v_mfma_f32_16x16x32_bf16 v[52:55], v[132:135], v[156:159], 0
	v_mfma_f32_16x16x32_bf16 v[44:47], v[140:143], v[156:159], 0
	v_mfma_f32_16x16x32_bf16 v[36:39], v[132:135], v[164:167], 0
	v_mfma_f32_16x16x32_bf16 v[28:31], v[140:143], v[164:167], 0
	v_mfma_f32_16x16x32_bf16 v[20:23], v[132:135], v[172:175], 0
	v_mfma_f32_16x16x32_bf16 v[12:15], v[140:143], v[172:175], 0
	v_mfma_f32_16x16x32_bf16 v[64:67], v[136:139], v[152:155], v[64:67]
	v_mfma_f32_16x16x32_bf16 v[60:63], v[144:147], v[152:155], v[60:63]
	v_mfma_f32_16x16x32_bf16 v[52:55], v[136:139], v[160:163], v[52:55]
	v_mfma_f32_16x16x32_bf16 v[44:47], v[144:147], v[160:163], v[44:47]
	v_mfma_f32_16x16x32_bf16 v[36:39], v[136:139], v[168:171], v[36:39]
	v_mfma_f32_16x16x32_bf16 v[28:31], v[144:147], v[168:171], v[28:31]
	v_mfma_f32_16x16x32_bf16 v[20:23], v[136:139], v[176:179], v[20:23]
	v_mfma_f32_16x16x32_bf16 v[12:15], v[144:147], v[176:179], v[12:15]
	v_mfma_f32_16x16x32_bf16 v[56:59], v[180:183], v[148:151], 0
	v_mfma_f32_16x16x32_bf16 v[48:51], v[188:191], v[148:151], 0
	v_mfma_f32_16x16x32_bf16 v[40:43], v[180:183], v[156:159], 0
	v_mfma_f32_16x16x32_bf16 v[32:35], v[188:191], v[156:159], 0
	v_mfma_f32_16x16x32_bf16 v[24:27], v[180:183], v[164:167], 0
	v_mfma_f32_16x16x32_bf16 v[16:19], v[188:191], v[164:167], 0
	v_mfma_f32_16x16x32_bf16 v[8:11], v[180:183], v[172:175], 0
	v_mfma_f32_16x16x32_bf16 v[4:7], v[188:191], v[172:175], 0
	v_mfma_f32_16x16x32_bf16 v[56:59], v[184:187], v[152:155], v[56:59]
	v_mfma_f32_16x16x32_bf16 v[48:51], v[202:205], v[152:155], v[48:51]
	v_mfma_f32_16x16x32_bf16 v[40:43], v[184:187], v[160:163], v[40:43]
	v_mfma_f32_16x16x32_bf16 v[32:35], v[202:205], v[160:163], v[32:35]
	v_mfma_f32_16x16x32_bf16 v[24:27], v[184:187], v[168:171], v[24:27]
	v_mfma_f32_16x16x32_bf16 v[16:19], v[202:205], v[168:171], v[16:19]
	v_mfma_f32_16x16x32_bf16 v[8:11], v[184:187], v[176:179], v[8:11]
	v_mfma_f32_16x16x32_bf16 v[4:7], v[202:205], v[176:179], v[4:7]
	s_barrier
	s_setprio 0
	s_add_i32 s52, 0, 0x18000
	v_add_u32_e32 v144, s52, v1
	ds_read_b128 v[132:135], v144
	ds_read_b128 v[136:139], v144 offset:1024
	ds_read_b128 v[140:143], v144 offset:2048
	ds_read_b128 v[144:147], v144 offset:3072
	s_add_u32 s24, s24, 0x80000
	s_addc_u32 s25, s25, 0
	ds_read_b128 v[148:151], v224 offset:32768
	ds_read_b128 v[152:155], v224 offset:33792
	ds_read_b128 v[156:159], v224 offset:34816
	ds_read_b128 v[160:163], v224 offset:35840
	ds_read_b128 v[164:167], v224 offset:36864
	ds_read_b128 v[168:171], v224 offset:37888
	ds_read_b128 v[172:175], v224 offset:38912
	ds_read_b128 v[176:179], v224 offset:39936
	s_mov_b32 m0, s36
	s_nop 0
	global_load_lds_dwordx4 v196, s[24:25]
	s_mov_b32 m0, s37
	s_nop 0
	global_load_lds_dwordx4 v194, s[24:25]
	s_add_i32 s24, 0, 0x1c000
	v_add_u32_e32 v202, s24, v1
	ds_read_b128 v[180:183], v202
	ds_read_b128 v[184:187], v202 offset:1024
	ds_read_b128 v[188:191], v202 offset:2048
	ds_read_b128 v[202:205], v202 offset:3072
	s_waitcnt lgkmcnt(0)
	s_setprio 1
	s_barrier
	v_mfma_f32_16x16x32_bf16 v[128:131], v[132:135], v[148:151], v[128:131]
	v_mfma_f32_16x16x32_bf16 v[124:127], v[140:143], v[148:151], v[124:127]
	v_mfma_f32_16x16x32_bf16 v[112:115], v[132:135], v[156:159], v[112:115]
	v_mfma_f32_16x16x32_bf16 v[108:111], v[140:143], v[156:159], v[108:111]
	v_mfma_f32_16x16x32_bf16 v[100:103], v[132:135], v[164:167], v[100:103]
	v_mfma_f32_16x16x32_bf16 v[92:95], v[140:143], v[164:167], v[92:95]
	v_mfma_f32_16x16x32_bf16 v[84:87], v[132:135], v[172:175], v[84:87]
	v_mfma_f32_16x16x32_bf16 v[76:79], v[140:143], v[172:175], v[76:79]
	v_mfma_f32_16x16x32_bf16 v[128:131], v[136:139], v[152:155], v[128:131]
	v_mfma_f32_16x16x32_bf16 v[124:127], v[144:147], v[152:155], v[124:127]
	v_mfma_f32_16x16x32_bf16 v[112:115], v[136:139], v[160:163], v[112:115]
	v_mfma_f32_16x16x32_bf16 v[108:111], v[144:147], v[160:163], v[108:111]
	v_mfma_f32_16x16x32_bf16 v[100:103], v[136:139], v[168:171], v[100:103]
	v_mfma_f32_16x16x32_bf16 v[92:95], v[144:147], v[168:171], v[92:95]
	v_mfma_f32_16x16x32_bf16 v[84:87], v[136:139], v[176:179], v[84:87]
	v_mfma_f32_16x16x32_bf16 v[76:79], v[144:147], v[176:179], v[76:79]
	v_mfma_f32_16x16x32_bf16 v[120:123], v[180:183], v[148:151], v[120:123]
	v_mfma_f32_16x16x32_bf16 v[116:119], v[188:191], v[148:151], v[116:119]
	v_mfma_f32_16x16x32_bf16 v[104:107], v[180:183], v[156:159], v[104:107]
	v_mfma_f32_16x16x32_bf16 v[96:99], v[188:191], v[156:159], v[96:99]
	v_mfma_f32_16x16x32_bf16 v[88:91], v[180:183], v[164:167], v[88:91]
	v_mfma_f32_16x16x32_bf16 v[80:83], v[188:191], v[164:167], v[80:83]
	v_mfma_f32_16x16x32_bf16 v[72:75], v[180:183], v[172:175], v[72:75]
	v_mfma_f32_16x16x32_bf16 v[68:71], v[188:191], v[172:175], v[68:71]
	v_mfma_f32_16x16x32_bf16 v[120:123], v[184:187], v[152:155], v[120:123]
	v_mfma_f32_16x16x32_bf16 v[116:119], v[202:205], v[152:155], v[116:119]
	v_mfma_f32_16x16x32_bf16 v[104:107], v[184:187], v[160:163], v[104:107]
	v_mfma_f32_16x16x32_bf16 v[96:99], v[202:205], v[160:163], v[96:99]
	v_mfma_f32_16x16x32_bf16 v[88:91], v[184:187], v[168:171], v[88:91]
	v_mfma_f32_16x16x32_bf16 v[80:83], v[202:205], v[168:171], v[80:83]
	v_mfma_f32_16x16x32_bf16 v[72:75], v[184:187], v[176:179], v[72:75]
	v_mfma_f32_16x16x32_bf16 v[68:71], v[202:205], v[176:179], v[68:71]
	s_barrier
; #define PG8_STAGE(bufoff, gbase, voff) do { _Pragma("unroll") for (int _i = 0; _i < 2; ++_i) \
;         __builtin_amdgcn_global_load_lds((const unsigned*)((const char*)(gbase) + (voff)[_i]), (LAS unsigned*)(lds + (bufoff) + ldsw + _i * 8192), 16, 0, 0); } while (0)
; #define PG8_LDA(dst, b, h) do { _Pragma("unroll") for (int m = 0; m < 4; ++m) _Pragma("unroll") for (int k = 0; k < 2; ++k) dst[m][k] = *(const LAS bf16x8*)(lds + PG8_SA(b, h) + aoff + m * 2048 + k * 1024); } while (0)
; #define PG8_LDB(dst, b, h) do { _Pragma("unroll") for (int n = 0; n < 2; ++n) _Pragma("unroll") for (int k = 0; k < 2; ++k) dst[n][k] = *(const LAS bf16x8*)(lds + PG8_SB(b, h) + boff + n * 2048 + k * 1024); } while (0)
; #define PG8_MMA(ai, bj, At, Bt) do { __builtin_amdgcn_s_setprio(1); _Pragma("unroll") for (int m = 0; m < 4; ++m) _Pragma("unroll") for (int n = 0; n < 2; ++n) _Pragma("unroll") for (int k = 0; k < 2; ++k) \
;         acc[ai][bj][m][n] = __builtin_amdgcn_mfma_f32_16x16x32_bf16(Bt[n][k], At[m][k], acc[ai][bj][m][n], 0, 0, 0); __builtin_amdgcn_s_setprio(0); } while (0)
; #define PG8_WAIT_V(n) asm volatile("s_waitcnt vmcnt(" #n ")" ::: "memory")
; #define PG8_WAIT_L(n) asm volatile("s_waitcnt lgkmcnt(" #n ")" ::: "memory")
; #define PG8_BAR __builtin_amdgcn_s_barrier()
; #define PG8_SCHED __builtin_amdgcn_sched_barrier(0)
; template <class Epi, class Sched>
; __device__ __forceinline__ void gemm_phase(LAS unsigned char* lds, const Gemm g, const Sched& S, const Epi& E) {
;     ...
;             PG8_LDB(B1, 1, 1); PG8_STAGE(PG8_SB(1, 0), b3, voffB);
;             PG8_BAR; PG8_WAIT_L(0); PG8_MMA(0, 1, At, B1); PG8_BAR;
;             PG8_LDA(At, 1, 1); PG8_STAGE(PG8_SA(1, 0), a3, voffA);
;             PG8_BAR; PG8_WAIT_L(0); PG8_MMA(1, 0, At, B0); PG8_BAR; PG8_SCHED;
;             PG8_STAGE(PG8_SB(1, 1), b3 + hstepB, voffB);
;             PG8_WAIT_V(6); PG8_BAR; PG8_MMA(1, 1, At, B1); PG8_BAR;
	s_setprio 0
	ds_read_b128 v[148:151], v224 offset:49152
	ds_read_b128 v[152:155], v224 offset:50176
	ds_read_b128 v[156:159], v224 offset:51200
	ds_read_b128 v[160:163], v224 offset:52224
	ds_read_b128 v[164:167], v224 offset:53248
	ds_read_b128 v[168:171], v224 offset:54272
	ds_read_b128 v[172:175], v224 offset:55296
	ds_read_b128 v[176:179], v224 offset:56320
	s_add_i32 s25, s52, s30
	v_lshl_add_u64 v[206:207], v[206:207], 0, s[8:9]
	s_mov_b32 m0, s25
	s_nop 0
	global_load_lds_dwordx4 v[206:207], off
	v_lshl_add_u64 v[206:207], v[208:209], 0, s[8:9]
	s_add_i32 m0, s25, 0x2000
	s_nop 0
	global_load_lds_dwordx4 v[206:207], off
	s_mov_b32 m0, s42
	v_lshl_add_u64 v[206:207], v[210:211], 0, s[8:9]
	global_load_lds_dwordx4 v[206:207], off
	v_lshl_add_u64 v[206:207], v[212:213], 0, s[8:9]
	s_mov_b32 m0, s43
	s_nop 0
	global_load_lds_dwordx4 v[206:207], off
	s_add_u32 s20, s20, 0x80080
	s_addc_u32 s21, s21, 0
	s_add_i32 s24, s24, s30
	s_mov_b32 m0, s24
	s_nop 0
	global_load_lds_dwordx4 v2, s[20:21]
	s_add_i32 m0, s24, 0x2000
	s_nop 0
	global_load_lds_dwordx4 v192, s[20:21]
	s_add_i32 s51, s51, 2
	s_add_u32 s6, s6, 0x100
	s_addc_u32 s7, s7, 0
	s_add_u32 s49, s49, 0x100
	s_addc_u32 s50, s50, 0
	s_cmp_gt_u32 s51, 29
	s_waitcnt lgkmcnt(0)
	s_waitcnt vmcnt(6)
	s_setprio 1
	s_barrier
	v_mfma_f32_16x16x32_bf16 v[64:67], v[132:135], v[148:151], v[64:67]
	v_mfma_f32_16x16x32_bf16 v[60:63], v[140:143], v[148:151], v[60:63]
	v_mfma_f32_16x16x32_bf16 v[52:55], v[132:135], v[156:159], v[52:55]
	v_mfma_f32_16x16x32_bf16 v[44:47], v[140:143], v[156:159], v[44:47]
	v_mfma_f32_16x16x32_bf16 v[36:39], v[132:135], v[164:167], v[36:39]
	v_mfma_f32_16x16x32_bf16 v[28:31], v[140:143], v[164:167], v[28:31]
	v_mfma_f32_16x16x32_bf16 v[20:23], v[132:135], v[172:175], v[20:23]
	v_mfma_f32_16x16x32_bf16 v[12:15], v[140:143], v[172:175], v[12:15]
	v_mfma_f32_16x16x32_bf16 v[64:67], v[136:139], v[152:155], v[64:67]
	v_mfma_f32_16x16x32_bf16 v[60:63], v[144:147], v[152:155], v[60:63]
	v_mfma_f32_16x16x32_bf16 v[52:55], v[136:139], v[160:163], v[52:55]
	v_mfma_f32_16x16x32_bf16 v[44:47], v[144:147], v[160:163], v[44:47]
	v_mfma_f32_16x16x32_bf16 v[36:39], v[136:139], v[168:171], v[36:39]
	v_mfma_f32_16x16x32_bf16 v[28:31], v[144:147], v[168:171], v[28:31]
	v_mfma_f32_16x16x32_bf16 v[20:23], v[136:139], v[176:179], v[20:23]
	v_mfma_f32_16x16x32_bf16 v[12:15], v[144:147], v[176:179], v[12:15]
	v_mfma_f32_16x16x32_bf16 v[56:59], v[180:183], v[148:151], v[56:59]
	v_mfma_f32_16x16x32_bf16 v[48:51], v[188:191], v[148:151], v[48:51]
	v_mfma_f32_16x16x32_bf16 v[40:43], v[180:183], v[156:159], v[40:43]
	v_mfma_f32_16x16x32_bf16 v[32:35], v[188:191], v[156:159], v[32:35]
	v_mfma_f32_16x16x32_bf16 v[24:27], v[180:183], v[164:167], v[24:27]
	v_mfma_f32_16x16x32_bf16 v[16:19], v[188:191], v[164:167], v[16:19]
	v_mfma_f32_16x16x32_bf16 v[8:11], v[180:183], v[172:175], v[8:11]
	v_mfma_f32_16x16x32_bf16 v[4:7], v[188:191], v[172:175], v[4:7]
	v_mfma_f32_16x16x32_bf16 v[56:59], v[184:187], v[152:155], v[56:59]
	v_mfma_f32_16x16x32_bf16 v[48:51], v[202:205], v[152:155], v[48:51]
	v_mfma_f32_16x16x32_bf16 v[40:43], v[184:187], v[160:163], v[40:43]
	v_mfma_f32_16x16x32_bf16 v[32:35], v[202:205], v[160:163], v[32:35]
	v_mfma_f32_16x16x32_bf16 v[24:27], v[184:187], v[168:171], v[24:27]
	v_mfma_f32_16x16x32_bf16 v[16:19], v[202:205], v[168:171], v[16:19]
	v_mfma_f32_16x16x32_bf16 v[8:11], v[184:187], v[176:179], v[8:11]
	v_mfma_f32_16x16x32_bf16 v[4:7], v[202:205], v[176:179], v[4:7]
	s_barrier
	s_setprio 0

; #define PG8_STAGE(bufoff, gbase, voff) do { _Pragma("unroll") for (int _i = 0; _i < 2; ++_i) \
;         __builtin_amdgcn_global_load_lds((const unsigned*)((const char*)(gbase) + (voff)[_i]), (LAS unsigned*)(lds + (bufoff) + ldsw + _i * 8192), 16, 0, 0); } while (0)
; #define PG8_LDA(dst, b, h) do { _Pragma("unroll") for (int m = 0; m < 4; ++m) _Pragma("unroll") for (int k = 0; k < 2; ++k) dst[m][k] = *(const LAS bf16x8*)(lds + PG8_SA(b, h) + aoff + m * 2048 + k * 1024); } while (0)
; #define PG8_LDB(dst, b, h) do { _Pragma("unroll") for (int n = 0; n < 2; ++n) _Pragma("unroll") for (int k = 0; k < 2; ++k) dst[n][k] = *(const LAS bf16x8*)(lds + PG8_SB(b, h) + boff + n * 2048 + k * 1024); } while (0)
; #define PG8_MMA(ai, bj, At, Bt) do { __builtin_amdgcn_s_setprio(1); _Pragma("unroll") for (int m = 0; m < 4; ++m) _Pragma("unroll") for (int n = 0; n < 2; ++n) _Pragma("unroll") for (int k = 0; k < 2; ++k) \
;         acc[ai][bj][m][n] = __builtin_amdgcn_mfma_f32_16x16x32_bf16(Bt[n][k], At[m][k], acc[ai][bj][m][n], 0, 0, 0); __builtin_amdgcn_s_setprio(0); } while (0)
; #define PG8_WAIT_V(n) asm volatile("s_waitcnt vmcnt(" #n ")" ::: "memory")
; #define PG8_WAIT_L(n) asm volatile("s_waitcnt lgkmcnt(" #n ")" ::: "memory")
; #define PG8_BAR __builtin_amdgcn_s_barrier()
; #define PG8_SCHED __builtin_amdgcn_sched_barrier(0)
; template <class Epi, class Sched>
; __device__ __forceinline__ void gemm_phase(LAS unsigned char* lds, const Gemm g, const Sched& S, const Epi& E) {
;     ...
;         const bool has_next = S.next(ui + 1, nxt);
;         const char* nA = has_next ? (const char*)g.A + (size_t)nxt.pm * tstepA : cA; const char* nB = has_next ? (const char*)g.Bt + (size_t)nxt.pn * tstepB : cB;
;     ...
;             PG8_LDB(B0, 0, 0); PG8_SCHED; PG8_LDA(At, 0, 0); PG8_STAGE(PG8_SA(1, 1), a1 + hstepA, voffA);
;             PG8_WAIT_L(8); PG8_BAR; PG8_WAIT_L(0); PG8_MMA(0, 0, At, B0); PG8_BAR; PG8_SCHED;
;             PG8_LDB(B1, 0, 1); PG8_STAGE(PG8_SB(0, 0), b2, voffB);
;             PG8_BAR; PG8_WAIT_L(0); PG8_MMA(0, 1, At, B1); PG8_BAR;
;             PG8_LDA(At, 0, 1); PG8_STAGE(PG8_SA(0, 0), a2, voffA);
;             PG8_BAR; PG8_WAIT_L(0); PG8_MMA(1, 0, At, B0); PG8_BAR; PG8_SCHED;
;             PG8_STAGE(PG8_SB(0, 1), b2 + hstepB, voffB);
;             PG8_WAIT_V(6); PG8_BAR; PG8_MMA(1, 1, At, B1); PG8_BAR;
.LBB0_1525:
	v_mov_b64_e32 v[4:5], 0x1600
	s_ashr_i32 s57, s56, 31
	v_cmp_lt_i64_e32 vcc, s[14:15], v[4:5]
	s_lshl_b64 s[14:15], s[56:57], 20
	s_add_u32 s58, s88, s14
	s_addc_u32 s59, s89, s15
	s_and_b64 s[14:15], vcc, exec
	s_cselect_b32 s57, s59, s5
	s_cselect_b32 s67, s58, s4
	s_ashr_i32 s55, s54, 31
	s_lshl_b64 s[14:15], s[54:55], 20
	s_add_u32 s60, s2, s14
	s_addc_u32 s61, s18, s15
	s_and_b64 s[14:15], vcc, exec
	s_cselect_b32 s55, s61, s7
	s_cselect_b32 s68, s60, s6
	s_add_u32 s4, s4, 0x80080
	s_addc_u32 s5, s5, 0
	s_add_u32 s69, s6, 0x100
	s_waitcnt vmcnt(0)
	s_addc_u32 s70, s7, 0
	s_mov_b32 s71, -2
	s_setprio 0
	s_add_u32 s6, s4, 0xfff80080
	s_addc_u32 s7, s5, -1
	s_add_i32 s72, 0, 0x10000
	v_add_u32_e32 v2, s72, v1
	ds_read_b128 v[132:135], v2
	ds_read_b128 v[136:139], v2 offset:1024
	ds_read_b128 v[140:143], v2 offset:2048
	ds_read_b128 v[144:147], v2 offset:3072
	s_cmp_eq_u32 s71, 28
	s_cselect_b32 s15, s57, s7
	s_cselect_b32 s14, s67, s6
	s_cselect_b32 s7, s55, s70
	s_cselect_b32 s6, s68, s69
	ds_read_b128 v[148:151], v207
	ds_read_b128 v[152:155], v207 offset:1024
	ds_read_b128 v[156:159], v207 offset:2048
	ds_read_b128 v[160:163], v207 offset:3072
	ds_read_b128 v[164:167], v207 offset:4096
	ds_read_b128 v[168:171], v207 offset:5120
	ds_read_b128 v[186:189], v207 offset:6144
	ds_read_b128 v[190:193], v207 offset:7168
	s_add_i32 s74, 0, 0x14000
	v_add_u32_e32 v2, s74, v1
	ds_read_b128 v[194:197], v2
	ds_read_b128 v[198:201], v2 offset:1024
	ds_read_b128 v[202:205], v2 offset:2048
	ds_read_b128 v[208:211], v2 offset:3072
	s_add_i32 m0, s20, 0xc000
	s_nop 0
	global_load_lds_dwordx4 v182, s[4:5]
	s_add_i32 m0, s20, 0xe000
	s_nop 0
	global_load_lds_dwordx4 v184, s[4:5]
	s_waitcnt lgkmcnt(0)
	s_setprio 1
	s_barrier
	v_mfma_f32_16x16x32_bf16 v[68:71], v[132:135], v[148:151], 0
	v_mfma_f32_16x16x32_bf16 v[72:75], v[140:143], v[148:151], 0
	v_mfma_f32_16x16x32_bf16 v[120:123], v[132:135], v[156:159], 0
	v_mfma_f32_16x16x32_bf16 v[116:119], v[140:143], v[156:159], 0
	v_mfma_f32_16x16x32_bf16 v[112:115], v[132:135], v[164:167], 0
	v_mfma_f32_16x16x32_bf16 v[108:111], v[140:143], v[164:167], 0
	v_mfma_f32_16x16x32_bf16 v[104:107], v[132:135], v[186:189], 0
	v_mfma_f32_16x16x32_bf16 v[100:103], v[140:143], v[186:189], 0
	v_mfma_f32_16x16x32_bf16 v[68:71], v[136:139], v[152:155], v[68:71]
	v_mfma_f32_16x16x32_bf16 v[72:75], v[144:147], v[152:155], v[72:75]
	v_mfma_f32_16x16x32_bf16 v[120:123], v[136:139], v[160:163], v[120:123]
	v_mfma_f32_16x16x32_bf16 v[116:119], v[144:147], v[160:163], v[116:119]
	v_mfma_f32_16x16x32_bf16 v[112:115], v[136:139], v[168:171], v[112:115]
	v_mfma_f32_16x16x32_bf16 v[108:111], v[144:147], v[168:171], v[108:111]
	v_mfma_f32_16x16x32_bf16 v[104:107], v[136:139], v[190:193], v[104:107]
	v_mfma_f32_16x16x32_bf16 v[100:103], v[144:147], v[190:193], v[100:103]
	v_mfma_f32_16x16x32_bf16 v[76:79], v[194:197], v[148:151], 0
	v_mfma_f32_16x16x32_bf16 v[80:83], v[202:205], v[148:151], 0
	v_mfma_f32_16x16x32_bf16 v[96:99], v[194:197], v[156:159], 0
	v_mfma_f32_16x16x32_bf16 v[92:95], v[202:205], v[156:159], 0
	v_mfma_f32_16x16x32_bf16 v[88:91], v[194:197], v[164:167], 0
	v_mfma_f32_16x16x32_bf16 v[84:87], v[202:205], v[164:167], 0
	v_mfma_f32_16x16x32_bf16 v[128:131], v[194:197], v[186:189], 0
	v_mfma_f32_16x16x32_bf16 v[124:127], v[202:205], v[186:189], 0
	v_mfma_f32_16x16x32_bf16 v[76:79], v[198:201], v[152:155], v[76:79]
	v_mfma_f32_16x16x32_bf16 v[80:83], v[208:211], v[152:155], v[80:83]
	v_mfma_f32_16x16x32_bf16 v[96:99], v[198:201], v[160:163], v[96:99]
	v_mfma_f32_16x16x32_bf16 v[92:95], v[208:211], v[160:163], v[92:95]
	v_mfma_f32_16x16x32_bf16 v[88:91], v[198:201], v[168:171], v[88:91]
	v_mfma_f32_16x16x32_bf16 v[84:87], v[208:211], v[168:171], v[84:87]
	v_mfma_f32_16x16x32_bf16 v[128:131], v[198:201], v[190:193], v[128:131]
	v_mfma_f32_16x16x32_bf16 v[124:127], v[208:211], v[190:193], v[124:127]
	s_barrier
	s_setprio 0
	ds_read_b128 v[148:151], v207 offset:16384
	ds_read_b128 v[152:155], v207 offset:17408
	ds_read_b128 v[156:159], v207 offset:18432
	ds_read_b128 v[160:163], v207 offset:19456
	ds_read_b128 v[164:167], v207 offset:20480
	ds_read_b128 v[168:171], v207 offset:21504
	ds_read_b128 v[186:189], v207 offset:22528
	ds_read_b128 v[190:193], v207 offset:23552
	s_add_i32 s72, s72, s19
	v_lshl_add_u64 v[172:173], s[6:7], 0, v[178:179]
	s_mov_b32 m0, s72
	s_nop 0
	global_load_lds_dwordx4 v[172:173], off
	v_lshl_add_u64 v[212:213], s[6:7], 0, v[174:175]
	s_add_i32 m0, s72, 0x2000
	s_nop 0
	global_load_lds_dwordx4 v[212:213], off
	s_mov_b32 m0, s20
	v_lshl_add_u64 v[216:217], s[14:15], 0, v[180:181]
	global_load_lds_dwordx4 v[216:217], off
	v_lshl_add_u64 v[218:219], s[14:15], 0, v[176:177]
	s_mov_b32 m0, s21
	s_nop 0
	global_load_lds_dwordx4 v[218:219], off
	s_add_u32 s72, s6, 0x80000
	s_addc_u32 s73, s7, 0
	s_add_i32 s74, s74, s19
	s_mov_b32 m0, s74
	s_nop 0
	global_load_lds_dwordx4 v178, s[72:73]
	s_add_i32 m0, s74, 0x2000
	s_nop 0
	global_load_lds_dwordx4 v174, s[72:73]
	s_waitcnt lgkmcnt(0)
	s_waitcnt vmcnt(6)
	s_setprio 1
	s_barrier
; #define PG8_STAGE(bufoff, gbase, voff) do { _Pragma("unroll") for (int _i = 0; _i < 2; ++_i) \
;         __builtin_amdgcn_global_load_lds((const unsigned*)((const char*)(gbase) + (voff)[_i]), (LAS unsigned*)(lds + (bufoff) + ldsw + _i * 8192), 16, 0, 0); } while (0)
; #define PG8_LDA(dst, b, h) do { _Pragma("unroll") for (int m = 0; m < 4; ++m) _Pragma("unroll") for (int k = 0; k < 2; ++k) dst[m][k] = *(const LAS bf16x8*)(lds + PG8_SA(b, h) + aoff + m * 2048 + k * 1024); } while (0)
; #define PG8_LDB(dst, b, h) do { _Pragma("unroll") for (int n = 0; n < 2; ++n) _Pragma("unroll") for (int k = 0; k < 2; ++k) dst[n][k] = *(const LAS bf16x8*)(lds + PG8_SB(b, h) + boff + n * 2048 + k * 1024); } while (0)
; #define PG8_MMA(ai, bj, At, Bt) do { __builtin_amdgcn_s_setprio(1); _Pragma("unroll") for (int m = 0; m < 4; ++m) _Pragma("unroll") for (int n = 0; n < 2; ++n) _Pragma("unroll") for (int k = 0; k < 2; ++k) \
;         acc[ai][bj][m][n] = __builtin_amdgcn_mfma_f32_16x16x32_bf16(Bt[n][k], At[m][k], acc[ai][bj][m][n], 0, 0, 0); __builtin_amdgcn_s_setprio(0); } while (0)
; #define PG8_WAIT_V(n) asm volatile("s_waitcnt vmcnt(" #n ")" ::: "memory")
; #define PG8_WAIT_L(n) asm volatile("s_waitcnt lgkmcnt(" #n ")" ::: "memory")
; #define PG8_BAR __builtin_amdgcn_s_barrier()
; #define PG8_SCHED __builtin_amdgcn_sched_barrier(0)
; template <class Epi, class Sched>
; __device__ __forceinline__ void gemm_phase(LAS unsigned char* lds, const Gemm g, const Sched& S, const Epi& E) {
;     ...
;             PG8_BAR; PG8_WAIT_L(0); PG8_MMA(1, 0, At, B0); PG8_BAR; PG8_SCHED;
;             PG8_STAGE(PG8_SB(0, 1), b2 + hstepB, voffB);
;             PG8_WAIT_V(6); PG8_BAR; PG8_MMA(1, 1, At, B1); PG8_BAR;
;             PG8_LDB(B0, 1, 0); PG8_SCHED; PG8_LDA(At, 1, 0); PG8_STAGE(PG8_SA(0, 1), a2 + hstepA, voffA);
;             PG8_WAIT_L(8); PG8_BAR; PG8_WAIT_L(0); PG8_MMA(0, 0, At, B0); PG8_BAR; PG8_SCHED;
;             PG8_LDB(B1, 1, 1); PG8_STAGE(PG8_SB(1, 0), b3, voffB);
;             PG8_BAR; PG8_WAIT_L(0); PG8_MMA(0, 1, At, B1); PG8_BAR;
	v_mfma_f32_16x16x32_bf16 v[56:59], v[132:135], v[148:151], 0
	v_mfma_f32_16x16x32_bf16 v[52:55], v[140:143], v[148:151], 0
	v_mfma_f32_16x16x32_bf16 v[48:51], v[132:135], v[156:159], 0
	v_mfma_f32_16x16x32_bf16 v[44:47], v[140:143], v[156:159], 0
	v_mfma_f32_16x16x32_bf16 v[40:43], v[132:135], v[164:167], 0
	v_mfma_f32_16x16x32_bf16 v[36:39], v[140:143], v[164:167], 0
	v_mfma_f32_16x16x32_bf16 v[32:35], v[132:135], v[186:189], 0
	v_mfma_f32_16x16x32_bf16 v[28:31], v[140:143], v[186:189], 0
	v_mfma_f32_16x16x32_bf16 v[56:59], v[136:139], v[152:155], v[56:59]
	v_mfma_f32_16x16x32_bf16 v[52:55], v[144:147], v[152:155], v[52:55]
	v_mfma_f32_16x16x32_bf16 v[48:51], v[136:139], v[160:163], v[48:51]
	v_mfma_f32_16x16x32_bf16 v[44:47], v[144:147], v[160:163], v[44:47]
	v_mfma_f32_16x16x32_bf16 v[40:43], v[136:139], v[168:171], v[40:43]
	v_mfma_f32_16x16x32_bf16 v[36:39], v[144:147], v[168:171], v[36:39]
	v_mfma_f32_16x16x32_bf16 v[32:35], v[136:139], v[190:193], v[32:35]
	v_mfma_f32_16x16x32_bf16 v[28:31], v[144:147], v[190:193], v[28:31]
	v_mfma_f32_16x16x32_bf16 v[24:27], v[194:197], v[148:151], 0
	v_mfma_f32_16x16x32_bf16 v[20:23], v[202:205], v[148:151], 0
	v_mfma_f32_16x16x32_bf16 v[16:19], v[194:197], v[156:159], 0
	v_mfma_f32_16x16x32_bf16 v[12:15], v[202:205], v[156:159], 0
	v_mfma_f32_16x16x32_bf16 v[8:11], v[194:197], v[164:167], 0
	v_mfma_f32_16x16x32_bf16 v[4:7], v[202:205], v[164:167], 0
	v_mfma_f32_16x16x32_bf16 v[60:63], v[194:197], v[186:189], 0
	v_mfma_f32_16x16x32_bf16 v[64:67], v[202:205], v[186:189], 0
	v_mfma_f32_16x16x32_bf16 v[24:27], v[198:201], v[152:155], v[24:27]
	v_mfma_f32_16x16x32_bf16 v[20:23], v[208:211], v[152:155], v[20:23]
	v_mfma_f32_16x16x32_bf16 v[16:19], v[198:201], v[160:163], v[16:19]
	v_mfma_f32_16x16x32_bf16 v[12:15], v[208:211], v[160:163], v[12:15]
	v_mfma_f32_16x16x32_bf16 v[8:11], v[198:201], v[168:171], v[8:11]
	v_mfma_f32_16x16x32_bf16 v[4:7], v[208:211], v[168:171], v[4:7]
	v_mfma_f32_16x16x32_bf16 v[60:63], v[198:201], v[190:193], v[60:63]
	v_mfma_f32_16x16x32_bf16 v[64:67], v[208:211], v[190:193], v[64:67]
	s_barrier
	s_setprio 0
	s_add_i32 s72, 0, 0x18000
	v_add_u32_e32 v2, s72, v1
	ds_read_b128 v[132:135], v2
	ds_read_b128 v[136:139], v2 offset:1024
	ds_read_b128 v[140:143], v2 offset:2048
	ds_read_b128 v[144:147], v2 offset:3072
	s_add_u32 s14, s14, 0x80000
	s_addc_u32 s15, s15, 0
	ds_read_b128 v[148:151], v207 offset:32768
	ds_read_b128 v[152:155], v207 offset:33792
	ds_read_b128 v[156:159], v207 offset:34816
	ds_read_b128 v[160:163], v207 offset:35840
	ds_read_b128 v[164:167], v207 offset:36864
	ds_read_b128 v[168:171], v207 offset:37888
	ds_read_b128 v[186:189], v207 offset:38912
	ds_read_b128 v[190:193], v207 offset:39936
	s_mov_b32 m0, s24
	s_nop 0
	global_load_lds_dwordx4 v180, s[14:15]
	s_mov_b32 m0, s25
	s_nop 0
	global_load_lds_dwordx4 v176, s[14:15]
	s_add_i32 s14, 0, 0x1c000
	v_add_u32_e32 v2, s14, v1
	ds_read_b128 v[194:197], v2
	ds_read_b128 v[198:201], v2 offset:1024
	ds_read_b128 v[202:205], v2 offset:2048
	ds_read_b128 v[208:211], v2 offset:3072
	s_waitcnt lgkmcnt(0)
	s_setprio 1
	s_barrier
	v_mfma_f32_16x16x32_bf16 v[68:71], v[132:135], v[148:151], v[68:71]
	v_mfma_f32_16x16x32_bf16 v[72:75], v[140:143], v[148:151], v[72:75]
	v_mfma_f32_16x16x32_bf16 v[120:123], v[132:135], v[156:159], v[120:123]
	v_mfma_f32_16x16x32_bf16 v[116:119], v[140:143], v[156:159], v[116:119]
	v_mfma_f32_16x16x32_bf16 v[112:115], v[132:135], v[164:167], v[112:115]
	v_mfma_f32_16x16x32_bf16 v[108:111], v[140:143], v[164:167], v[108:111]
	v_mfma_f32_16x16x32_bf16 v[104:107], v[132:135], v[186:189], v[104:107]
	v_mfma_f32_16x16x32_bf16 v[100:103], v[140:143], v[186:189], v[100:103]
	v_mfma_f32_16x16x32_bf16 v[68:71], v[136:139], v[152:155], v[68:71]
	v_mfma_f32_16x16x32_bf16 v[72:75], v[144:147], v[152:155], v[72:75]
	v_mfma_f32_16x16x32_bf16 v[120:123], v[136:139], v[160:163], v[120:123]
	v_mfma_f32_16x16x32_bf16 v[116:119], v[144:147], v[160:163], v[116:119]
	v_mfma_f32_16x16x32_bf16 v[112:115], v[136:139], v[168:171], v[112:115]
	v_mfma_f32_16x16x32_bf16 v[108:111], v[144:147], v[168:171], v[108:111]
	v_mfma_f32_16x16x32_bf16 v[104:107], v[136:139], v[190:193], v[104:107]
	v_mfma_f32_16x16x32_bf16 v[100:103], v[144:147], v[190:193], v[100:103]
	v_mfma_f32_16x16x32_bf16 v[76:79], v[194:197], v[148:151], v[76:79]
	v_mfma_f32_16x16x32_bf16 v[80:83], v[202:205], v[148:151], v[80:83]
	v_mfma_f32_16x16x32_bf16 v[96:99], v[194:197], v[156:159], v[96:99]
	v_mfma_f32_16x16x32_bf16 v[92:95], v[202:205], v[156:159], v[92:95]
	v_mfma_f32_16x16x32_bf16 v[88:91], v[194:197], v[164:167], v[88:91]
	v_mfma_f32_16x16x32_bf16 v[84:87], v[202:205], v[164:167], v[84:87]
	v_mfma_f32_16x16x32_bf16 v[128:131], v[194:197], v[186:189], v[128:131]
	v_mfma_f32_16x16x32_bf16 v[124:127], v[202:205], v[186:189], v[124:127]
	v_mfma_f32_16x16x32_bf16 v[76:79], v[198:201], v[152:155], v[76:79]
	v_mfma_f32_16x16x32_bf16 v[80:83], v[208:211], v[152:155], v[80:83]
	v_mfma_f32_16x16x32_bf16 v[96:99], v[198:201], v[160:163], v[96:99]
	v_mfma_f32_16x16x32_bf16 v[92:95], v[208:211], v[160:163], v[92:95]
	v_mfma_f32_16x16x32_bf16 v[88:91], v[198:201], v[168:171], v[88:91]
	v_mfma_f32_16x16x32_bf16 v[84:87], v[208:211], v[168:171], v[84:87]
	v_mfma_f32_16x16x32_bf16 v[128:131], v[198:201], v[190:193], v[128:131]
	v_mfma_f32_16x16x32_bf16 v[124:127], v[208:211], v[190:193], v[124:127]
	s_barrier
; #define PG8_STAGE(bufoff, gbase, voff) do { _Pragma("unroll") for (int _i = 0; _i < 2; ++_i) \
;         __builtin_amdgcn_global_load_lds((const unsigned*)((const char*)(gbase) + (voff)[_i]), (LAS unsigned*)(lds + (bufoff) + ldsw + _i * 8192), 16, 0, 0); } while (0)
; #define PG8_LDA(dst, b, h) do { _Pragma("unroll") for (int m = 0; m < 4; ++m) _Pragma("unroll") for (int k = 0; k < 2; ++k) dst[m][k] = *(const LAS bf16x8*)(lds + PG8_SA(b, h) + aoff + m * 2048 + k * 1024); } while (0)
; #define PG8_LDB(dst, b, h) do { _Pragma("unroll") for (int n = 0; n < 2; ++n) _Pragma("unroll") for (int k = 0; k < 2; ++k) dst[n][k] = *(const LAS bf16x8*)(lds + PG8_SB(b, h) + boff + n * 2048 + k * 1024); } while (0)
; #define PG8_MMA(ai, bj, At, Bt) do { __builtin_amdgcn_s_setprio(1); _Pragma("unroll") for (int m = 0; m < 4; ++m) _Pragma("unroll") for (int n = 0; n < 2; ++n) _Pragma("unroll") for (int k = 0; k < 2; ++k) \
;         acc[ai][bj][m][n] = __builtin_amdgcn_mfma_f32_16x16x32_bf16(Bt[n][k], At[m][k], acc[ai][bj][m][n], 0, 0, 0); __builtin_amdgcn_s_setprio(0); } while (0)
; #define PG8_WAIT_V(n) asm volatile("s_waitcnt vmcnt(" #n ")" ::: "memory")
; #define PG8_WAIT_L(n) asm volatile("s_waitcnt lgkmcnt(" #n ")" ::: "memory")
; #define PG8_BAR __builtin_amdgcn_s_barrier()
; #define PG8_SCHED __builtin_amdgcn_sched_barrier(0)
; template <class Epi, class Sched>
; __device__ __forceinline__ void gemm_phase(LAS unsigned char* lds, const Gemm g, const Sched& S, const Epi& E) {
;     ...
;             PG8_LDB(B1, 1, 1); PG8_STAGE(PG8_SB(1, 0), b3, voffB);
;             PG8_BAR; PG8_WAIT_L(0); PG8_MMA(0, 1, At, B1); PG8_BAR;
;             PG8_LDA(At, 1, 1); PG8_STAGE(PG8_SA(1, 0), a3, voffA);
;             PG8_BAR; PG8_WAIT_L(0); PG8_MMA(1, 0, At, B0); PG8_BAR; PG8_SCHED;
;             PG8_STAGE(PG8_SB(1, 1), b3 + hstepB, voffB);
;             PG8_WAIT_V(6); PG8_BAR; PG8_MMA(1, 1, At, B1); PG8_BAR;
	s_setprio 0
	ds_read_b128 v[148:151], v207 offset:49152
	ds_read_b128 v[152:155], v207 offset:50176
	ds_read_b128 v[156:159], v207 offset:51200
	ds_read_b128 v[160:163], v207 offset:52224
	ds_read_b128 v[164:167], v207 offset:53248
	ds_read_b128 v[168:171], v207 offset:54272
	ds_read_b128 v[186:189], v207 offset:55296
	ds_read_b128 v[190:193], v207 offset:56320
	s_add_i32 s15, s72, s19
	v_lshl_add_u64 v[172:173], v[172:173], 0, s[8:9]
	s_mov_b32 m0, s15
	s_nop 0
	global_load_lds_dwordx4 v[172:173], off
	v_lshl_add_u64 v[172:173], v[212:213], 0, s[8:9]
	s_add_i32 m0, s15, 0x2000
	s_nop 0
	global_load_lds_dwordx4 v[172:173], off
	s_mov_b32 m0, s30
	v_lshl_add_u64 v[172:173], v[216:217], 0, s[8:9]
	global_load_lds_dwordx4 v[172:173], off
	v_lshl_add_u64 v[172:173], v[218:219], 0, s[8:9]
	s_mov_b32 m0, s31
	s_nop 0
	global_load_lds_dwordx4 v[172:173], off
	s_add_u32 s6, s6, 0x80080
	s_addc_u32 s7, s7, 0
	s_add_i32 s14, s14, s19
	s_mov_b32 m0, s14
	s_nop 0
	global_load_lds_dwordx4 v178, s[6:7]
	s_add_i32 m0, s14, 0x2000
	s_nop 0
	global_load_lds_dwordx4 v174, s[6:7]
	s_add_i32 s71, s71, 2
	s_add_u32 s4, s4, 0x100
	s_addc_u32 s5, s5, 0
	s_add_u32 s69, s69, 0x100
	s_addc_u32 s70, s70, 0
	s_cmp_gt_u32 s71, 29
	s_waitcnt lgkmcnt(0)
	s_waitcnt vmcnt(6)
	s_setprio 1
	s_barrier
	v_mfma_f32_16x16x32_bf16 v[56:59], v[132:135], v[148:151], v[56:59]
	v_mfma_f32_16x16x32_bf16 v[52:55], v[140:143], v[148:151], v[52:55]
	v_mfma_f32_16x16x32_bf16 v[48:51], v[132:135], v[156:159], v[48:51]
	v_mfma_f32_16x16x32_bf16 v[44:47], v[140:143], v[156:159], v[44:47]
	v_mfma_f32_16x16x32_bf16 v[40:43], v[132:135], v[164:167], v[40:43]
	v_mfma_f32_16x16x32_bf16 v[36:39], v[140:143], v[164:167], v[36:39]
	v_mfma_f32_16x16x32_bf16 v[32:35], v[132:135], v[186:189], v[32:35]
	v_mfma_f32_16x16x32_bf16 v[28:31], v[140:143], v[186:189], v[28:31]
	v_mfma_f32_16x16x32_bf16 v[56:59], v[136:139], v[152:155], v[56:59]
	v_mfma_f32_16x16x32_bf16 v[52:55], v[144:147], v[152:155], v[52:55]
	v_mfma_f32_16x16x32_bf16 v[48:51], v[136:139], v[160:163], v[48:51]
	v_mfma_f32_16x16x32_bf16 v[44:47], v[144:147], v[160:163], v[44:47]
	v_mfma_f32_16x16x32_bf16 v[40:43], v[136:139], v[168:171], v[40:43]
	v_mfma_f32_16x16x32_bf16 v[36:39], v[144:147], v[168:171], v[36:39]
	v_mfma_f32_16x16x32_bf16 v[32:35], v[136:139], v[190:193], v[32:35]
	v_mfma_f32_16x16x32_bf16 v[28:31], v[144:147], v[190:193], v[28:31]
	v_mfma_f32_16x16x32_bf16 v[24:27], v[194:197], v[148:151], v[24:27]
	v_mfma_f32_16x16x32_bf16 v[20:23], v[202:205], v[148:151], v[20:23]
	v_mfma_f32_16x16x32_bf16 v[16:19], v[194:197], v[156:159], v[16:19]
	v_mfma_f32_16x16x32_bf16 v[12:15], v[202:205], v[156:159], v[12:15]
	v_mfma_f32_16x16x32_bf16 v[8:11], v[194:197], v[164:167], v[8:11]
	v_mfma_f32_16x16x32_bf16 v[4:7], v[202:205], v[164:167], v[4:7]
	v_mfma_f32_16x16x32_bf16 v[60:63], v[194:197], v[186:189], v[60:63]
	v_mfma_f32_16x16x32_bf16 v[64:67], v[202:205], v[186:189], v[64:67]
	v_mfma_f32_16x16x32_bf16 v[24:27], v[198:201], v[152:155], v[24:27]
	v_mfma_f32_16x16x32_bf16 v[20:23], v[208:211], v[152:155], v[20:23]
	v_mfma_f32_16x16x32_bf16 v[16:19], v[198:201], v[160:163], v[16:19]
	v_mfma_f32_16x16x32_bf16 v[12:15], v[208:211], v[160:163], v[12:15]
	v_mfma_f32_16x16x32_bf16 v[8:11], v[198:201], v[168:171], v[8:11]
	v_mfma_f32_16x16x32_bf16 v[4:7], v[208:211], v[168:171], v[4:7]
	v_mfma_f32_16x16x32_bf16 v[60:63], v[198:201], v[190:193], v[60:63]
	v_mfma_f32_16x16x32_bf16 v[64:67], v[208:211], v[190:193], v[64:67]
	s_barrier
	s_setprio 0

; #define PG8_STAGE(bufoff, gbase, voff) do { _Pragma("unroll") for (int _i = 0; _i < 2; ++_i) \
;         __builtin_amdgcn_global_load_lds((const unsigned*)((const char*)(gbase) + (voff)[_i]), (LAS unsigned*)(lds + (bufoff) + ldsw + _i * 8192), 16, 0, 0); } while (0)
; #define PG8_LDA(dst, b, h) do { _Pragma("unroll") for (int m = 0; m < 4; ++m) _Pragma("unroll") for (int k = 0; k < 2; ++k) dst[m][k] = *(const LAS bf16x8*)(lds + PG8_SA(b, h) + aoff + m * 2048 + k * 1024); } while (0)
; #define PG8_LDB(dst, b, h) do { _Pragma("unroll") for (int n = 0; n < 2; ++n) _Pragma("unroll") for (int k = 0; k < 2; ++k) dst[n][k] = *(const LAS bf16x8*)(lds + PG8_SB(b, h) + boff + n * 2048 + k * 1024); } while (0)
; #define PG8_MMA(ai, bj, At, Bt) do { __builtin_amdgcn_s_setprio(1); _Pragma("unroll") for (int m = 0; m < 4; ++m) _Pragma("unroll") for (int n = 0; n < 2; ++n) _Pragma("unroll") for (int k = 0; k < 2; ++k) \
;         acc[ai][bj][m][n] = __builtin_amdgcn_mfma_f32_16x16x32_bf16(Bt[n][k], At[m][k], acc[ai][bj][m][n], 0, 0, 0); __builtin_amdgcn_s_setprio(0); } while (0)
; #define PG8_WAIT_V(n) asm volatile("s_waitcnt vmcnt(" #n ")" ::: "memory")
; #define PG8_WAIT_L(n) asm volatile("s_waitcnt lgkmcnt(" #n ")" ::: "memory")
; #define PG8_BAR __builtin_amdgcn_s_barrier()
; #define PG8_SCHED __builtin_amdgcn_sched_barrier(0)
; template <class Epi, class Sched>
; __device__ __forceinline__ void gemm_phase(LAS unsigned char* lds, const Gemm g, const Sched& S, const Epi& E) {
;     ...
;             PG8_LDB(B0, 0, 0); PG8_SCHED; PG8_LDA(At, 0, 0); PG8_STAGE(PG8_SA(1, 1), a1 + hstepA, voffA);
;             PG8_WAIT_L(8); PG8_BAR; PG8_WAIT_L(0); PG8_MMA(0, 0, At, B0); PG8_BAR; PG8_SCHED;
;             PG8_LDB(B1, 0, 1); PG8_STAGE(PG8_SB(0, 0), b2, voffB);
;             PG8_BAR; PG8_WAIT_L(0); PG8_MMA(0, 1, At, B1); PG8_BAR;
;             PG8_LDA(At, 0, 1); PG8_STAGE(PG8_SA(0, 0), a2, voffA);
;             PG8_BAR; PG8_WAIT_L(0); PG8_MMA(1, 0, At, B0); PG8_BAR; PG8_SCHED;
;             PG8_STAGE(PG8_SB(0, 1), b2 + hstepB, voffB);
;             PG8_WAIT_V(6); PG8_BAR; PG8_MMA(1, 1, At, B1); PG8_BAR;
.LBB0_1665:
	s_add_u32 s42, s14, 0x100
	s_addc_u32 s43, s15, 0
	s_mov_b32 s44, -2
	s_waitcnt vmcnt(0)
	s_setprio 0
	s_add_u32 s14, s6, 0x100
	s_addc_u32 s15, s7, 0
	s_add_i32 s45, 0, 0x10000
	v_add_u32_e32 v144, s45, v1
	ds_read_b128 v[132:135], v144
	ds_read_b128 v[136:139], v144 offset:1024
	ds_read_b128 v[140:143], v144 offset:2048
	ds_read_b128 v[144:147], v144 offset:3072
	s_cmpk_eq_i32 s44, 0x54
	s_cselect_b32 s21, s1, s15
	s_cselect_b32 s20, s0, s14
	s_cselect_b32 s19, s5, s43
	s_cselect_b32 s18, s4, s42
	ds_read_b128 v[148:151], v224
	ds_read_b128 v[152:155], v224 offset:1024
	ds_read_b128 v[156:159], v224 offset:2048
	ds_read_b128 v[160:163], v224 offset:3072
	ds_read_b128 v[164:167], v224 offset:4096
	ds_read_b128 v[168:171], v224 offset:5120
	ds_read_b128 v[172:175], v224 offset:6144
	ds_read_b128 v[176:179], v224 offset:7168
	s_add_i32 s51, 0, 0x14000
	v_add_u32_e32 v202, s51, v1
	ds_read_b128 v[180:183], v202
	ds_read_b128 v[184:187], v202 offset:1024
	ds_read_b128 v[188:191], v202 offset:2048
	ds_read_b128 v[202:205], v202 offset:3072
	s_add_i32 m0, s29, 0xc000
	s_nop 0
	global_load_lds_dwordx4 v198, s[6:7]
	s_add_i32 m0, s29, 0xe000
	s_nop 0
	global_load_lds_dwordx4 v200, s[6:7]
	s_waitcnt lgkmcnt(0)
	s_setprio 1
	s_barrier
	v_mfma_f32_16x16x32_bf16 v[128:131], v[132:135], v[148:151], 0
	v_mfma_f32_16x16x32_bf16 v[124:127], v[140:143], v[148:151], 0
	v_mfma_f32_16x16x32_bf16 v[112:115], v[132:135], v[156:159], 0
	v_mfma_f32_16x16x32_bf16 v[108:111], v[140:143], v[156:159], 0
	v_mfma_f32_16x16x32_bf16 v[100:103], v[132:135], v[164:167], 0
	v_mfma_f32_16x16x32_bf16 v[92:95], v[140:143], v[164:167], 0
	v_mfma_f32_16x16x32_bf16 v[84:87], v[132:135], v[172:175], 0
	v_mfma_f32_16x16x32_bf16 v[76:79], v[140:143], v[172:175], 0
	v_mfma_f32_16x16x32_bf16 v[128:131], v[136:139], v[152:155], v[128:131]
	v_mfma_f32_16x16x32_bf16 v[124:127], v[144:147], v[152:155], v[124:127]
	v_mfma_f32_16x16x32_bf16 v[112:115], v[136:139], v[160:163], v[112:115]
	v_mfma_f32_16x16x32_bf16 v[108:111], v[144:147], v[160:163], v[108:111]
	v_mfma_f32_16x16x32_bf16 v[100:103], v[136:139], v[168:171], v[100:103]
	v_mfma_f32_16x16x32_bf16 v[92:95], v[144:147], v[168:171], v[92:95]
	v_mfma_f32_16x16x32_bf16 v[84:87], v[136:139], v[176:179], v[84:87]
	v_mfma_f32_16x16x32_bf16 v[76:79], v[144:147], v[176:179], v[76:79]
	v_mfma_f32_16x16x32_bf16 v[120:123], v[180:183], v[148:151], 0
	v_mfma_f32_16x16x32_bf16 v[116:119], v[188:191], v[148:151], 0
	v_mfma_f32_16x16x32_bf16 v[104:107], v[180:183], v[156:159], 0
	v_mfma_f32_16x16x32_bf16 v[96:99], v[188:191], v[156:159], 0
	v_mfma_f32_16x16x32_bf16 v[88:91], v[180:183], v[164:167], 0
	v_mfma_f32_16x16x32_bf16 v[80:83], v[188:191], v[164:167], 0
	v_mfma_f32_16x16x32_bf16 v[72:75], v[180:183], v[172:175], 0
	v_mfma_f32_16x16x32_bf16 v[68:71], v[188:191], v[172:175], 0
	v_mfma_f32_16x16x32_bf16 v[120:123], v[184:187], v[152:155], v[120:123]
	v_mfma_f32_16x16x32_bf16 v[116:119], v[202:205], v[152:155], v[116:119]
	v_mfma_f32_16x16x32_bf16 v[104:107], v[184:187], v[160:163], v[104:107]
	v_mfma_f32_16x16x32_bf16 v[96:99], v[202:205], v[160:163], v[96:99]
	v_mfma_f32_16x16x32_bf16 v[88:91], v[184:187], v[168:171], v[88:91]
	v_mfma_f32_16x16x32_bf16 v[80:83], v[202:205], v[168:171], v[80:83]
	v_mfma_f32_16x16x32_bf16 v[72:75], v[184:187], v[176:179], v[72:75]
	v_mfma_f32_16x16x32_bf16 v[68:71], v[202:205], v[176:179], v[68:71]
	s_barrier
	s_setprio 0
	ds_read_b128 v[148:151], v224 offset:16384
	ds_read_b128 v[152:155], v224 offset:17408
	ds_read_b128 v[156:159], v224 offset:18432
	ds_read_b128 v[160:163], v224 offset:19456
	ds_read_b128 v[164:167], v224 offset:20480
	ds_read_b128 v[168:171], v224 offset:21504
	ds_read_b128 v[172:175], v224 offset:22528
	ds_read_b128 v[176:179], v224 offset:23552
	s_add_i32 s6, s45, s28
	v_lshl_add_u64 v[206:207], s[18:19], 0, v[2:3]
	s_mov_b32 m0, s6
	s_nop 0
	global_load_lds_dwordx4 v[206:207], off
	v_lshl_add_u64 v[208:209], s[18:19], 0, v[192:193]
	s_add_i32 m0, s6, 0x2000
	s_nop 0
	global_load_lds_dwordx4 v[208:209], off
	s_mov_b32 m0, s29
	v_lshl_add_u64 v[210:211], s[20:21], 0, v[196:197]
	global_load_lds_dwordx4 v[210:211], off
	v_lshl_add_u64 v[212:213], s[20:21], 0, v[194:195]
	s_mov_b32 m0, s30
	s_nop 0
	global_load_lds_dwordx4 v[212:213], off
	s_add_u32 s6, s18, 0x160000
	s_addc_u32 s7, s19, 0
	s_add_i32 s45, s51, s28
	s_mov_b32 m0, s45
	s_nop 0
	global_load_lds_dwordx4 v2, s[6:7]
	s_add_i32 m0, s45, 0x2000
	s_nop 0
	global_load_lds_dwordx4 v192, s[6:7]
	s_waitcnt lgkmcnt(0)
	s_waitcnt vmcnt(6)
	s_setprio 1
	s_barrier
	v_mfma_f32_16x16x32_bf16 v[64:67], v[132:135], v[148:151], 0
	v_mfma_f32_16x16x32_bf16 v[60:63], v[140:143], v[148:151], 0
	v_mfma_f32_16x16x32_bf16 v[52:55], v[132:135], v[156:159], 0
	v_mfma_f32_16x16x32_bf16 v[44:47], v[140:143], v[156:159], 0
	v_mfma_f32_16x16x32_bf16 v[36:39], v[132:135], v[164:167], 0
	v_mfma_f32_16x16x32_bf16 v[28:31], v[140:143], v[164:167], 0
	v_mfma_f32_16x16x32_bf16 v[20:23], v[132:135], v[172:175], 0
	v_mfma_f32_16x16x32_bf16 v[12:15], v[140:143], v[172:175], 0
	v_mfma_f32_16x16x32_bf16 v[64:67], v[136:139], v[152:155], v[64:67]
	v_mfma_f32_16x16x32_bf16 v[60:63], v[144:147], v[152:155], v[60:63]
	v_mfma_f32_16x16x32_bf16 v[52:55], v[136:139], v[160:163], v[52:55]
	v_mfma_f32_16x16x32_bf16 v[44:47], v[144:147], v[160:163], v[44:47]
	v_mfma_f32_16x16x32_bf16 v[36:39], v[136:139], v[168:171], v[36:39]
	v_mfma_f32_16x16x32_bf16 v[28:31], v[144:147], v[168:171], v[28:31]
	v_mfma_f32_16x16x32_bf16 v[20:23], v[136:139], v[176:179], v[20:23]
	v_mfma_f32_16x16x32_bf16 v[12:15], v[144:147], v[176:179], v[12:15]
	v_mfma_f32_16x16x32_bf16 v[56:59], v[180:183], v[148:151], 0
	v_mfma_f32_16x16x32_bf16 v[48:51], v[188:191], v[148:151], 0
	v_mfma_f32_16x16x32_bf16 v[40:43], v[180:183], v[156:159], 0
	v_mfma_f32_16x16x32_bf16 v[32:35], v[188:191], v[156:159], 0
	v_mfma_f32_16x16x32_bf16 v[24:27], v[180:183], v[164:167], 0
	v_mfma_f32_16x16x32_bf16 v[16:19], v[188:191], v[164:167], 0
	v_mfma_f32_16x16x32_bf16 v[8:11], v[180:183], v[172:175], 0
	v_mfma_f32_16x16x32_bf16 v[4:7], v[188:191], v[172:175], 0
	v_mfma_f32_16x16x32_bf16 v[56:59], v[184:187], v[152:155], v[56:59]
	v_mfma_f32_16x16x32_bf16 v[48:51], v[202:205], v[152:155], v[48:51]
	v_mfma_f32_16x16x32_bf16 v[40:43], v[184:187], v[160:163], v[40:43]
	v_mfma_f32_16x16x32_bf16 v[32:35], v[202:205], v[160:163], v[32:35]
	v_mfma_f32_16x16x32_bf16 v[24:27], v[184:187], v[168:171], v[24:27]
	v_mfma_f32_16x16x32_bf16 v[16:19], v[202:205], v[168:171], v[16:19]
	v_mfma_f32_16x16x32_bf16 v[8:11], v[184:187], v[176:179], v[8:11]
	v_mfma_f32_16x16x32_bf16 v[4:7], v[202:205], v[176:179], v[4:7]
	s_barrier
; #define PG8_STAGE(bufoff, gbase, voff) do { _Pragma("unroll") for (int _i = 0; _i < 2; ++_i) \
;         __builtin_amdgcn_global_load_lds((const unsigned*)((const char*)(gbase) + (voff)[_i]), (LAS unsigned*)(lds + (bufoff) + ldsw + _i * 8192), 16, 0, 0); } while (0)
; #define PG8_LDA(dst, b, h) do { _Pragma("unroll") for (int m = 0; m < 4; ++m) _Pragma("unroll") for (int k = 0; k < 2; ++k) dst[m][k] = *(const LAS bf16x8*)(lds + PG8_SA(b, h) + aoff + m * 2048 + k * 1024); } while (0)
; #define PG8_LDB(dst, b, h) do { _Pragma("unroll") for (int n = 0; n < 2; ++n) _Pragma("unroll") for (int k = 0; k < 2; ++k) dst[n][k] = *(const LAS bf16x8*)(lds + PG8_SB(b, h) + boff + n * 2048 + k * 1024); } while (0)
; #define PG8_MMA(ai, bj, At, Bt) do { __builtin_amdgcn_s_setprio(1); _Pragma("unroll") for (int m = 0; m < 4; ++m) _Pragma("unroll") for (int n = 0; n < 2; ++n) _Pragma("unroll") for (int k = 0; k < 2; ++k) \
;         acc[ai][bj][m][n] = __builtin_amdgcn_mfma_f32_16x16x32_bf16(Bt[n][k], At[m][k], acc[ai][bj][m][n], 0, 0, 0); __builtin_amdgcn_s_setprio(0); } while (0)
; #define PG8_WAIT_V(n) asm volatile("s_waitcnt vmcnt(" #n ")" ::: "memory")
; #define PG8_WAIT_L(n) asm volatile("s_waitcnt lgkmcnt(" #n ")" ::: "memory")
; #define PG8_BAR __builtin_amdgcn_s_barrier()
; #define PG8_SCHED __builtin_amdgcn_sched_barrier(0)
; template <class Epi, class Sched>
; __device__ __forceinline__ void gemm_phase(LAS unsigned char* lds, const Gemm g, const Sched& S, const Epi& E) {
;     ...
;             PG8_LDB(B0, 1, 0); PG8_SCHED; PG8_LDA(At, 1, 0); PG8_STAGE(PG8_SA(0, 1), a2 + hstepA, voffA);
;             PG8_WAIT_L(8); PG8_BAR; PG8_WAIT_L(0); PG8_MMA(0, 0, At, B0); PG8_BAR; PG8_SCHED;
;             PG8_LDB(B1, 1, 1); PG8_STAGE(PG8_SB(1, 0), b3, voffB);
;             PG8_BAR; PG8_WAIT_L(0); PG8_MMA(0, 1, At, B1); PG8_BAR;
;             PG8_LDA(At, 1, 1); PG8_STAGE(PG8_SA(1, 0), a3, voffA);
;             PG8_BAR; PG8_WAIT_L(0); PG8_MMA(1, 0, At, B0); PG8_BAR; PG8_SCHED;
;             PG8_STAGE(PG8_SB(1, 1), b3 + hstepB, voffB);
;             PG8_WAIT_V(6); PG8_BAR; PG8_MMA(1, 1, At, B1); PG8_BAR;
	s_setprio 0
	s_add_i32 s45, 0, 0x18000
	v_add_u32_e32 v144, s45, v1
	ds_read_b128 v[132:135], v144
	ds_read_b128 v[136:139], v144 offset:1024
	ds_read_b128 v[140:143], v144 offset:2048
	ds_read_b128 v[144:147], v144 offset:3072
	s_add_u32 s6, s20, 0x160000
	s_addc_u32 s7, s21, 0
	ds_read_b128 v[148:151], v224 offset:32768
	ds_read_b128 v[152:155], v224 offset:33792
	ds_read_b128 v[156:159], v224 offset:34816
	ds_read_b128 v[160:163], v224 offset:35840
	ds_read_b128 v[164:167], v224 offset:36864
	ds_read_b128 v[168:171], v224 offset:37888
	ds_read_b128 v[172:175], v224 offset:38912
	ds_read_b128 v[176:179], v224 offset:39936
	s_mov_b32 m0, s31
	s_nop 0
	global_load_lds_dwordx4 v196, s[6:7]
	s_mov_b32 m0, s35
	s_nop 0
	global_load_lds_dwordx4 v194, s[6:7]
	s_add_i32 s20, 0, 0x1c000
	v_add_u32_e32 v202, s20, v1
	ds_read_b128 v[180:183], v202
	ds_read_b128 v[184:187], v202 offset:1024
	ds_read_b128 v[188:191], v202 offset:2048
	ds_read_b128 v[202:205], v202 offset:3072
	s_waitcnt lgkmcnt(0)
	s_setprio 1
	s_barrier
	v_mfma_f32_16x16x32_bf16 v[128:131], v[132:135], v[148:151], v[128:131]
	v_mfma_f32_16x16x32_bf16 v[124:127], v[140:143], v[148:151], v[124:127]
	v_mfma_f32_16x16x32_bf16 v[112:115], v[132:135], v[156:159], v[112:115]
	v_mfma_f32_16x16x32_bf16 v[108:111], v[140:143], v[156:159], v[108:111]
	v_mfma_f32_16x16x32_bf16 v[100:103], v[132:135], v[164:167], v[100:103]
	v_mfma_f32_16x16x32_bf16 v[92:95], v[140:143], v[164:167], v[92:95]
	v_mfma_f32_16x16x32_bf16 v[84:87], v[132:135], v[172:175], v[84:87]
	v_mfma_f32_16x16x32_bf16 v[76:79], v[140:143], v[172:175], v[76:79]
	v_mfma_f32_16x16x32_bf16 v[128:131], v[136:139], v[152:155], v[128:131]
	v_mfma_f32_16x16x32_bf16 v[124:127], v[144:147], v[152:155], v[124:127]
	v_mfma_f32_16x16x32_bf16 v[112:115], v[136:139], v[160:163], v[112:115]
	v_mfma_f32_16x16x32_bf16 v[108:111], v[144:147], v[160:163], v[108:111]
	v_mfma_f32_16x16x32_bf16 v[100:103], v[136:139], v[168:171], v[100:103]
	v_mfma_f32_16x16x32_bf16 v[92:95], v[144:147], v[168:171], v[92:95]
	v_mfma_f32_16x16x32_bf16 v[84:87], v[136:139], v[176:179], v[84:87]
	v_mfma_f32_16x16x32_bf16 v[76:79], v[144:147], v[176:179], v[76:79]
	v_mfma_f32_16x16x32_bf16 v[120:123], v[180:183], v[148:151], v[120:123]
	v_mfma_f32_16x16x32_bf16 v[116:119], v[188:191], v[148:151], v[116:119]
	v_mfma_f32_16x16x32_bf16 v[104:107], v[180:183], v[156:159], v[104:107]
	v_mfma_f32_16x16x32_bf16 v[96:99], v[188:191], v[156:159], v[96:99]
	v_mfma_f32_16x16x32_bf16 v[88:91], v[180:183], v[164:167], v[88:91]
	v_mfma_f32_16x16x32_bf16 v[80:83], v[188:191], v[164:167], v[80:83]
	v_mfma_f32_16x16x32_bf16 v[72:75], v[180:183], v[172:175], v[72:75]
	v_mfma_f32_16x16x32_bf16 v[68:71], v[188:191], v[172:175], v[68:71]
	v_mfma_f32_16x16x32_bf16 v[120:123], v[184:187], v[152:155], v[120:123]
	v_mfma_f32_16x16x32_bf16 v[116:119], v[202:205], v[152:155], v[116:119]
	v_mfma_f32_16x16x32_bf16 v[104:107], v[184:187], v[160:163], v[104:107]
	v_mfma_f32_16x16x32_bf16 v[96:99], v[202:205], v[160:163], v[96:99]
	v_mfma_f32_16x16x32_bf16 v[88:91], v[184:187], v[168:171], v[88:91]
	v_mfma_f32_16x16x32_bf16 v[80:83], v[202:205], v[168:171], v[80:83]
	v_mfma_f32_16x16x32_bf16 v[72:75], v[184:187], v[176:179], v[72:75]
	v_mfma_f32_16x16x32_bf16 v[68:71], v[202:205], v[176:179], v[68:71]
	s_barrier
	s_setprio 0
	ds_read_b128 v[148:151], v224 offset:49152
	ds_read_b128 v[152:155], v224 offset:50176
	ds_read_b128 v[156:159], v224 offset:51200
	ds_read_b128 v[160:163], v224 offset:52224
	ds_read_b128 v[164:167], v224 offset:53248
	ds_read_b128 v[168:171], v224 offset:54272
	ds_read_b128 v[172:175], v224 offset:55296
	ds_read_b128 v[176:179], v224 offset:56320
	s_add_i32 s6, s45, s28
	v_lshl_add_u64 v[206:207], v[206:207], 0, s[8:9]
	s_mov_b32 m0, s6
	s_nop 0
	global_load_lds_dwordx4 v[206:207], off
	v_lshl_add_u64 v[206:207], v[208:209], 0, s[8:9]
	s_add_i32 m0, s6, 0x2000
	s_nop 0
	global_load_lds_dwordx4 v[206:207], off
	s_mov_b32 m0, s38
	v_lshl_add_u64 v[206:207], v[210:211], 0, s[8:9]
	global_load_lds_dwordx4 v[206:207], off
	v_lshl_add_u64 v[206:207], v[212:213], 0, s[8:9]
	s_mov_b32 m0, s39
	s_nop 0
	global_load_lds_dwordx4 v[206:207], off
	s_add_u32 s6, s18, 0x160080
	s_addc_u32 s7, s19, 0
	s_add_i32 s18, s20, s28
	s_mov_b32 m0, s18
	s_nop 0
	global_load_lds_dwordx4 v2, s[6:7]
	s_add_i32 m0, s18, 0x2000
	s_nop 0
	global_load_lds_dwordx4 v192, s[6:7]
	s_add_i32 s44, s44, 2
	s_add_u32 s42, s42, 0x100
	s_addc_u32 s43, s43, 0
	s_cmpk_gt_u32 s44, 0x55
	s_mov_b64 s[6:7], s[14:15]
	s_waitcnt lgkmcnt(0)
	s_waitcnt vmcnt(6)
	s_setprio 1
	s_barrier
	v_mfma_f32_16x16x32_bf16 v[64:67], v[132:135], v[148:151], v[64:67]
	v_mfma_f32_16x16x32_bf16 v[60:63], v[140:143], v[148:151], v[60:63]
	v_mfma_f32_16x16x32_bf16 v[52:55], v[132:135], v[156:159], v[52:55]
	v_mfma_f32_16x16x32_bf16 v[44:47], v[140:143], v[156:159], v[44:47]
	v_mfma_f32_16x16x32_bf16 v[36:39], v[132:135], v[164:167], v[36:39]
	v_mfma_f32_16x16x32_bf16 v[28:31], v[140:143], v[164:167], v[28:31]
	v_mfma_f32_16x16x32_bf16 v[20:23], v[132:135], v[172:175], v[20:23]
	v_mfma_f32_16x16x32_bf16 v[12:15], v[140:143], v[172:175], v[12:15]
	v_mfma_f32_16x16x32_bf16 v[64:67], v[136:139], v[152:155], v[64:67]
	v_mfma_f32_16x16x32_bf16 v[60:63], v[144:147], v[152:155], v[60:63]
	v_mfma_f32_16x16x32_bf16 v[52:55], v[136:139], v[160:163], v[52:55]
	v_mfma_f32_16x16x32_bf16 v[44:47], v[144:147], v[160:163], v[44:47]
	v_mfma_f32_16x16x32_bf16 v[36:39], v[136:139], v[168:171], v[36:39]
	v_mfma_f32_16x16x32_bf16 v[28:31], v[144:147], v[168:171], v[28:31]
	v_mfma_f32_16x16x32_bf16 v[20:23], v[136:139], v[176:179], v[20:23]
	v_mfma_f32_16x16x32_bf16 v[12:15], v[144:147], v[176:179], v[12:15]
	v_mfma_f32_16x16x32_bf16 v[56:59], v[180:183], v[148:151], v[56:59]
	v_mfma_f32_16x16x32_bf16 v[48:51], v[188:191], v[148:151], v[48:51]
	v_mfma_f32_16x16x32_bf16 v[40:43], v[180:183], v[156:159], v[40:43]
	v_mfma_f32_16x16x32_bf16 v[32:35], v[188:191], v[156:159], v[32:35]
	v_mfma_f32_16x16x32_bf16 v[24:27], v[180:183], v[164:167], v[24:27]
	v_mfma_f32_16x16x32_bf16 v[16:19], v[188:191], v[164:167], v[16:19]
	v_mfma_f32_16x16x32_bf16 v[8:11], v[180:183], v[172:175], v[8:11]
	v_mfma_f32_16x16x32_bf16 v[4:7], v[188:191], v[172:175], v[4:7]
	v_mfma_f32_16x16x32_bf16 v[56:59], v[184:187], v[152:155], v[56:59]
	v_mfma_f32_16x16x32_bf16 v[48:51], v[202:205], v[152:155], v[48:51]
	v_mfma_f32_16x16x32_bf16 v[40:43], v[184:187], v[160:163], v[40:43]
	v_mfma_f32_16x16x32_bf16 v[32:35], v[202:205], v[160:163], v[32:35]
	v_mfma_f32_16x16x32_bf16 v[24:27], v[184:187], v[168:171], v[24:27]
	v_mfma_f32_16x16x32_bf16 v[16:19], v[202:205], v[168:171], v[16:19]
	v_mfma_f32_16x16x32_bf16 v[8:11], v[184:187], v[176:179], v[8:11]
	v_mfma_f32_16x16x32_bf16 v[4:7], v[202:205], v[176:179], v[4:7]
	s_barrier
	s_setprio 0
